# on top of dedup waits: s_setprio 1 moved above the s_barrier that opens each GEMM compute interval (48 sites)
# baseline (speedup 1.0000x reference)
; #define PG8_STAGE(bufoff, gbase) do { _Pragma("unroll") for (int _i = 0; _i < 2; ++_i) \
;         __builtin_amdgcn_global_load_lds((const unsigned*)((const char*)(gbase) + voff[_i]), (LAS unsigned*)(lds + (bufoff) + ldsw + _i * 8192), 16, 0, 0); } while (0)
; #define PG8_LDA(dst, b, h) do { _Pragma("unroll") for (int m = 0; m < 4; ++m) _Pragma("unroll") for (int k = 0; k < 2; ++k) dst[m][k] = *(const LAS bf16x8*)(lds + PG8_SA(b, h) + aoff + m * 2048 + k * 1024); } while (0)
; #define PG8_LDB(dst, b, h) do { _Pragma("unroll") for (int n = 0; n < 2; ++n) _Pragma("unroll") for (int k = 0; k < 2; ++k) dst[n][k] = *(const LAS bf16x8*)(lds + PG8_SB(b, h) + boff + n * 2048 + k * 1024); } while (0)
; #define PG8_MMA(ai, bj, At, Bt) do { __builtin_amdgcn_s_setprio(1); _Pragma("unroll") for (int m = 0; m < 4; ++m) _Pragma("unroll") for (int n = 0; n < 2; ++n) _Pragma("unroll") for (int k = 0; k < 2; ++k) \
;         acc[ai][bj][m][n] = __builtin_amdgcn_mfma_f32_16x16x32_bf16(Bt[n][k], At[m][k], acc[ai][bj][m][n], 0, 0, 0); __builtin_amdgcn_s_setprio(0); } while (0)
; #define PG8_WAIT_L(n) asm volatile("s_waitcnt lgkmcnt(" #n ")" ::: "memory")
; #define PG8_BAR __builtin_amdgcn_s_barrier()
; #define PG8_SCHED __builtin_amdgcn_sched_barrier(0)
; template <class Epi>
; DI void gemm_phase(LAS unsigned char* lds, const Gemm g, const StaticOrder& S, const Epi& E) {
;     ...
;         for (int t = 0; t < nt; t += 2) {
;             const bool last = (t == nt - 2);
;             const char* a1 = cA + (size_t)(t + 1) * kstep;
;             const char* a2 = last ? nA : cA + (size_t)(t + 2) * kstep; const char* b2 = last ? nB : cB + (size_t)(t + 2) * kstep;
;             const char* a3 = a2 + kstep; const char* b3 = b2 + kstep;
;             PG8_LDB(B0, 0, 0); PG8_SCHED; PG8_LDA(At, 0, 0); PG8_STAGE(PG8_SA(1, 1), a1 + hstep);
;             PG8_WAIT_L(8); PG8_BAR; PG8_WAIT_L(0); PG8_MMA(0, 0, At, B0); PG8_BAR; PG8_SCHED;
;             PG8_LDB(B1, 0, 1); PG8_STAGE(PG8_SB(0, 0), b2);
;             PG8_BAR; PG8_WAIT_L(0); PG8_MMA(0, 1, At, B1); PG8_BAR;
;             PG8_LDA(At, 0, 1); PG8_STAGE(PG8_SA(0, 0), a2);
;             PG8_BAR; PG8_WAIT_L(0); PG8_MMA(1, 0, At, B0); PG8_BAR; PG8_SCHED;
.LBB0_37:
	s_add_u32 s20, s18, 0xfff80080
	s_addc_u32 s21, s19, -1
	s_add_i32 s39, 0, 0x10000
	v_add_u32_e32 v150, s39, v135
	ds_read_b128 v[138:141], v150
	ds_read_b128 v[142:145], v150 offset:1024
	ds_read_b128 v[146:149], v150 offset:2048
	ds_read_b128 v[150:153], v150 offset:3072
	s_cmp_eq_u32 s38, 28
	s_cselect_b32 s23, s4, s21
	s_cselect_b32 s22, s5, s20
	s_cselect_b32 s21, s9, s37
	s_cselect_b32 s20, s11, s33
	v_lshl_add_u64 v[154:155], s[18:19], 0, v[130:131]
	s_add_i32 m0, s28, 0xc000
	ds_read_b128 v[186:189], v137
	ds_read_b128 v[190:193], v137 offset:1024
	ds_read_b128 v[194:197], v137 offset:2048
	ds_read_b128 v[198:201], v137 offset:3072
	ds_read_b128 v[202:205], v137 offset:4096
	ds_read_b128 v[206:209], v137 offset:5120
	ds_read_b128 v[210:213], v137 offset:6144
	ds_read_b128 v[214:217], v137 offset:7168
	global_load_lds_dwordx4 v[154:155], off
	v_lshl_add_u64 v[154:155], s[18:19], 0, v[132:133]
	s_add_i32 m0, s28, 0xe000
	s_nop 0
	global_load_lds_dwordx4 v[154:155], off
	s_waitcnt lgkmcnt(8)
	s_setprio 1
	s_barrier
	s_waitcnt lgkmcnt(0)
	v_mfma_f32_16x16x32_bf16 v[124:127], v[138:141], v[186:189], v[124:127]
	v_mfma_f32_16x16x32_bf16 v[120:123], v[146:149], v[186:189], v[120:123]
	v_mfma_f32_16x16x32_bf16 v[108:111], v[138:141], v[194:197], v[108:111]
	v_mfma_f32_16x16x32_bf16 v[104:107], v[146:149], v[194:197], v[104:107]
	v_mfma_f32_16x16x32_bf16 v[92:95], v[138:141], v[202:205], v[92:95]
	v_mfma_f32_16x16x32_bf16 v[88:91], v[146:149], v[202:205], v[88:91]
	v_mfma_f32_16x16x32_bf16 v[76:79], v[138:141], v[210:213], v[76:79]
	v_mfma_f32_16x16x32_bf16 v[72:75], v[146:149], v[210:213], v[72:75]
	v_mfma_f32_16x16x32_bf16 v[124:127], v[142:145], v[190:193], v[124:127]
	v_mfma_f32_16x16x32_bf16 v[120:123], v[150:153], v[190:193], v[120:123]
	v_mfma_f32_16x16x32_bf16 v[108:111], v[142:145], v[198:201], v[108:111]
	v_mfma_f32_16x16x32_bf16 v[104:107], v[150:153], v[198:201], v[104:107]
	v_mfma_f32_16x16x32_bf16 v[92:95], v[142:145], v[206:209], v[92:95]
	v_mfma_f32_16x16x32_bf16 v[88:91], v[150:153], v[206:209], v[88:91]
	v_mfma_f32_16x16x32_bf16 v[76:79], v[142:145], v[214:217], v[76:79]
	v_mfma_f32_16x16x32_bf16 v[72:75], v[150:153], v[214:217], v[72:75]
	s_setprio 0
	s_barrier
	s_add_i32 s42, 0, 0x14000
	v_add_u32_e32 v154, s42, v135
	s_add_i32 s39, s39, s27
	ds_read_b128 v[226:229], v154
	ds_read_b128 v[230:233], v154 offset:1024
	ds_read_b128 v[234:237], v154 offset:2048
	ds_read_b128 v[238:241], v154 offset:3072
	v_lshl_add_u64 v[154:155], s[20:21], 0, v[158:159]
	s_mov_b32 m0, s39
	v_lshl_add_u64 v[218:219], s[20:21], 0, v[128:129]
	global_load_lds_dwordx4 v[154:155], off
	s_add_i32 m0, s39, 0x2000
	s_nop 0
	global_load_lds_dwordx4 v[218:219], off
	s_setprio 1
	s_barrier
	s_waitcnt lgkmcnt(0)
	v_mfma_f32_16x16x32_bf16 v[116:119], v[226:229], v[186:189], v[116:119]
	v_mfma_f32_16x16x32_bf16 v[112:115], v[234:237], v[186:189], v[112:115]
	v_mfma_f32_16x16x32_bf16 v[100:103], v[226:229], v[194:197], v[100:103]
	v_mfma_f32_16x16x32_bf16 v[96:99], v[234:237], v[194:197], v[96:99]
	v_mfma_f32_16x16x32_bf16 v[84:87], v[226:229], v[202:205], v[84:87]
	v_mfma_f32_16x16x32_bf16 v[80:83], v[234:237], v[202:205], v[80:83]
	v_mfma_f32_16x16x32_bf16 v[68:71], v[226:229], v[210:213], v[68:71]
	v_mfma_f32_16x16x32_bf16 v[64:67], v[234:237], v[210:213], v[64:67]
	v_mfma_f32_16x16x32_bf16 v[116:119], v[230:233], v[190:193], v[116:119]
	v_mfma_f32_16x16x32_bf16 v[112:115], v[238:241], v[190:193], v[112:115]
	v_mfma_f32_16x16x32_bf16 v[100:103], v[230:233], v[198:201], v[100:103]
	v_mfma_f32_16x16x32_bf16 v[96:99], v[238:241], v[198:201], v[96:99]
	v_mfma_f32_16x16x32_bf16 v[84:87], v[230:233], v[206:209], v[84:87]
	v_mfma_f32_16x16x32_bf16 v[80:83], v[238:241], v[206:209], v[80:83]
	v_mfma_f32_16x16x32_bf16 v[68:71], v[230:233], v[214:217], v[68:71]
	v_mfma_f32_16x16x32_bf16 v[64:67], v[238:241], v[214:217], v[64:67]
	s_setprio 0
	s_mov_b32 m0, s28
	v_lshl_add_u64 v[220:221], s[22:23], 0, v[158:159]
	s_barrier
	ds_read_b128 v[186:189], v137 offset:16384
	ds_read_b128 v[190:193], v137 offset:17408
	ds_read_b128 v[194:197], v137 offset:18432
	ds_read_b128 v[198:201], v137 offset:19456
	ds_read_b128 v[202:205], v137 offset:20480
	ds_read_b128 v[206:209], v137 offset:21504
	ds_read_b128 v[210:213], v137 offset:22528
	ds_read_b128 v[214:217], v137 offset:23552
	global_load_lds_dwordx4 v[220:221], off
	v_lshl_add_u64 v[242:243], s[22:23], 0, v[128:129]
	s_mov_b32 m0, s29
	s_nop 0
	global_load_lds_dwordx4 v[242:243], off
	s_setprio 1
	s_barrier
	s_waitcnt lgkmcnt(0)
	v_mfma_f32_16x16x32_bf16 v[60:63], v[138:141], v[186:189], v[60:63]
	v_mfma_f32_16x16x32_bf16 v[56:59], v[146:149], v[186:189], v[56:59]
	v_mfma_f32_16x16x32_bf16 v[44:47], v[138:141], v[194:197], v[44:47]
	v_mfma_f32_16x16x32_bf16 v[40:43], v[146:149], v[194:197], v[40:43]
	v_mfma_f32_16x16x32_bf16 v[28:31], v[138:141], v[202:205], v[28:31]
	v_mfma_f32_16x16x32_bf16 v[24:27], v[146:149], v[202:205], v[24:27]
	v_mfma_f32_16x16x32_bf16 v[12:15], v[138:141], v[210:213], v[12:15]
	v_mfma_f32_16x16x32_bf16 v[8:11], v[146:149], v[210:213], v[8:11]
	v_mfma_f32_16x16x32_bf16 v[60:63], v[142:145], v[190:193], v[60:63]
	v_mfma_f32_16x16x32_bf16 v[56:59], v[150:153], v[190:193], v[56:59]
	v_mfma_f32_16x16x32_bf16 v[44:47], v[142:145], v[198:201], v[44:47]
	v_mfma_f32_16x16x32_bf16 v[40:43], v[150:153], v[198:201], v[40:43]
	v_mfma_f32_16x16x32_bf16 v[28:31], v[142:145], v[206:209], v[28:31]
	v_mfma_f32_16x16x32_bf16 v[24:27], v[150:153], v[206:209], v[24:27]
	v_mfma_f32_16x16x32_bf16 v[12:15], v[142:145], v[214:217], v[12:15]
	v_mfma_f32_16x16x32_bf16 v[8:11], v[150:153], v[214:217], v[8:11]
	s_setprio 0
	s_barrier
; #define PG8_STAGE(bufoff, gbase) do { _Pragma("unroll") for (int _i = 0; _i < 2; ++_i) \
;         __builtin_amdgcn_global_load_lds((const unsigned*)((const char*)(gbase) + voff[_i]), (LAS unsigned*)(lds + (bufoff) + ldsw + _i * 8192), 16, 0, 0); } while (0)
; #define PG8_LDA(dst, b, h) do { _Pragma("unroll") for (int m = 0; m < 4; ++m) _Pragma("unroll") for (int k = 0; k < 2; ++k) dst[m][k] = *(const LAS bf16x8*)(lds + PG8_SA(b, h) + aoff + m * 2048 + k * 1024); } while (0)
; #define PG8_LDB(dst, b, h) do { _Pragma("unroll") for (int n = 0; n < 2; ++n) _Pragma("unroll") for (int k = 0; k < 2; ++k) dst[n][k] = *(const LAS bf16x8*)(lds + PG8_SB(b, h) + boff + n * 2048 + k * 1024); } while (0)
; #define PG8_MMA(ai, bj, At, Bt) do { __builtin_amdgcn_s_setprio(1); _Pragma("unroll") for (int m = 0; m < 4; ++m) _Pragma("unroll") for (int n = 0; n < 2; ++n) _Pragma("unroll") for (int k = 0; k < 2; ++k) \
;         acc[ai][bj][m][n] = __builtin_amdgcn_mfma_f32_16x16x32_bf16(Bt[n][k], At[m][k], acc[ai][bj][m][n], 0, 0, 0); __builtin_amdgcn_s_setprio(0); } while (0)
; #define PG8_WAIT_V(n) asm volatile("s_waitcnt vmcnt(" #n ")" ::: "memory")
; #define PG8_WAIT_L(n) asm volatile("s_waitcnt lgkmcnt(" #n ")" ::: "memory")
; #define PG8_BAR __builtin_amdgcn_s_barrier()
; #define PG8_SCHED __builtin_amdgcn_sched_barrier(0)
; template <class Epi>
; DI void gemm_phase(LAS unsigned char* lds, const Gemm g, const StaticOrder& S, const Epi& E) {
;     ...
;             PG8_STAGE(PG8_SB(0, 1), b2 + hstep);
;             PG8_WAIT_V(6); PG8_BAR; PG8_MMA(1, 1, At, B1); PG8_BAR;
;             PG8_LDB(B0, 1, 0); PG8_SCHED; PG8_LDA(At, 1, 0); PG8_STAGE(PG8_SA(0, 1), a2 + hstep);
;             PG8_WAIT_L(8); PG8_BAR; PG8_WAIT_L(0); PG8_MMA(0, 0, At, B0); PG8_BAR; PG8_SCHED;
;             PG8_LDB(B1, 1, 1); PG8_STAGE(PG8_SB(1, 0), b3);
;             PG8_BAR; PG8_WAIT_L(0); PG8_MMA(0, 1, At, B1); PG8_BAR;
;             PG8_LDA(At, 1, 1); PG8_STAGE(PG8_SA(1, 0), a3);
;             PG8_BAR; PG8_WAIT_L(0); PG8_MMA(1, 0, At, B0); PG8_BAR; PG8_SCHED;
;             PG8_STAGE(PG8_SB(1, 1), b3 + hstep);
	s_add_u32 s40, s20, 0x80000
	s_addc_u32 s41, s21, 0
	s_add_i32 s39, s42, s27
	v_lshl_add_u64 v[138:139], s[40:41], 0, v[158:159]
	s_mov_b32 m0, s39
	s_nop 0
	global_load_lds_dwordx4 v[138:139], off
	v_lshl_add_u64 v[138:139], s[40:41], 0, v[128:129]
	s_add_i32 m0, s39, 0x2000
	s_nop 0
	global_load_lds_dwordx4 v[138:139], off
	s_waitcnt vmcnt(6)
	s_setprio 1
	s_barrier
	v_mfma_f32_16x16x32_bf16 v[52:55], v[226:229], v[186:189], v[52:55]
	v_mfma_f32_16x16x32_bf16 v[48:51], v[234:237], v[186:189], v[48:51]
	v_mfma_f32_16x16x32_bf16 v[36:39], v[226:229], v[194:197], v[36:39]
	v_mfma_f32_16x16x32_bf16 v[32:35], v[234:237], v[194:197], v[32:35]
	v_mfma_f32_16x16x32_bf16 v[20:23], v[226:229], v[202:205], v[20:23]
	v_mfma_f32_16x16x32_bf16 v[16:19], v[234:237], v[202:205], v[16:19]
	v_mfma_f32_16x16x32_bf16 v[4:7], v[226:229], v[210:213], v[4:7]
	v_mfma_f32_16x16x32_bf16 v[0:3], v[234:237], v[210:213], v[0:3]
	v_mfma_f32_16x16x32_bf16 v[52:55], v[230:233], v[190:193], v[52:55]
	v_mfma_f32_16x16x32_bf16 v[48:51], v[238:241], v[190:193], v[48:51]
	v_mfma_f32_16x16x32_bf16 v[36:39], v[230:233], v[198:201], v[36:39]
	v_mfma_f32_16x16x32_bf16 v[32:35], v[238:241], v[198:201], v[32:35]
	v_mfma_f32_16x16x32_bf16 v[20:23], v[230:233], v[206:209], v[20:23]
	v_mfma_f32_16x16x32_bf16 v[16:19], v[238:241], v[206:209], v[16:19]
	v_mfma_f32_16x16x32_bf16 v[4:7], v[230:233], v[214:217], v[4:7]
	v_mfma_f32_16x16x32_bf16 v[0:3], v[238:241], v[214:217], v[0:3]
	s_setprio 0
	s_add_i32 s39, 0, 0x18000
	v_add_u32_e32 v150, s39, v135
	s_barrier
	ds_read_b128 v[138:141], v150
	ds_read_b128 v[142:145], v150 offset:1024
	ds_read_b128 v[146:149], v150 offset:2048
	ds_read_b128 v[150:153], v150 offset:3072
	s_add_u32 s22, s22, 0x80000
	s_addc_u32 s23, s23, 0
	s_mov_b32 m0, s30
	v_lshl_add_u64 v[226:227], s[22:23], 0, v[158:159]
	ds_read_b128 v[186:189], v137 offset:32768
	ds_read_b128 v[190:193], v137 offset:33792
	ds_read_b128 v[194:197], v137 offset:34816
	ds_read_b128 v[198:201], v137 offset:35840
	ds_read_b128 v[202:205], v137 offset:36864
	ds_read_b128 v[206:209], v137 offset:37888
	ds_read_b128 v[210:213], v137 offset:38912
	ds_read_b128 v[214:217], v137 offset:39936
	global_load_lds_dwordx4 v[226:227], off
	v_lshl_add_u64 v[226:227], s[22:23], 0, v[128:129]
	s_mov_b32 m0, s31
	s_nop 0
	global_load_lds_dwordx4 v[226:227], off
	s_waitcnt lgkmcnt(8)
	s_setprio 1
	s_barrier
	s_waitcnt lgkmcnt(0)
	v_mfma_f32_16x16x32_bf16 v[124:127], v[138:141], v[186:189], v[124:127]
	v_mfma_f32_16x16x32_bf16 v[120:123], v[146:149], v[186:189], v[120:123]
	v_mfma_f32_16x16x32_bf16 v[108:111], v[138:141], v[194:197], v[108:111]
	v_mfma_f32_16x16x32_bf16 v[104:107], v[146:149], v[194:197], v[104:107]
	v_mfma_f32_16x16x32_bf16 v[92:95], v[138:141], v[202:205], v[92:95]
	v_mfma_f32_16x16x32_bf16 v[88:91], v[146:149], v[202:205], v[88:91]
	v_mfma_f32_16x16x32_bf16 v[76:79], v[138:141], v[210:213], v[76:79]
	v_mfma_f32_16x16x32_bf16 v[72:75], v[146:149], v[210:213], v[72:75]
	v_mfma_f32_16x16x32_bf16 v[124:127], v[142:145], v[190:193], v[124:127]
	v_mfma_f32_16x16x32_bf16 v[120:123], v[150:153], v[190:193], v[120:123]
	v_mfma_f32_16x16x32_bf16 v[108:111], v[142:145], v[198:201], v[108:111]
	v_mfma_f32_16x16x32_bf16 v[104:107], v[150:153], v[198:201], v[104:107]
	v_mfma_f32_16x16x32_bf16 v[92:95], v[142:145], v[206:209], v[92:95]
	v_mfma_f32_16x16x32_bf16 v[88:91], v[150:153], v[206:209], v[88:91]
	v_mfma_f32_16x16x32_bf16 v[76:79], v[142:145], v[214:217], v[76:79]
	v_mfma_f32_16x16x32_bf16 v[72:75], v[150:153], v[214:217], v[72:75]
	s_setprio 0
	s_barrier
	s_add_i32 s22, 0, 0x1c000
	s_add_i32 s23, s39, s27
	v_add_u32_e32 v225, s22, v135
	v_lshl_add_u64 v[154:155], v[154:155], 0, s[94:95]
	s_mov_b32 m0, s23
	ds_read_b128 v[226:229], v225
	ds_read_b128 v[230:233], v225 offset:1024
	ds_read_b128 v[234:237], v225 offset:2048
	ds_read_b128 v[238:241], v225 offset:3072
	global_load_lds_dwordx4 v[154:155], off
	v_lshl_add_u64 v[154:155], v[218:219], 0, s[94:95]
	s_add_i32 m0, s23, 0x2000
	s_nop 0
	global_load_lds_dwordx4 v[154:155], off
	s_setprio 1
	s_barrier
	s_waitcnt lgkmcnt(0)
	v_mfma_f32_16x16x32_bf16 v[116:119], v[226:229], v[186:189], v[116:119]
	v_mfma_f32_16x16x32_bf16 v[112:115], v[234:237], v[186:189], v[112:115]
	v_mfma_f32_16x16x32_bf16 v[100:103], v[226:229], v[194:197], v[100:103]
	v_mfma_f32_16x16x32_bf16 v[96:99], v[234:237], v[194:197], v[96:99]
	v_mfma_f32_16x16x32_bf16 v[84:87], v[226:229], v[202:205], v[84:87]
	v_mfma_f32_16x16x32_bf16 v[80:83], v[234:237], v[202:205], v[80:83]
	v_mfma_f32_16x16x32_bf16 v[68:71], v[226:229], v[210:213], v[68:71]
	v_mfma_f32_16x16x32_bf16 v[64:67], v[234:237], v[210:213], v[64:67]
	v_mfma_f32_16x16x32_bf16 v[116:119], v[230:233], v[190:193], v[116:119]
	v_mfma_f32_16x16x32_bf16 v[112:115], v[238:241], v[190:193], v[112:115]
	v_mfma_f32_16x16x32_bf16 v[100:103], v[230:233], v[198:201], v[100:103]
	v_mfma_f32_16x16x32_bf16 v[96:99], v[238:241], v[198:201], v[96:99]
	v_mfma_f32_16x16x32_bf16 v[84:87], v[230:233], v[206:209], v[84:87]
	v_mfma_f32_16x16x32_bf16 v[80:83], v[238:241], v[206:209], v[80:83]
	v_mfma_f32_16x16x32_bf16 v[68:71], v[230:233], v[214:217], v[68:71]
	v_mfma_f32_16x16x32_bf16 v[64:67], v[238:241], v[214:217], v[64:67]
	s_setprio 0
	s_mov_b32 m0, s34
	v_lshl_add_u64 v[154:155], v[220:221], 0, s[94:95]
	s_barrier
	ds_read_b128 v[186:189], v137 offset:49152
	ds_read_b128 v[190:193], v137 offset:50176
	ds_read_b128 v[194:197], v137 offset:51200
	ds_read_b128 v[198:201], v137 offset:52224
	ds_read_b128 v[202:205], v137 offset:53248
	ds_read_b128 v[206:209], v137 offset:54272
	ds_read_b128 v[210:213], v137 offset:55296
	ds_read_b128 v[214:217], v137 offset:56320
	global_load_lds_dwordx4 v[154:155], off
	v_lshl_add_u64 v[154:155], v[242:243], 0, s[94:95]
	s_mov_b32 m0, s35
	s_nop 0
	global_load_lds_dwordx4 v[154:155], off
	s_setprio 1
	s_barrier
; #define PG8_STAGE(bufoff, gbase) do { _Pragma("unroll") for (int _i = 0; _i < 2; ++_i) \
;         __builtin_amdgcn_global_load_lds((const unsigned*)((const char*)(gbase) + voff[_i]), (LAS unsigned*)(lds + (bufoff) + ldsw + _i * 8192), 16, 0, 0); } while (0)
; #define PG8_MMA(ai, bj, At, Bt) do { __builtin_amdgcn_s_setprio(1); _Pragma("unroll") for (int m = 0; m < 4; ++m) _Pragma("unroll") for (int n = 0; n < 2; ++n) _Pragma("unroll") for (int k = 0; k < 2; ++k) \
;         acc[ai][bj][m][n] = __builtin_amdgcn_mfma_f32_16x16x32_bf16(Bt[n][k], At[m][k], acc[ai][bj][m][n], 0, 0, 0); __builtin_amdgcn_s_setprio(0); } while (0)
; #define PG8_WAIT_V(n) asm volatile("s_waitcnt vmcnt(" #n ")" ::: "memory")
; #define PG8_WAIT_L(n) asm volatile("s_waitcnt lgkmcnt(" #n ")" ::: "memory")
; #define PG8_BAR __builtin_amdgcn_s_barrier()
; #define PG8_SCHED __builtin_amdgcn_sched_barrier(0)
; template <class Epi>
; DI void gemm_phase(LAS unsigned char* lds, const Gemm g, const StaticOrder& S, const Epi& E) {
;     ...
;             PG8_BAR; PG8_WAIT_L(0); PG8_MMA(1, 0, At, B0); PG8_BAR; PG8_SCHED;
;             PG8_STAGE(PG8_SB(1, 1), b3 + hstep);
;             PG8_WAIT_V(6); PG8_BAR; PG8_MMA(1, 1, At, B1); PG8_BAR;
;     DI void operator()(const f32x4 (&acc)[2][2][4][2], const Unit& u, int wr, int wc, int fr, int fq) const {
;         const int row0 = u.pm * BM + wr * 64 + fr, col0 = u.pn * HALF + wc * 32 + 8 * fq;
; #pragma unroll
;         for (int ai = 0; ai < 2; ++ai)
; #pragma unroll
;             for (int m = 0; m < 4; ++m) { float hv[8];
; #pragma unroll
;                 for (int n = 0; n < 2; ++n)
; #pragma unroll
;                     for (int e = 0; e < 4; ++e) { const float gt = acc[ai][0][m][n][e], up = acc[ai][1][m][n][e];
;                         hv[n * 4 + e] = gt * __builtin_amdgcn_rcpf(1.f + __builtin_amdgcn_exp2f(-1.4426950408889634f * gt)) * up; }
;                 *(u32x4*)(H + (size_t)(row0 + ai * HALF + m * 16) * DFF + col0) = (u32x4){pk(hv[0], hv[1]), pk(hv[2], hv[3]), pk(hv[4], hv[5]), pk(hv[6], hv[7])}; }
	s_waitcnt lgkmcnt(0)
	v_mfma_f32_16x16x32_bf16 v[60:63], v[138:141], v[186:189], v[60:63]
	v_mfma_f32_16x16x32_bf16 v[56:59], v[146:149], v[186:189], v[56:59]
	v_mfma_f32_16x16x32_bf16 v[44:47], v[138:141], v[194:197], v[44:47]
	v_mfma_f32_16x16x32_bf16 v[40:43], v[146:149], v[194:197], v[40:43]
	v_mfma_f32_16x16x32_bf16 v[28:31], v[138:141], v[202:205], v[28:31]
	v_mfma_f32_16x16x32_bf16 v[24:27], v[146:149], v[202:205], v[24:27]
	v_mfma_f32_16x16x32_bf16 v[12:15], v[138:141], v[210:213], v[12:15]
	v_mfma_f32_16x16x32_bf16 v[8:11], v[146:149], v[210:213], v[8:11]
	v_mfma_f32_16x16x32_bf16 v[60:63], v[142:145], v[190:193], v[60:63]
	v_mfma_f32_16x16x32_bf16 v[56:59], v[150:153], v[190:193], v[56:59]
	v_mfma_f32_16x16x32_bf16 v[44:47], v[142:145], v[198:201], v[44:47]
	v_mfma_f32_16x16x32_bf16 v[40:43], v[150:153], v[198:201], v[40:43]
	v_mfma_f32_16x16x32_bf16 v[28:31], v[142:145], v[206:209], v[28:31]
	v_mfma_f32_16x16x32_bf16 v[24:27], v[150:153], v[206:209], v[24:27]
	v_mfma_f32_16x16x32_bf16 v[12:15], v[142:145], v[214:217], v[12:15]
	v_mfma_f32_16x16x32_bf16 v[8:11], v[150:153], v[214:217], v[8:11]
	s_setprio 0
	s_barrier
	s_add_u32 s20, s20, 0x80080
	s_addc_u32 s21, s21, 0
	s_add_i32 s22, s22, s27
	v_lshl_add_u64 v[138:139], s[20:21], 0, v[158:159]
	s_mov_b32 m0, s22
	s_nop 0
	global_load_lds_dwordx4 v[138:139], off
	v_lshl_add_u64 v[138:139], s[20:21], 0, v[128:129]
	s_add_i32 m0, s22, 0x2000
	s_nop 0
	global_load_lds_dwordx4 v[138:139], off
	s_waitcnt vmcnt(6)
	s_setprio 1
	s_barrier
	v_mfma_f32_16x16x32_bf16 v[52:55], v[226:229], v[186:189], v[52:55]
	v_mfma_f32_16x16x32_bf16 v[48:51], v[234:237], v[186:189], v[48:51]
	v_mfma_f32_16x16x32_bf16 v[36:39], v[226:229], v[194:197], v[36:39]
	v_mfma_f32_16x16x32_bf16 v[32:35], v[234:237], v[194:197], v[32:35]
	v_mfma_f32_16x16x32_bf16 v[20:23], v[226:229], v[202:205], v[20:23]
	v_mfma_f32_16x16x32_bf16 v[16:19], v[234:237], v[202:205], v[16:19]
	v_mfma_f32_16x16x32_bf16 v[4:7], v[226:229], v[210:213], v[4:7]
	v_mfma_f32_16x16x32_bf16 v[0:3], v[234:237], v[210:213], v[0:3]
	v_mfma_f32_16x16x32_bf16 v[52:55], v[230:233], v[190:193], v[52:55]
	v_mfma_f32_16x16x32_bf16 v[48:51], v[238:241], v[190:193], v[48:51]
	v_mfma_f32_16x16x32_bf16 v[36:39], v[230:233], v[198:201], v[36:39]
	v_mfma_f32_16x16x32_bf16 v[32:35], v[238:241], v[198:201], v[32:35]
	v_mfma_f32_16x16x32_bf16 v[20:23], v[230:233], v[206:209], v[20:23]
	v_mfma_f32_16x16x32_bf16 v[16:19], v[238:241], v[206:209], v[16:19]
	v_mfma_f32_16x16x32_bf16 v[4:7], v[230:233], v[214:217], v[4:7]
	v_mfma_f32_16x16x32_bf16 v[0:3], v[238:241], v[214:217], v[0:3]
	s_setprio 0
	s_add_i32 s38, s38, 2
	s_add_u32 s18, s18, 0x100
	s_addc_u32 s19, s19, 0
	s_add_u32 s33, s33, 0x100
	s_addc_u32 s37, s37, 0
	s_cmp_gt_u32 s38, 29
	s_barrier
	s_cbranch_scc0 .LBB0_37
	v_mul_f32_e32 v139, 0xbfb8aa3b, v124
	v_exp_f32_e32 v139, v139
	v_lshl_or_b32 v140, s2, 7, v136
	v_lshl_add_u32 v138, s3, 8, v134
	v_ashrrev_i32_e32 v141, 31, v140
	v_add_f32_e32 v139, 1.0, v139
	v_rcp_f32_e32 v142, v139
	v_mul_f32_e32 v139, 0xbfb8aa3b, v125
	v_exp_f32_e32 v139, v139
	s_movk_i32 s4, 0x2c00
	s_and_b64 vcc, exec, s[6:7]
	s_mov_b64 s[20:21], s[16:17]
	v_add_f32_e32 v139, 1.0, v139
	v_rcp_f32_e32 v143, v139
	v_mul_f32_e32 v139, 0xbfb8aa3b, v126
	v_exp_f32_e32 v139, v139
	s_mov_b64 s[18:19], s[14:15]
	v_pk_mul_f32 v[124:125], v[124:125], v[142:143]
	v_add_f32_e32 v139, 1.0, v139
	v_rcp_f32_e32 v144, v139
	v_mul_f32_e32 v139, 0xbfb8aa3b, v127
	v_exp_f32_e32 v139, v139
	v_pk_mul_f32 v[116:117], v[124:125], v[116:117]
	v_add_f32_e32 v139, 1.0, v139
	v_rcp_f32_e32 v145, v139
	v_mul_f32_e32 v139, 0xbfb8aa3b, v120
	v_exp_f32_e32 v139, v139
	v_cvt_pk_bf16_f32 v116, v116, v117
	v_pk_mul_f32 v[124:125], v[126:127], v[144:145]
	v_add_f32_e32 v139, 1.0, v139
	v_rcp_f32_e32 v146, v139
	v_mul_f32_e32 v139, 0xbfb8aa3b, v121
	v_exp_f32_e32 v139, v139
	v_pk_mul_f32 v[118:119], v[124:125], v[118:119]
	v_add_f32_e32 v139, 1.0, v139
	v_rcp_f32_e32 v147, v139
	v_mul_f32_e32 v139, 0xbfb8aa3b, v122
	v_exp_f32_e32 v139, v139
	v_cvt_pk_bf16_f32 v117, v118, v119
	v_pk_mul_f32 v[118:119], v[120:121], v[146:147]
	v_add_f32_e32 v139, 1.0, v139
	v_rcp_f32_e32 v148, v139
	v_mul_f32_e32 v139, 0xbfb8aa3b, v123
	v_exp_f32_e32 v139, v139
	v_pk_mul_f32 v[112:113], v[118:119], v[112:113]
	v_add_f32_e32 v139, 1.0, v139
	v_rcp_f32_e32 v149, v139
	v_cvt_pk_bf16_f32 v118, v112, v113
	v_pk_mul_f32 v[112:113], v[122:123], v[148:149]
	s_nop 0
	v_pk_mul_f32 v[112:113], v[112:113], v[114:115]
	v_lshlrev_b64 v[114:115], 1, v[140:141]
	v_cvt_pk_bf16_f32 v119, v112, v113
	v_mov_b64_e32 v[112:113], s[54:55]
	v_mad_i64_i32 v[120:121], s[2:3], v138, s4, v[112:113]
	v_lshl_add_u64 v[120:121], v[120:121], 0, v[114:115]
	global_store_dwordx4 v[120:121], v[116:119], off
	v_mul_f32_e32 v120, 0xbfb8aa3b, v104
	v_mul_f32_e32 v121, 0xbfb8aa3b, v105
	v_mul_f32_e32 v116, 0xbfb8aa3b, v108
	v_mul_f32_e32 v117, 0xbfb8aa3b, v109
	v_exp_f32_e32 v116, v116
	v_exp_f32_e32 v117, v117
	v_mul_f32_e32 v118, 0xbfb8aa3b, v110
	v_mul_f32_e32 v119, 0xbfb8aa3b, v111
	v_exp_f32_e32 v118, v118
	v_exp_f32_e32 v119, v119
	v_exp_f32_e32 v120, v120
	v_exp_f32_e32 v121, v121
	v_add_f32_e32 v116, 1.0, v116
	v_add_f32_e32 v117, 1.0, v117
	v_mul_f32_e32 v122, 0xbfb8aa3b, v106
	v_mul_f32_e32 v123, 0xbfb8aa3b, v107
	v_rcp_f32_e32 v116, v116
	v_rcp_f32_e32 v117, v117
	v_add_f32_e32 v118, 1.0, v118
	v_add_f32_e32 v119, 1.0, v119
	v_exp_f32_e32 v122, v122
	v_exp_f32_e32 v123, v123
	v_rcp_f32_e32 v118, v118
	v_rcp_f32_e32 v119, v119
	v_add_f32_e32 v120, 1.0, v120
	v_add_f32_e32 v121, 1.0, v121
	v_rcp_f32_e32 v120, v120
	v_rcp_f32_e32 v121, v121
	v_add_f32_e32 v122, 1.0, v122
;     DI void operator()(const f32x4 (&acc)[2][2][4][2], const Unit& u, int wr, int wc, int fr, int fq) const {
;     ...
;             for (int m = 0; m < 4; ++m) { float hv[8];
; #pragma unroll
;                 for (int n = 0; n < 2; ++n)
; #pragma unroll
;                     for (int e = 0; e < 4; ++e) { const float gt = acc[ai][0][m][n][e], up = acc[ai][1][m][n][e];
;                         hv[n * 4 + e] = gt * __builtin_amdgcn_rcpf(1.f + __builtin_amdgcn_exp2f(-1.4426950408889634f * gt)) * up; }
;                 *(u32x4*)(H + (size_t)(row0 + ai * HALF + m * 16) * DFF + col0) = (u32x4){pk(hv[0], hv[1]), pk(hv[2], hv[3]), pk(hv[4], hv[5]), pk(hv[6], hv[7])}; }
	v_add_f32_e32 v123, 1.0, v123
	v_pk_mul_f32 v[108:109], v[108:109], v[116:117]
	v_rcp_f32_e32 v122, v122
	v_rcp_f32_e32 v123, v123
	v_pk_mul_f32 v[100:101], v[108:109], v[100:101]
	v_pk_mul_f32 v[108:109], v[110:111], v[118:119]
	v_cvt_pk_bf16_f32 v100, v100, v101
	v_pk_mul_f32 v[102:103], v[108:109], v[102:103]
	s_nop 0
	v_cvt_pk_bf16_f32 v101, v102, v103
	v_pk_mul_f32 v[102:103], v[104:105], v[120:121]
	s_nop 0
	v_pk_mul_f32 v[96:97], v[102:103], v[96:97]
	s_nop 0
	v_cvt_pk_bf16_f32 v102, v96, v97
	v_pk_mul_f32 v[96:97], v[106:107], v[122:123]
	s_nop 0
	v_pk_mul_f32 v[96:97], v[96:97], v[98:99]
	v_mul_f32_e32 v98, 0xbfb8aa3b, v94
	v_cvt_pk_bf16_f32 v103, v96, v97
	v_or_b32_e32 v96, 16, v138
	v_mad_i64_i32 v[96:97], s[2:3], v96, s4, v[112:113]
	v_lshl_add_u64 v[96:97], v[96:97], 0, v[114:115]
	global_store_dwordx4 v[96:97], v[100:103], off
	v_mul_f32_e32 v96, 0xbfb8aa3b, v92
	v_mul_f32_e32 v97, 0xbfb8aa3b, v93
	v_exp_f32_e32 v96, v96
	v_exp_f32_e32 v97, v97
	v_mul_f32_e32 v99, 0xbfb8aa3b, v95
	v_exp_f32_e32 v98, v98
	v_exp_f32_e32 v99, v99
	v_mul_f32_e32 v100, 0xbfb8aa3b, v88
	v_mul_f32_e32 v101, 0xbfb8aa3b, v89
	v_exp_f32_e32 v100, v100
	v_exp_f32_e32 v101, v101
	v_add_f32_e32 v96, 1.0, v96
	v_add_f32_e32 v97, 1.0, v97
	v_mul_f32_e32 v102, 0xbfb8aa3b, v90
	v_mul_f32_e32 v103, 0xbfb8aa3b, v91
	v_rcp_f32_e32 v96, v96
	v_rcp_f32_e32 v97, v97
	v_add_f32_e32 v98, 1.0, v98
	v_add_f32_e32 v99, 1.0, v99
	v_exp_f32_e32 v102, v102
	v_exp_f32_e32 v103, v103
	v_rcp_f32_e32 v98, v98
	v_rcp_f32_e32 v99, v99
	v_add_f32_e32 v100, 1.0, v100
	v_add_f32_e32 v101, 1.0, v101
	v_rcp_f32_e32 v100, v100
	v_rcp_f32_e32 v101, v101
	v_add_f32_e32 v102, 1.0, v102
	v_add_f32_e32 v103, 1.0, v103
	v_pk_mul_f32 v[92:93], v[92:93], v[96:97]
	v_rcp_f32_e32 v102, v102
	v_rcp_f32_e32 v103, v103
	v_pk_mul_f32 v[84:85], v[92:93], v[84:85]
	v_pk_mul_f32 v[92:93], v[94:95], v[98:99]
	v_cvt_pk_bf16_f32 v84, v84, v85
	v_pk_mul_f32 v[86:87], v[92:93], v[86:87]
	s_nop 0
	v_cvt_pk_bf16_f32 v85, v86, v87
	v_pk_mul_f32 v[86:87], v[88:89], v[100:101]
	s_nop 0
	v_pk_mul_f32 v[80:81], v[86:87], v[80:81]
	s_nop 0
	v_cvt_pk_bf16_f32 v86, v80, v81
	v_pk_mul_f32 v[80:81], v[90:91], v[102:103]
	s_nop 0
	v_pk_mul_f32 v[80:81], v[80:81], v[82:83]
	v_mul_f32_e32 v82, 0xbfb8aa3b, v78
	v_cvt_pk_bf16_f32 v87, v80, v81
	v_or_b32_e32 v80, 32, v138
	v_mad_i64_i32 v[80:81], s[2:3], v80, s4, v[112:113]
	v_lshl_add_u64 v[80:81], v[80:81], 0, v[114:115]
	global_store_dwordx4 v[80:81], v[84:87], off
	v_mul_f32_e32 v80, 0xbfb8aa3b, v76
	v_mul_f32_e32 v81, 0xbfb8aa3b, v77
	v_exp_f32_e32 v80, v80
	v_exp_f32_e32 v81, v81
	v_mul_f32_e32 v83, 0xbfb8aa3b, v79
	v_exp_f32_e32 v82, v82
	v_exp_f32_e32 v83, v83
	v_mul_f32_e32 v84, 0xbfb8aa3b, v72
	v_mul_f32_e32 v85, 0xbfb8aa3b, v73
	v_exp_f32_e32 v84, v84
	v_exp_f32_e32 v85, v85
	v_add_f32_e32 v80, 1.0, v80
	v_add_f32_e32 v81, 1.0, v81
	v_mul_f32_e32 v86, 0xbfb8aa3b, v74
	v_mul_f32_e32 v87, 0xbfb8aa3b, v75
	v_rcp_f32_e32 v80, v80
	v_rcp_f32_e32 v81, v81
	v_add_f32_e32 v82, 1.0, v82
	v_add_f32_e32 v83, 1.0, v83
	v_exp_f32_e32 v86, v86
	v_exp_f32_e32 v87, v87
	v_rcp_f32_e32 v82, v82
	v_rcp_f32_e32 v83, v83
	v_add_f32_e32 v84, 1.0, v84
	v_add_f32_e32 v85, 1.0, v85
	v_rcp_f32_e32 v84, v84
	v_rcp_f32_e32 v85, v85
	v_add_f32_e32 v86, 1.0, v86
	v_add_f32_e32 v87, 1.0, v87
	v_pk_mul_f32 v[76:77], v[76:77], v[80:81]
	v_rcp_f32_e32 v86, v86
	v_rcp_f32_e32 v87, v87
	v_pk_mul_f32 v[68:69], v[76:77], v[68:69]
	v_pk_mul_f32 v[76:77], v[78:79], v[82:83]
	v_cvt_pk_bf16_f32 v68, v68, v69
	v_pk_mul_f32 v[70:71], v[76:77], v[70:71]
	s_nop 0
	v_cvt_pk_bf16_f32 v69, v70, v71
	v_pk_mul_f32 v[70:71], v[72:73], v[84:85]
	v_add_u32_e32 v72, 0x80, v138
	v_pk_mul_f32 v[64:65], v[70:71], v[64:65]
	s_nop 0
	v_cvt_pk_bf16_f32 v70, v64, v65
	v_pk_mul_f32 v[64:65], v[74:75], v[86:87]
	s_nop 0
	v_pk_mul_f32 v[64:65], v[64:65], v[66:67]
	v_mul_f32_e32 v66, 0xbfb8aa3b, v62
	v_cvt_pk_bf16_f32 v71, v64, v65
	v_or_b32_e32 v64, 48, v138
	v_mad_i64_i32 v[64:65], s[2:3], v64, s4, v[112:113]
	v_lshl_add_u64 v[64:65], v[64:65], 0, v[114:115]
	global_store_dwordx4 v[64:65], v[68:71], off
	v_mul_f32_e32 v64, 0xbfb8aa3b, v60
	v_mul_f32_e32 v65, 0xbfb8aa3b, v61
	v_exp_f32_e32 v64, v64
	v_exp_f32_e32 v65, v65
	v_mul_f32_e32 v67, 0xbfb8aa3b, v63
	v_exp_f32_e32 v66, v66
	v_exp_f32_e32 v67, v67
	v_mul_f32_e32 v68, 0xbfb8aa3b, v56
	v_mul_f32_e32 v69, 0xbfb8aa3b, v57
	v_exp_f32_e32 v68, v68
	v_exp_f32_e32 v69, v69
	v_add_f32_e32 v64, 1.0, v64
	v_add_f32_e32 v65, 1.0, v65
	v_mul_f32_e32 v70, 0xbfb8aa3b, v58
	v_mul_f32_e32 v71, 0xbfb8aa3b, v59
	v_rcp_f32_e32 v64, v64
	v_rcp_f32_e32 v65, v65
	v_add_f32_e32 v66, 1.0, v66
	v_add_f32_e32 v67, 1.0, v67
	v_exp_f32_e32 v70, v70
	v_exp_f32_e32 v71, v71
	v_rcp_f32_e32 v66, v66
	v_rcp_f32_e32 v67, v67
	v_add_f32_e32 v68, 1.0, v68
	v_add_f32_e32 v69, 1.0, v69
	v_rcp_f32_e32 v68, v68
	v_rcp_f32_e32 v69, v69
	v_add_f32_e32 v70, 1.0, v70
	v_add_f32_e32 v71, 1.0, v71
	v_pk_mul_f32 v[60:61], v[60:61], v[64:65]
	v_rcp_f32_e32 v70, v70
	v_rcp_f32_e32 v71, v71
	v_pk_mul_f32 v[52:53], v[60:61], v[52:53]
	v_pk_mul_f32 v[60:61], v[62:63], v[66:67]
	v_cvt_pk_bf16_f32 v52, v52, v53
	v_pk_mul_f32 v[54:55], v[60:61], v[54:55]
	s_nop 0
	v_cvt_pk_bf16_f32 v53, v54, v55
	v_pk_mul_f32 v[54:55], v[56:57], v[68:69]
; #define PG8_WAIT_V(n) asm volatile("s_waitcnt vmcnt(" #n ")" ::: "memory")
; #define PG8_BAR __builtin_amdgcn_s_barrier()
; template <class Epi>
; DI void gemm_phase(LAS unsigned char* lds, const Gemm g, const StaticOrder& S, const Epi& E) {
;     ...
;     PG8_WAIT_V(0);
;     if (wr == 0) PG8_BAR;
;     PG8_BAR;
;     DI void operator()(const f32x4 (&acc)[2][2][4][2], const Unit& u, int wr, int wc, int fr, int fq) const {
;     ...
;             for (int m = 0; m < 4; ++m) { float hv[8];
; #pragma unroll
;                 for (int n = 0; n < 2; ++n)
; #pragma unroll
;                     for (int e = 0; e < 4; ++e) { const float gt = acc[ai][0][m][n][e], up = acc[ai][1][m][n][e];
;                         hv[n * 4 + e] = gt * __builtin_amdgcn_rcpf(1.f + __builtin_amdgcn_exp2f(-1.4426950408889634f * gt)) * up; }
;                 *(u32x4*)(H + (size_t)(row0 + ai * HALF + m * 16) * DFF + col0) = (u32x4){pk(hv[0], hv[1]), pk(hv[2], hv[3]), pk(hv[4], hv[5]), pk(hv[6], hv[7])}; }
	s_nop 0
	v_pk_mul_f32 v[48:49], v[54:55], v[48:49]
	s_nop 0
	v_cvt_pk_bf16_f32 v54, v48, v49
	v_pk_mul_f32 v[48:49], v[58:59], v[70:71]
	s_nop 0
	v_pk_mul_f32 v[48:49], v[48:49], v[50:51]
	v_mul_f32_e32 v50, 0xbfb8aa3b, v46
	v_cvt_pk_bf16_f32 v55, v48, v49
	v_mad_i64_i32 v[48:49], s[2:3], v72, s4, v[112:113]
	v_lshl_add_u64 v[48:49], v[48:49], 0, v[114:115]
	global_store_dwordx4 v[48:49], v[52:55], off
	v_mul_f32_e32 v48, 0xbfb8aa3b, v44
	v_mul_f32_e32 v49, 0xbfb8aa3b, v45
	v_exp_f32_e32 v48, v48
	v_exp_f32_e32 v49, v49
	v_mul_f32_e32 v51, 0xbfb8aa3b, v47
	v_exp_f32_e32 v50, v50
	v_exp_f32_e32 v51, v51
	v_mul_f32_e32 v52, 0xbfb8aa3b, v40
	v_mul_f32_e32 v53, 0xbfb8aa3b, v41
	v_exp_f32_e32 v52, v52
	v_exp_f32_e32 v53, v53
	v_add_f32_e32 v48, 1.0, v48
	v_add_f32_e32 v49, 1.0, v49
	v_mul_f32_e32 v54, 0xbfb8aa3b, v42
	v_mul_f32_e32 v55, 0xbfb8aa3b, v43
	v_rcp_f32_e32 v48, v48
	v_rcp_f32_e32 v49, v49
	v_add_f32_e32 v50, 1.0, v50
	v_add_f32_e32 v51, 1.0, v51
	v_exp_f32_e32 v54, v54
	v_exp_f32_e32 v55, v55
	v_rcp_f32_e32 v50, v50
	v_rcp_f32_e32 v51, v51
	v_add_f32_e32 v52, 1.0, v52
	v_add_f32_e32 v53, 1.0, v53
	v_rcp_f32_e32 v52, v52
	v_rcp_f32_e32 v53, v53
	v_add_f32_e32 v54, 1.0, v54
	v_add_f32_e32 v55, 1.0, v55
	v_pk_mul_f32 v[44:45], v[44:45], v[48:49]
	v_rcp_f32_e32 v54, v54
	v_rcp_f32_e32 v55, v55
	v_pk_mul_f32 v[36:37], v[44:45], v[36:37]
	v_pk_mul_f32 v[44:45], v[46:47], v[50:51]
	v_cvt_pk_bf16_f32 v36, v36, v37
	v_pk_mul_f32 v[38:39], v[44:45], v[38:39]
	s_nop 0
	v_cvt_pk_bf16_f32 v37, v38, v39
	v_pk_mul_f32 v[38:39], v[40:41], v[52:53]
	s_nop 0
	v_pk_mul_f32 v[32:33], v[38:39], v[32:33]
	s_nop 0
	v_cvt_pk_bf16_f32 v38, v32, v33
	v_pk_mul_f32 v[32:33], v[42:43], v[54:55]
	s_nop 0
	v_pk_mul_f32 v[32:33], v[32:33], v[34:35]
	v_mul_f32_e32 v34, 0xbfb8aa3b, v30
	v_cvt_pk_bf16_f32 v39, v32, v33
	v_add_u32_e32 v32, 0x90, v138
	v_mad_i64_i32 v[32:33], s[2:3], v32, s4, v[112:113]
	v_lshl_add_u64 v[32:33], v[32:33], 0, v[114:115]
	global_store_dwordx4 v[32:33], v[36:39], off
	v_mul_f32_e32 v32, 0xbfb8aa3b, v28
	v_mul_f32_e32 v33, 0xbfb8aa3b, v29
	v_exp_f32_e32 v32, v32
	v_exp_f32_e32 v33, v33
	v_mul_f32_e32 v35, 0xbfb8aa3b, v31
	v_exp_f32_e32 v34, v34
	v_exp_f32_e32 v35, v35
	v_mul_f32_e32 v36, 0xbfb8aa3b, v24
	v_mul_f32_e32 v37, 0xbfb8aa3b, v25
	v_exp_f32_e32 v36, v36
	v_exp_f32_e32 v37, v37
	v_add_f32_e32 v32, 1.0, v32
	v_add_f32_e32 v33, 1.0, v33
	v_mul_f32_e32 v38, 0xbfb8aa3b, v26
	v_mul_f32_e32 v39, 0xbfb8aa3b, v27
	v_rcp_f32_e32 v32, v32
	v_rcp_f32_e32 v33, v33
	v_add_f32_e32 v34, 1.0, v34
	v_add_f32_e32 v35, 1.0, v35
	v_exp_f32_e32 v38, v38
	v_exp_f32_e32 v39, v39
	v_rcp_f32_e32 v34, v34
	v_rcp_f32_e32 v35, v35
	v_add_f32_e32 v36, 1.0, v36
	v_add_f32_e32 v37, 1.0, v37
	v_rcp_f32_e32 v36, v36
	v_rcp_f32_e32 v37, v37
	v_add_f32_e32 v38, 1.0, v38
	v_add_f32_e32 v39, 1.0, v39
	v_pk_mul_f32 v[28:29], v[28:29], v[32:33]
	v_rcp_f32_e32 v38, v38
	v_rcp_f32_e32 v39, v39
	v_pk_mul_f32 v[20:21], v[28:29], v[20:21]
	v_pk_mul_f32 v[28:29], v[30:31], v[34:35]
	v_cvt_pk_bf16_f32 v20, v20, v21
	v_pk_mul_f32 v[22:23], v[28:29], v[22:23]
	s_nop 0
	v_cvt_pk_bf16_f32 v21, v22, v23
	v_pk_mul_f32 v[22:23], v[24:25], v[36:37]
	s_nop 0
	v_pk_mul_f32 v[16:17], v[22:23], v[16:17]
	s_nop 0
	v_cvt_pk_bf16_f32 v22, v16, v17
	v_pk_mul_f32 v[16:17], v[26:27], v[38:39]
	s_nop 0
	v_pk_mul_f32 v[16:17], v[16:17], v[18:19]
	v_mul_f32_e32 v18, 0xbfb8aa3b, v14
	v_cvt_pk_bf16_f32 v23, v16, v17
	v_add_u32_e32 v16, 0xa0, v138
	v_mad_i64_i32 v[16:17], s[2:3], v16, s4, v[112:113]
	v_lshl_add_u64 v[16:17], v[16:17], 0, v[114:115]
	global_store_dwordx4 v[16:17], v[20:23], off
	v_mul_f32_e32 v16, 0xbfb8aa3b, v12
	v_mul_f32_e32 v17, 0xbfb8aa3b, v13
	v_exp_f32_e32 v16, v16
	v_exp_f32_e32 v17, v17
	v_mul_f32_e32 v19, 0xbfb8aa3b, v15
	v_exp_f32_e32 v18, v18
	v_exp_f32_e32 v19, v19
	v_mul_f32_e32 v20, 0xbfb8aa3b, v8
	v_mul_f32_e32 v21, 0xbfb8aa3b, v9
	v_exp_f32_e32 v20, v20
	v_exp_f32_e32 v21, v21
	v_add_f32_e32 v16, 1.0, v16
	v_add_f32_e32 v17, 1.0, v17
	v_mul_f32_e32 v22, 0xbfb8aa3b, v10
	v_mul_f32_e32 v23, 0xbfb8aa3b, v11
	v_rcp_f32_e32 v16, v16
	v_rcp_f32_e32 v17, v17
	v_add_f32_e32 v18, 1.0, v18
	v_add_f32_e32 v19, 1.0, v19
	v_exp_f32_e32 v22, v22
	v_exp_f32_e32 v23, v23
	v_rcp_f32_e32 v18, v18
	v_rcp_f32_e32 v19, v19
	v_add_f32_e32 v20, 1.0, v20
	v_add_f32_e32 v21, 1.0, v21
	v_rcp_f32_e32 v20, v20
	v_rcp_f32_e32 v21, v21
	v_add_f32_e32 v22, 1.0, v22
	v_add_f32_e32 v23, 1.0, v23
	v_pk_mul_f32 v[12:13], v[12:13], v[16:17]
	v_rcp_f32_e32 v22, v22
	v_rcp_f32_e32 v23, v23
	v_pk_mul_f32 v[4:5], v[12:13], v[4:5]
	v_pk_mul_f32 v[12:13], v[14:15], v[18:19]
	v_cvt_pk_bf16_f32 v4, v4, v5
	v_pk_mul_f32 v[6:7], v[12:13], v[6:7]
	s_nop 0
	v_cvt_pk_bf16_f32 v5, v6, v7
	v_pk_mul_f32 v[6:7], v[8:9], v[20:21]
	s_nop 0
	v_pk_mul_f32 v[0:1], v[6:7], v[0:1]
	s_nop 0
	v_cvt_pk_bf16_f32 v6, v0, v1
	v_pk_mul_f32 v[0:1], v[10:11], v[22:23]
	s_nop 0
	v_pk_mul_f32 v[0:1], v[0:1], v[2:3]
	s_nop 0
	v_cvt_pk_bf16_f32 v7, v0, v1
	v_add_u32_e32 v0, 0xb0, v138
	v_mad_i64_i32 v[0:1], s[2:3], v0, s4, v[112:113]
	v_lshl_add_u64 v[0:1], v[0:1], 0, v[114:115]
	s_mov_b32 s2, s8
	s_mov_b32 s3, s10
	global_store_dwordx4 v[0:1], v[4:7], off
	s_cbranch_vccz .LBB0_34
	s_waitcnt vmcnt(0)
	s_cmpk_gt_u32 s24, 0xff
	s_cbranch_scc1 .LBB0_41
	s_barrier

; #define PG8_STAGE(bufoff, gbase) do { _Pragma("unroll") for (int _i = 0; _i < 2; ++_i) \
;         __builtin_amdgcn_global_load_lds((const unsigned*)((const char*)(gbase) + voff[_i]), (LAS unsigned*)(lds + (bufoff) + ldsw + _i * 8192), 16, 0, 0); } while (0)
; #define PG8_LDA(dst, b, h) do { _Pragma("unroll") for (int m = 0; m < 4; ++m) _Pragma("unroll") for (int k = 0; k < 2; ++k) dst[m][k] = *(const LAS bf16x8*)(lds + PG8_SA(b, h) + aoff + m * 2048 + k * 1024); } while (0)
; #define PG8_LDB(dst, b, h) do { _Pragma("unroll") for (int n = 0; n < 2; ++n) _Pragma("unroll") for (int k = 0; k < 2; ++k) dst[n][k] = *(const LAS bf16x8*)(lds + PG8_SB(b, h) + boff + n * 2048 + k * 1024); } while (0)
; #define PG8_MMA(ai, bj, At, Bt) do { __builtin_amdgcn_s_setprio(1); _Pragma("unroll") for (int m = 0; m < 4; ++m) _Pragma("unroll") for (int n = 0; n < 2; ++n) _Pragma("unroll") for (int k = 0; k < 2; ++k) \
;         acc[ai][bj][m][n] = __builtin_amdgcn_mfma_f32_16x16x32_bf16(Bt[n][k], At[m][k], acc[ai][bj][m][n], 0, 0, 0); __builtin_amdgcn_s_setprio(0); } while (0)
; #define PG8_WAIT_L(n) asm volatile("s_waitcnt lgkmcnt(" #n ")" ::: "memory")
; #define PG8_BAR __builtin_amdgcn_s_barrier()
; #define PG8_SCHED __builtin_amdgcn_sched_barrier(0)
; template <class Epi>
; DI void gemm_phase(LAS unsigned char* lds, const Gemm g, const StaticOrder& S, const Epi& E) {
;     ...
;         for (int t = 0; t < nt; t += 2) {
;             const bool last = (t == nt - 2);
;             const char* a1 = cA + (size_t)(t + 1) * kstep;
;             const char* a2 = last ? nA : cA + (size_t)(t + 2) * kstep; const char* b2 = last ? nB : cB + (size_t)(t + 2) * kstep;
;             const char* a3 = a2 + kstep; const char* b3 = b2 + kstep;
;             PG8_LDB(B0, 0, 0); PG8_SCHED; PG8_LDA(At, 0, 0); PG8_STAGE(PG8_SA(1, 1), a1 + hstep);
;             PG8_WAIT_L(8); PG8_BAR; PG8_WAIT_L(0); PG8_MMA(0, 0, At, B0); PG8_BAR; PG8_SCHED;
;             PG8_LDB(B1, 0, 1); PG8_STAGE(PG8_SB(0, 0), b2);
;             PG8_BAR; PG8_WAIT_L(0); PG8_MMA(0, 1, At, B1); PG8_BAR;
;             PG8_LDA(At, 0, 1); PG8_STAGE(PG8_SA(0, 0), a2);
;             PG8_BAR; PG8_WAIT_L(0); PG8_MMA(1, 0, At, B0); PG8_BAR; PG8_SCHED;
.LBB0_77:
	s_add_u32 s22, s20, 0x100
	s_addc_u32 s23, s21, 0
	s_add_i32 s43, 0, 0x10000
	v_add_u32_e32 v140, s43, v226
	ds_read_b128 v[128:131], v140
	ds_read_b128 v[132:135], v140 offset:1024
	ds_read_b128 v[136:139], v140 offset:2048
	ds_read_b128 v[140:143], v140 offset:3072
	s_cmp_eq_u32 s33, 32
	s_cselect_b32 s27, s9, s23
	s_cselect_b32 s26, s8, s22
	s_cselect_b32 s25, s11, s5
	s_cselect_b32 s24, s10, s4
	v_lshl_add_u64 v[214:215], s[20:21], 0, v[190:191]
	s_add_i32 m0, s34, 0xc000
	ds_read_b128 v[144:147], v228
	ds_read_b128 v[148:151], v228 offset:1024
	ds_read_b128 v[152:155], v228 offset:2048
	ds_read_b128 v[194:197], v228 offset:3072
	ds_read_b128 v[198:201], v228 offset:4096
	ds_read_b128 v[202:205], v228 offset:5120
	ds_read_b128 v[206:209], v228 offset:6144
	ds_read_b128 v[210:213], v228 offset:7168
	global_load_lds_dwordx4 v[214:215], off
	v_lshl_add_u64 v[214:215], s[20:21], 0, v[192:193]
	s_add_i32 m0, s34, 0xe000
	s_nop 0
	global_load_lds_dwordx4 v[214:215], off
	s_waitcnt lgkmcnt(8)
	s_setprio 1
	s_barrier
	s_waitcnt lgkmcnt(0)
	v_mfma_f32_16x16x32_bf16 v[124:127], v[128:131], v[144:147], v[124:127]
	v_mfma_f32_16x16x32_bf16 v[120:123], v[136:139], v[144:147], v[120:123]
	v_mfma_f32_16x16x32_bf16 v[116:119], v[128:131], v[152:155], v[116:119]
	v_mfma_f32_16x16x32_bf16 v[112:115], v[136:139], v[152:155], v[112:115]
	v_mfma_f32_16x16x32_bf16 v[108:111], v[128:131], v[198:201], v[108:111]
	v_mfma_f32_16x16x32_bf16 v[104:107], v[136:139], v[198:201], v[104:107]
	v_mfma_f32_16x16x32_bf16 v[100:103], v[128:131], v[206:209], v[100:103]
	v_mfma_f32_16x16x32_bf16 v[96:99], v[136:139], v[206:209], v[96:99]
	v_mfma_f32_16x16x32_bf16 v[124:127], v[132:135], v[148:151], v[124:127]
	v_mfma_f32_16x16x32_bf16 v[120:123], v[140:143], v[148:151], v[120:123]
	v_mfma_f32_16x16x32_bf16 v[116:119], v[132:135], v[194:197], v[116:119]
	v_mfma_f32_16x16x32_bf16 v[112:115], v[140:143], v[194:197], v[112:115]
	v_mfma_f32_16x16x32_bf16 v[108:111], v[132:135], v[202:205], v[108:111]
	v_mfma_f32_16x16x32_bf16 v[104:107], v[140:143], v[202:205], v[104:107]
	v_mfma_f32_16x16x32_bf16 v[100:103], v[132:135], v[210:213], v[100:103]
	v_mfma_f32_16x16x32_bf16 v[96:99], v[140:143], v[210:213], v[96:99]
	s_setprio 0
	s_barrier
	s_add_i32 s44, 0, 0x14000
	s_add_i32 s20, s43, s31
	v_add_u32_e32 v158, s44, v226
	v_lshl_add_u64 v[218:219], s[24:25], 0, v[188:189]
	s_mov_b32 m0, s20
	ds_read_b128 v[214:217], v158
	ds_read_b128 v[230:233], v158 offset:1024
	ds_read_b128 v[234:237], v158 offset:2048
	ds_read_b128 v[238:241], v158 offset:3072
	global_load_lds_dwordx4 v[218:219], off
	v_lshl_add_u64 v[220:221], s[24:25], 0, v[186:187]
	s_add_i32 m0, s20, 0x2000
	s_nop 0
	global_load_lds_dwordx4 v[220:221], off
	s_setprio 1
	s_barrier
	s_waitcnt lgkmcnt(0)
	v_mfma_f32_16x16x32_bf16 v[60:63], v[214:217], v[144:147], v[60:63]
	v_mfma_f32_16x16x32_bf16 v[56:59], v[234:237], v[144:147], v[56:59]
	v_mfma_f32_16x16x32_bf16 v[52:55], v[214:217], v[152:155], v[52:55]
	v_mfma_f32_16x16x32_bf16 v[48:51], v[234:237], v[152:155], v[48:51]
	v_mfma_f32_16x16x32_bf16 v[44:47], v[214:217], v[198:201], v[44:47]
	v_mfma_f32_16x16x32_bf16 v[40:43], v[234:237], v[198:201], v[40:43]
	v_mfma_f32_16x16x32_bf16 v[36:39], v[214:217], v[206:209], v[36:39]
	v_mfma_f32_16x16x32_bf16 v[32:35], v[234:237], v[206:209], v[32:35]
	v_mfma_f32_16x16x32_bf16 v[60:63], v[230:233], v[148:151], v[60:63]
	v_mfma_f32_16x16x32_bf16 v[56:59], v[238:241], v[148:151], v[56:59]
	v_mfma_f32_16x16x32_bf16 v[52:55], v[230:233], v[194:197], v[52:55]
	v_mfma_f32_16x16x32_bf16 v[48:51], v[238:241], v[194:197], v[48:51]
	v_mfma_f32_16x16x32_bf16 v[44:47], v[230:233], v[202:205], v[44:47]
	v_mfma_f32_16x16x32_bf16 v[40:43], v[238:241], v[202:205], v[40:43]
	v_mfma_f32_16x16x32_bf16 v[36:39], v[230:233], v[210:213], v[36:39]
	v_mfma_f32_16x16x32_bf16 v[32:35], v[238:241], v[210:213], v[32:35]
	s_setprio 0
	s_mov_b32 m0, s34
	v_lshl_add_u64 v[242:243], s[26:27], 0, v[188:189]
	s_barrier
	ds_read_b128 v[144:147], v228 offset:16384
	ds_read_b128 v[148:151], v228 offset:17408
	ds_read_b128 v[152:155], v228 offset:18432
	ds_read_b128 v[194:197], v228 offset:19456
	ds_read_b128 v[198:201], v228 offset:20480
	ds_read_b128 v[202:205], v228 offset:21504
	ds_read_b128 v[206:209], v228 offset:22528
	ds_read_b128 v[210:213], v228 offset:23552
	global_load_lds_dwordx4 v[242:243], off
	v_lshl_add_u64 v[244:245], s[26:27], 0, v[186:187]
	s_mov_b32 m0, s35
	s_nop 0
	global_load_lds_dwordx4 v[244:245], off
	s_setprio 1
	s_barrier
	s_waitcnt lgkmcnt(0)
	v_mfma_f32_16x16x32_bf16 v[92:95], v[128:131], v[144:147], v[92:95]
	v_mfma_f32_16x16x32_bf16 v[88:91], v[136:139], v[144:147], v[88:91]
	v_mfma_f32_16x16x32_bf16 v[84:87], v[128:131], v[152:155], v[84:87]
	v_mfma_f32_16x16x32_bf16 v[80:83], v[136:139], v[152:155], v[80:83]
	v_mfma_f32_16x16x32_bf16 v[76:79], v[128:131], v[198:201], v[76:79]
	v_mfma_f32_16x16x32_bf16 v[72:75], v[136:139], v[198:201], v[72:75]
	v_mfma_f32_16x16x32_bf16 v[68:71], v[128:131], v[206:209], v[68:71]
	v_mfma_f32_16x16x32_bf16 v[64:67], v[136:139], v[206:209], v[64:67]
	v_mfma_f32_16x16x32_bf16 v[92:95], v[132:135], v[148:151], v[92:95]
	v_mfma_f32_16x16x32_bf16 v[88:91], v[140:143], v[148:151], v[88:91]
	v_mfma_f32_16x16x32_bf16 v[84:87], v[132:135], v[194:197], v[84:87]
	v_mfma_f32_16x16x32_bf16 v[80:83], v[140:143], v[194:197], v[80:83]
	v_mfma_f32_16x16x32_bf16 v[76:79], v[132:135], v[202:205], v[76:79]
	v_mfma_f32_16x16x32_bf16 v[72:75], v[140:143], v[202:205], v[72:75]
	v_mfma_f32_16x16x32_bf16 v[68:71], v[132:135], v[210:213], v[68:71]
	v_mfma_f32_16x16x32_bf16 v[64:67], v[140:143], v[210:213], v[64:67]
	s_setprio 0
	s_barrier
; #define PG8_STAGE(bufoff, gbase) do { _Pragma("unroll") for (int _i = 0; _i < 2; ++_i) \
;         __builtin_amdgcn_global_load_lds((const unsigned*)((const char*)(gbase) + voff[_i]), (LAS unsigned*)(lds + (bufoff) + ldsw + _i * 8192), 16, 0, 0); } while (0)
; #define PG8_LDA(dst, b, h) do { _Pragma("unroll") for (int m = 0; m < 4; ++m) _Pragma("unroll") for (int k = 0; k < 2; ++k) dst[m][k] = *(const LAS bf16x8*)(lds + PG8_SA(b, h) + aoff + m * 2048 + k * 1024); } while (0)
; #define PG8_LDB(dst, b, h) do { _Pragma("unroll") for (int n = 0; n < 2; ++n) _Pragma("unroll") for (int k = 0; k < 2; ++k) dst[n][k] = *(const LAS bf16x8*)(lds + PG8_SB(b, h) + boff + n * 2048 + k * 1024); } while (0)
; #define PG8_MMA(ai, bj, At, Bt) do { __builtin_amdgcn_s_setprio(1); _Pragma("unroll") for (int m = 0; m < 4; ++m) _Pragma("unroll") for (int n = 0; n < 2; ++n) _Pragma("unroll") for (int k = 0; k < 2; ++k) \
;         acc[ai][bj][m][n] = __builtin_amdgcn_mfma_f32_16x16x32_bf16(Bt[n][k], At[m][k], acc[ai][bj][m][n], 0, 0, 0); __builtin_amdgcn_s_setprio(0); } while (0)
; #define PG8_WAIT_V(n) asm volatile("s_waitcnt vmcnt(" #n ")" ::: "memory")
; #define PG8_WAIT_L(n) asm volatile("s_waitcnt lgkmcnt(" #n ")" ::: "memory")
; #define PG8_BAR __builtin_amdgcn_s_barrier()
; #define PG8_SCHED __builtin_amdgcn_sched_barrier(0)
; template <class Epi>
; DI void gemm_phase(LAS unsigned char* lds, const Gemm g, const StaticOrder& S, const Epi& E) {
;     ...
;             PG8_STAGE(PG8_SB(0, 1), b2 + hstep);
;             PG8_WAIT_V(6); PG8_BAR; PG8_MMA(1, 1, At, B1); PG8_BAR;
;             PG8_LDB(B0, 1, 0); PG8_SCHED; PG8_LDA(At, 1, 0); PG8_STAGE(PG8_SA(0, 1), a2 + hstep);
;             PG8_WAIT_L(8); PG8_BAR; PG8_WAIT_L(0); PG8_MMA(0, 0, At, B0); PG8_BAR; PG8_SCHED;
;             PG8_LDB(B1, 1, 1); PG8_STAGE(PG8_SB(1, 0), b3);
;             PG8_BAR; PG8_WAIT_L(0); PG8_MMA(0, 1, At, B1); PG8_BAR;
;             PG8_LDA(At, 1, 1); PG8_STAGE(PG8_SA(1, 0), a3);
	s_add_u32 s20, s24, 0x90000
	s_addc_u32 s21, s25, 0
	s_add_i32 s43, s44, s31
	v_lshl_add_u64 v[128:129], s[20:21], 0, v[188:189]
	s_mov_b32 m0, s43
	s_nop 0
	global_load_lds_dwordx4 v[128:129], off
	v_lshl_add_u64 v[128:129], s[20:21], 0, v[186:187]
	s_add_i32 m0, s43, 0x2000
	s_nop 0
	global_load_lds_dwordx4 v[128:129], off
	s_waitcnt vmcnt(6)
	s_setprio 1
	s_barrier
	v_mfma_f32_16x16x32_bf16 v[28:31], v[214:217], v[144:147], v[28:31]
	v_mfma_f32_16x16x32_bf16 v[24:27], v[234:237], v[144:147], v[24:27]
	v_mfma_f32_16x16x32_bf16 v[20:23], v[214:217], v[152:155], v[20:23]
	v_mfma_f32_16x16x32_bf16 v[16:19], v[234:237], v[152:155], v[16:19]
	v_mfma_f32_16x16x32_bf16 v[12:15], v[214:217], v[198:201], v[12:15]
	v_mfma_f32_16x16x32_bf16 v[8:11], v[234:237], v[198:201], v[8:11]
	v_mfma_f32_16x16x32_bf16 v[4:7], v[214:217], v[206:209], v[4:7]
	v_mfma_f32_16x16x32_bf16 v[0:3], v[234:237], v[206:209], v[0:3]
	v_mfma_f32_16x16x32_bf16 v[28:31], v[230:233], v[148:151], v[28:31]
	v_mfma_f32_16x16x32_bf16 v[24:27], v[238:241], v[148:151], v[24:27]
	v_mfma_f32_16x16x32_bf16 v[20:23], v[230:233], v[194:197], v[20:23]
	v_mfma_f32_16x16x32_bf16 v[16:19], v[238:241], v[194:197], v[16:19]
	v_mfma_f32_16x16x32_bf16 v[12:15], v[230:233], v[202:205], v[12:15]
	v_mfma_f32_16x16x32_bf16 v[8:11], v[238:241], v[202:205], v[8:11]
	v_mfma_f32_16x16x32_bf16 v[4:7], v[230:233], v[210:213], v[4:7]
	v_mfma_f32_16x16x32_bf16 v[0:3], v[238:241], v[210:213], v[0:3]
	s_setprio 0
	s_add_i32 s43, 0, 0x18000
	v_add_u32_e32 v140, s43, v226
	s_barrier
	ds_read_b128 v[128:131], v140
	ds_read_b128 v[132:135], v140 offset:1024
	ds_read_b128 v[136:139], v140 offset:2048
	ds_read_b128 v[140:143], v140 offset:3072
	s_add_u32 s20, s26, 0x90000
	s_addc_u32 s21, s27, 0
	s_mov_b32 m0, s36
	v_lshl_add_u64 v[214:215], s[20:21], 0, v[188:189]
	ds_read_b128 v[144:147], v228 offset:32768
	ds_read_b128 v[148:151], v228 offset:33792
	ds_read_b128 v[152:155], v228 offset:34816
	ds_read_b128 v[194:197], v228 offset:35840
	ds_read_b128 v[198:201], v228 offset:36864
	ds_read_b128 v[202:205], v228 offset:37888
	ds_read_b128 v[206:209], v228 offset:38912
	ds_read_b128 v[210:213], v228 offset:39936
	global_load_lds_dwordx4 v[214:215], off
	v_lshl_add_u64 v[214:215], s[20:21], 0, v[186:187]
	s_mov_b32 m0, s37
	s_nop 0
	global_load_lds_dwordx4 v[214:215], off
	s_waitcnt lgkmcnt(8)
	s_setprio 1
	s_barrier
	s_waitcnt lgkmcnt(0)
	v_mfma_f32_16x16x32_bf16 v[124:127], v[128:131], v[144:147], v[124:127]
	v_mfma_f32_16x16x32_bf16 v[120:123], v[136:139], v[144:147], v[120:123]
	v_mfma_f32_16x16x32_bf16 v[116:119], v[128:131], v[152:155], v[116:119]
	v_mfma_f32_16x16x32_bf16 v[112:115], v[136:139], v[152:155], v[112:115]
	v_mfma_f32_16x16x32_bf16 v[108:111], v[128:131], v[198:201], v[108:111]
	v_mfma_f32_16x16x32_bf16 v[104:107], v[136:139], v[198:201], v[104:107]
	v_mfma_f32_16x16x32_bf16 v[100:103], v[128:131], v[206:209], v[100:103]
	v_mfma_f32_16x16x32_bf16 v[96:99], v[136:139], v[206:209], v[96:99]
	v_mfma_f32_16x16x32_bf16 v[124:127], v[132:135], v[148:151], v[124:127]
	v_mfma_f32_16x16x32_bf16 v[120:123], v[140:143], v[148:151], v[120:123]
	v_mfma_f32_16x16x32_bf16 v[116:119], v[132:135], v[194:197], v[116:119]
	v_mfma_f32_16x16x32_bf16 v[112:115], v[140:143], v[194:197], v[112:115]
	v_mfma_f32_16x16x32_bf16 v[108:111], v[132:135], v[202:205], v[108:111]
	v_mfma_f32_16x16x32_bf16 v[104:107], v[140:143], v[202:205], v[104:107]
	v_mfma_f32_16x16x32_bf16 v[100:103], v[132:135], v[210:213], v[100:103]
	v_mfma_f32_16x16x32_bf16 v[96:99], v[140:143], v[210:213], v[96:99]
	s_setprio 0
	s_barrier
	s_add_i32 s26, 0, 0x1c000
	s_add_i32 s20, s43, s31
	v_add_u32_e32 v158, s26, v226
	v_lshl_add_u64 v[218:219], v[218:219], 0, s[94:95]
	s_mov_b32 m0, s20
	ds_read_b128 v[214:217], v158
	ds_read_b128 v[230:233], v158 offset:1024
	ds_read_b128 v[234:237], v158 offset:2048
	ds_read_b128 v[238:241], v158 offset:3072
	global_load_lds_dwordx4 v[218:219], off
	v_lshl_add_u64 v[218:219], v[220:221], 0, s[94:95]
	s_add_i32 m0, s20, 0x2000
	s_nop 0
	global_load_lds_dwordx4 v[218:219], off
	s_setprio 1
	s_barrier
	s_waitcnt lgkmcnt(0)
	v_mfma_f32_16x16x32_bf16 v[60:63], v[214:217], v[144:147], v[60:63]
	v_mfma_f32_16x16x32_bf16 v[56:59], v[234:237], v[144:147], v[56:59]
	v_mfma_f32_16x16x32_bf16 v[52:55], v[214:217], v[152:155], v[52:55]
	v_mfma_f32_16x16x32_bf16 v[48:51], v[234:237], v[152:155], v[48:51]
	v_mfma_f32_16x16x32_bf16 v[44:47], v[214:217], v[198:201], v[44:47]
	v_mfma_f32_16x16x32_bf16 v[40:43], v[234:237], v[198:201], v[40:43]
	v_mfma_f32_16x16x32_bf16 v[36:39], v[214:217], v[206:209], v[36:39]
	v_mfma_f32_16x16x32_bf16 v[32:35], v[234:237], v[206:209], v[32:35]
	v_mfma_f32_16x16x32_bf16 v[60:63], v[230:233], v[148:151], v[60:63]
	v_mfma_f32_16x16x32_bf16 v[56:59], v[238:241], v[148:151], v[56:59]
	v_mfma_f32_16x16x32_bf16 v[52:55], v[230:233], v[194:197], v[52:55]
	v_mfma_f32_16x16x32_bf16 v[48:51], v[238:241], v[194:197], v[48:51]
	v_mfma_f32_16x16x32_bf16 v[44:47], v[230:233], v[202:205], v[44:47]
	v_mfma_f32_16x16x32_bf16 v[40:43], v[238:241], v[202:205], v[40:43]
	v_mfma_f32_16x16x32_bf16 v[36:39], v[230:233], v[210:213], v[36:39]
	v_mfma_f32_16x16x32_bf16 v[32:35], v[238:241], v[210:213], v[32:35]
	s_setprio 0
	s_mov_b32 m0, s38
	v_lshl_add_u64 v[218:219], v[242:243], 0, s[94:95]
	s_barrier
	ds_read_b128 v[144:147], v228 offset:49152
	ds_read_b128 v[148:151], v228 offset:50176
	ds_read_b128 v[152:155], v228 offset:51200
	ds_read_b128 v[194:197], v228 offset:52224
	ds_read_b128 v[198:201], v228 offset:53248
	ds_read_b128 v[202:205], v228 offset:54272
	ds_read_b128 v[206:209], v228 offset:55296
	ds_read_b128 v[210:213], v228 offset:56320
	global_load_lds_dwordx4 v[218:219], off
	v_lshl_add_u64 v[218:219], v[244:245], 0, s[94:95]
	s_mov_b32 m0, s39
	s_nop 0
	global_load_lds_dwordx4 v[218:219], off
	s_setprio 1
	s_barrier
; #define PG8_BAR __builtin_amdgcn_s_barrier()
; template <class Epi>
; DI void gemm_phase(LAS unsigned char* lds, const Gemm g, const StaticOrder& S, const Epi& E) {
;     ...
;             PG8_BAR; PG8_WAIT_L(0); PG8_MMA(1, 0, At, B0); PG8_BAR; PG8_SCHED;
;             PG8_STAGE(PG8_SB(1, 1), b3 + hstep);
;             PG8_WAIT_V(6); PG8_BAR; PG8_MMA(1, 1, At, B1); PG8_BAR;
;     template <bool LN, int BJ, int LO, int HI> DI void batch(const f32x4 (&acc)[2][2][4][2], unsigned row0, unsigned col0, const f32x4 (&gv)[2], const f32x4 (&bv)[2]) const {
;         f32x4 r[HI - LO]; float mean[(HI - LO) / 2], rstd[(HI - LO) / 2];
; #pragma unroll
;         for (int i = LO; i < HI; ++i) { const int ai = i >> 3, m = (i >> 1) & 3, n = i & 1; const unsigned row = row0 + ai * HALF + m * 16;
;             if (n == 0) { mean[(i - LO) >> 1] = 0.f; rstd[(i - LO) >> 1] = 1.f;
;                 if (LN) { const float2 st = *(const float2*)(stats + row * 2u); mean[(i - LO) >> 1] = st.x; rstd[(i - LO) >> 1] = st.y; } }
;             r[i - LO] = *(const f32x4*)(src + (row * (unsigned)DM + col0 + BJ * HALF + n * 16)); }
; #pragma unroll
;         for (int i = LO; i < HI; ++i) { const int ai = i >> 3, m = (i >> 1) & 3, n = i & 1; const unsigned row = row0 + ai * HALF + m * 16;
;             *(f32x4*)(Y + (row * (unsigned)DM + col0 + BJ * HALF + n * 16)) = acc[ai][BJ][m][n] + ((r[i - LO] - mean[(i - LO) >> 1]) * rstd[(i - LO) >> 1]) * gv[n] + bv[n]; }
;         __builtin_amdgcn_sched_barrier(0);
;     }
;     template <bool LN, int BJ> DI void load_gb(unsigned col0, f32x4 (&gv)[2], f32x4 (&bv)[2]) const {
; #pragma unroll
;         for (int n = 0; n < 2; ++n) {
;             if (LN) { gv[n] = *(const f32x4*)(gam + col0 + BJ * HALF + n * 16) * ALPHA; bv[n] = *(const f32x4*)(bet + col0 + BJ * HALF + n * 16) * ALPHA; }
;             else { gv[n] = (f32x4){ALPHA, ALPHA, ALPHA, ALPHA}; bv[n] = (f32x4){0.f, 0.f, 0.f, 0.f}; }
;         }
;     }
;     template <bool LN> DI void run(const f32x4 (&acc)[2][2][4][2], const Unit& u, int wr, int wc, int fr, int fq) const {
;         const unsigned row0 = u.pm * BM + wr * 64 + fr, col0 = u.pn * BM + wc * 32 + 4 * fq;
;         f32x4 gv[2], bv[2];
;         load_gb<LN, 0>(col0, gv, bv);
;         batch<LN, 0, 0, 4>(acc, row0, col0, gv, bv);
;         batch<LN, 0, 4, 8>(acc, row0, col0, gv, bv);
;         batch<LN, 0, 8, 12>(acc, row0, col0, gv, bv);
	s_waitcnt lgkmcnt(0)
	v_mfma_f32_16x16x32_bf16 v[92:95], v[128:131], v[144:147], v[92:95]
	v_mfma_f32_16x16x32_bf16 v[88:91], v[136:139], v[144:147], v[88:91]
	v_mfma_f32_16x16x32_bf16 v[84:87], v[128:131], v[152:155], v[84:87]
	v_mfma_f32_16x16x32_bf16 v[80:83], v[136:139], v[152:155], v[80:83]
	v_mfma_f32_16x16x32_bf16 v[76:79], v[128:131], v[198:201], v[76:79]
	v_mfma_f32_16x16x32_bf16 v[72:75], v[136:139], v[198:201], v[72:75]
	v_mfma_f32_16x16x32_bf16 v[68:71], v[128:131], v[206:209], v[68:71]
	v_mfma_f32_16x16x32_bf16 v[64:67], v[136:139], v[206:209], v[64:67]
	v_mfma_f32_16x16x32_bf16 v[92:95], v[132:135], v[148:151], v[92:95]
	v_mfma_f32_16x16x32_bf16 v[88:91], v[140:143], v[148:151], v[88:91]
	v_mfma_f32_16x16x32_bf16 v[84:87], v[132:135], v[194:197], v[84:87]
	v_mfma_f32_16x16x32_bf16 v[80:83], v[140:143], v[194:197], v[80:83]
	v_mfma_f32_16x16x32_bf16 v[76:79], v[132:135], v[202:205], v[76:79]
	v_mfma_f32_16x16x32_bf16 v[72:75], v[140:143], v[202:205], v[72:75]
	v_mfma_f32_16x16x32_bf16 v[68:71], v[132:135], v[210:213], v[68:71]
	v_mfma_f32_16x16x32_bf16 v[64:67], v[140:143], v[210:213], v[64:67]
	s_setprio 0
	s_barrier
	s_add_u32 s20, s24, 0x90080
	s_addc_u32 s21, s25, 0
	s_add_i32 s24, s26, s31
	v_lshl_add_u64 v[128:129], s[20:21], 0, v[188:189]
	s_mov_b32 m0, s24
	s_nop 0
	global_load_lds_dwordx4 v[128:129], off
	v_lshl_add_u64 v[128:129], s[20:21], 0, v[186:187]
	s_add_i32 m0, s24, 0x2000
	s_nop 0
	global_load_lds_dwordx4 v[128:129], off
	s_waitcnt vmcnt(6)
	s_setprio 1
	s_barrier
	v_mfma_f32_16x16x32_bf16 v[28:31], v[214:217], v[144:147], v[28:31]
	v_mfma_f32_16x16x32_bf16 v[24:27], v[234:237], v[144:147], v[24:27]
	v_mfma_f32_16x16x32_bf16 v[20:23], v[214:217], v[152:155], v[20:23]
	v_mfma_f32_16x16x32_bf16 v[16:19], v[234:237], v[152:155], v[16:19]
	v_mfma_f32_16x16x32_bf16 v[12:15], v[214:217], v[198:201], v[12:15]
	v_mfma_f32_16x16x32_bf16 v[8:11], v[234:237], v[198:201], v[8:11]
	v_mfma_f32_16x16x32_bf16 v[4:7], v[214:217], v[206:209], v[4:7]
	v_mfma_f32_16x16x32_bf16 v[0:3], v[234:237], v[206:209], v[0:3]
	v_mfma_f32_16x16x32_bf16 v[28:31], v[230:233], v[148:151], v[28:31]
	v_mfma_f32_16x16x32_bf16 v[24:27], v[238:241], v[148:151], v[24:27]
	v_mfma_f32_16x16x32_bf16 v[20:23], v[230:233], v[194:197], v[20:23]
	v_mfma_f32_16x16x32_bf16 v[16:19], v[238:241], v[194:197], v[16:19]
	v_mfma_f32_16x16x32_bf16 v[12:15], v[230:233], v[202:205], v[12:15]
	v_mfma_f32_16x16x32_bf16 v[8:11], v[238:241], v[202:205], v[8:11]
	v_mfma_f32_16x16x32_bf16 v[4:7], v[230:233], v[210:213], v[4:7]
	v_mfma_f32_16x16x32_bf16 v[0:3], v[238:241], v[210:213], v[0:3]
	s_setprio 0
	s_add_i32 s33, s33, 2
	s_add_u32 s4, s4, 0x100
	s_addc_u32 s5, s5, 0
	s_cmp_gt_u32 s33, 33
	s_mov_b64 s[20:21], s[22:23]
	s_barrier
	s_cbranch_scc0 .LBB0_77
	v_lshl_add_u32 v206, s3, 8, v225
	v_lshl_or_b32 v158, s2, 8, v227
	v_lshlrev_b32_e32 v232, 11, v206
	s_andn2_b64 vcc, exec, s[14:15]
	v_or_b32_e32 v231, 16, v158
	v_add_u32_e32 v194, v232, v158
	v_or_b32_e32 v230, 0x80, v158
	v_or_b32_e32 v229, 0x90, v158
	s_cbranch_vccnz .LBB0_80
	v_lshlrev_b64 v[132:133], 2, v[158:159]
	v_lshl_add_u64 v[140:141], s[16:17], 0, v[132:133]
	global_load_dwordx4 v[128:131], v[140:141], off
	v_lshl_add_u64 v[142:143], s[18:19], 0, v[132:133]
	v_readlane_b32 s2, v253, 8
	v_mov_b32_e32 v195, v159
	v_lshlrev_b32_e32 v136, 1, v206
	v_mov_b32_e32 v137, v159
	v_readlane_b32 s3, v253, 9
	v_lshlrev_b64 v[212:213], 2, v[194:195]
	v_add_u32_e32 v146, v232, v231
	v_lshl_add_u64 v[144:145], v[136:137], 2, s[2:3]
	v_lshl_add_u64 v[136:137], s[88:89], 0, v[212:213]
	v_mov_b32_e32 v147, v159
	v_lshl_add_u64 v[146:147], v[146:147], 2, s[88:89]
	v_or_b32_e32 v195, 16, v206
	v_mov_b32_e32 v201, v159
	v_mov_b32_e32 v209, v159
	v_lshl_add_u64 v[212:213], s[90:91], 0, v[212:213]
	s_waitcnt vmcnt(0)
	v_pk_mul_f32 v[152:153], v[130:131], s[78:79] op_sel_hi:[1,0]
	v_pk_mul_f32 v[154:155], v[128:129], s[78:79] op_sel_hi:[1,0]
	global_load_dwordx4 v[132:135], v[142:143], off
	global_load_dwordx4 v[128:131], v[140:141], off offset:64
	global_load_dwordx2 v[204:205], v[144:145], off
	global_load_dwordx4 v[196:199], v[146:147], off
	v_lshlrev_b32_e32 v146, 1, v195
	global_load_dwordx4 v[136:139], v[136:137], off
	v_lshlrev_b32_e32 v195, 11, v195
	v_mov_b32_e32 v147, v159
	v_add_u32_e32 v200, v195, v158
	v_lshl_add_u64 v[146:147], v[146:147], 2, s[2:3]
	v_lshl_add_u64 v[200:201], v[200:201], 2, s[88:89]
	global_load_dwordx2 v[214:215], v[146:147], off
	v_add_u32_e32 v208, v195, v231
	global_load_dwordx4 v[200:203], v[200:201], off
	v_lshl_add_u64 v[208:209], v[208:209], 2, s[88:89]
	global_load_dwordx4 v[208:211], v[208:209], off
	s_waitcnt vmcnt(0)
	v_pk_mul_f32 v[148:149], v[130:131], s[78:79] op_sel_hi:[1,0]
	v_pk_mul_f32 v[150:151], v[128:129], s[78:79] op_sel_hi:[1,0]
	global_load_dwordx4 v[128:131], v[142:143], off offset:64
	v_sub_f32_e32 v137, v137, v204
	v_sub_f32_e32 v136, v136, v204
	v_sub_f32_e32 v139, v139, v204
	v_sub_f32_e32 v138, v138, v204
	v_pk_mul_f32 v[138:139], v[204:205], v[138:139] op_sel:[1,0]
	v_pk_mul_f32 v[136:137], v[204:205], v[136:137] op_sel:[1,0]
	v_pk_fma_f32 v[138:139], v[152:153], v[138:139], v[126:127]
	v_pk_fma_f32 v[136:137], v[154:155], v[136:137], v[124:125]
	v_pk_fma_f32 v[138:139], v[134:135], s[78:79], v[138:139] op_sel_hi:[1,0,1]
	v_pk_fma_f32 v[136:137], v[132:133], s[78:79], v[136:137] op_sel_hi:[1,0,1]
	global_store_dwordx4 v[212:213], v[136:139], off
	s_nop 1
	v_sub_f32_e32 v137, v197, v204
	v_sub_f32_e32 v136, v196, v204
	v_sub_f32_e32 v139, v199, v204
	v_sub_f32_e32 v138, v198, v204
	v_pk_mul_f32 v[138:139], v[204:205], v[138:139] op_sel:[1,0]
	v_pk_mul_f32 v[136:137], v[204:205], v[136:137] op_sel:[1,0]
	v_pk_fma_f32 v[138:139], v[148:149], v[138:139], v[122:123]
	v_pk_fma_f32 v[136:137], v[150:151], v[136:137], v[120:121]
	v_or_b32_e32 v196, 16, v194
	v_mov_b32_e32 v197, v159
	v_lshl_add_u64 v[196:197], v[196:197], 2, s[90:91]
	s_waitcnt vmcnt(0)
;     template <bool LN, int BJ, int LO, int HI> DI void batch(const f32x4 (&acc)[2][2][4][2], unsigned row0, unsigned col0, const f32x4 (&gv)[2], const f32x4 (&bv)[2]) const {
;         f32x4 r[HI - LO]; float mean[(HI - LO) / 2], rstd[(HI - LO) / 2];
; #pragma unroll
;         for (int i = LO; i < HI; ++i) { const int ai = i >> 3, m = (i >> 1) & 3, n = i & 1; const unsigned row = row0 + ai * HALF + m * 16;
;             if (n == 0) { mean[(i - LO) >> 1] = 0.f; rstd[(i - LO) >> 1] = 1.f;
;                 if (LN) { const float2 st = *(const float2*)(stats + row * 2u); mean[(i - LO) >> 1] = st.x; rstd[(i - LO) >> 1] = st.y; } }
;             r[i - LO] = *(const f32x4*)(src + (row * (unsigned)DM + col0 + BJ * HALF + n * 16)); }
; #pragma unroll
;         for (int i = LO; i < HI; ++i) { const int ai = i >> 3, m = (i >> 1) & 3, n = i & 1; const unsigned row = row0 + ai * HALF + m * 16;
;             *(f32x4*)(Y + (row * (unsigned)DM + col0 + BJ * HALF + n * 16)) = acc[ai][BJ][m][n] + ((r[i - LO] - mean[(i - LO) >> 1]) * rstd[(i - LO) >> 1]) * gv[n] + bv[n]; }
;         __builtin_amdgcn_sched_barrier(0);
;     }
;     template <bool LN, int BJ> DI void load_gb(unsigned col0, f32x4 (&gv)[2], f32x4 (&bv)[2]) const {
; #pragma unroll
;         for (int n = 0; n < 2; ++n) {
;             if (LN) { gv[n] = *(const f32x4*)(gam + col0 + BJ * HALF + n * 16) * ALPHA; bv[n] = *(const f32x4*)(bet + col0 + BJ * HALF + n * 16) * ALPHA; }
;             else { gv[n] = (f32x4){ALPHA, ALPHA, ALPHA, ALPHA}; bv[n] = (f32x4){0.f, 0.f, 0.f, 0.f}; }
;         }
;     }
;     template <bool LN> DI void run(const f32x4 (&acc)[2][2][4][2], const Unit& u, int wr, int wc, int fr, int fq) const {
;         const unsigned row0 = u.pm * BM + wr * 64 + fr, col0 = u.pn * BM + wc * 32 + 4 * fq;
;         f32x4 gv[2], bv[2];
;         load_gb<LN, 0>(col0, gv, bv);
;         batch<LN, 0, 0, 4>(acc, row0, col0, gv, bv);
;         batch<LN, 0, 4, 8>(acc, row0, col0, gv, bv);
;         batch<LN, 0, 8, 12>(acc, row0, col0, gv, bv);
;         batch<LN, 0, 12, 16>(acc, row0, col0, gv, bv);
;         load_gb<LN, 1>(col0, gv, bv);
;         batch<LN, 1, 0, 8>(acc, row0, col0, gv, bv);
;         batch<LN, 1, 8, 16>(acc, row0, col0, gv, bv);
	v_pk_fma_f32 v[138:139], v[130:131], s[78:79], v[138:139] op_sel_hi:[1,0,1]
	v_pk_fma_f32 v[136:137], v[128:129], s[78:79], v[136:137] op_sel_hi:[1,0,1]
	global_store_dwordx4 v[196:197], v[136:139], off
	v_add_u32_e32 v196, 0x8000, v194
	v_mov_b32_e32 v197, v159
	v_sub_f32_e32 v137, v201, v214
	v_sub_f32_e32 v136, v200, v214
	v_sub_f32_e32 v139, v203, v214
	v_sub_f32_e32 v138, v202, v214
	v_pk_mul_f32 v[138:139], v[214:215], v[138:139] op_sel:[1,0]
	v_pk_mul_f32 v[136:137], v[214:215], v[136:137] op_sel:[1,0]
	v_pk_fma_f32 v[138:139], v[152:153], v[138:139], v[118:119]
	v_pk_fma_f32 v[136:137], v[154:155], v[136:137], v[116:117]
	v_pk_fma_f32 v[138:139], v[134:135], s[78:79], v[138:139] op_sel_hi:[1,0,1]
	v_pk_fma_f32 v[136:137], v[132:133], s[78:79], v[136:137] op_sel_hi:[1,0,1]
	v_lshl_add_u64 v[196:197], v[196:197], 2, s[90:91]
	global_store_dwordx4 v[196:197], v[136:139], off
	v_add_u32_e32 v196, 0x8010, v194
	v_mov_b32_e32 v197, v159
	v_sub_f32_e32 v137, v209, v214
	v_sub_f32_e32 v136, v208, v214
	v_sub_f32_e32 v139, v211, v214
	v_sub_f32_e32 v138, v210, v214
	v_pk_mul_f32 v[138:139], v[214:215], v[138:139] op_sel:[1,0]
	v_pk_mul_f32 v[136:137], v[214:215], v[136:137] op_sel:[1,0]
	v_pk_fma_f32 v[138:139], v[148:149], v[138:139], v[114:115]
	v_pk_fma_f32 v[136:137], v[150:151], v[136:137], v[112:113]
	v_pk_fma_f32 v[138:139], v[130:131], s[78:79], v[138:139] op_sel_hi:[1,0,1]
	v_pk_fma_f32 v[136:137], v[128:129], s[78:79], v[136:137] op_sel_hi:[1,0,1]
	v_lshl_add_u64 v[196:197], v[196:197], 2, s[90:91]
	global_store_dwordx4 v[196:197], v[136:139], off
	s_nop 1
	v_or_b32_e32 v138, 32, v206
	v_lshlrev_b32_e32 v136, 1, v138
	v_mov_b32_e32 v137, v159
	v_lshlrev_b32_e32 v236, 11, v138
	v_lshl_add_u64 v[200:201], v[136:137], 2, s[2:3]
	v_add_u32_e32 v136, v236, v158
	v_lshl_add_u64 v[136:137], v[136:137], 2, s[88:89]
	global_load_dwordx2 v[204:205], v[200:201], off
	v_add_u32_e32 v196, v236, v231
	global_load_dwordx4 v[136:139], v[136:137], off
	v_mov_b32_e32 v197, v159
	v_lshl_add_u64 v[196:197], v[196:197], 2, s[88:89]
	global_load_dwordx4 v[196:199], v[196:197], off
	v_or_b32_e32 v207, 48, v206
	v_lshlrev_b32_e32 v235, 11, v207
	v_lshlrev_b32_e32 v202, 1, v207
	v_mov_b32_e32 v203, v159
	v_add_u32_e32 v208, v235, v158
	v_mov_b32_e32 v209, v159
	v_lshl_add_u64 v[202:203], v[202:203], 2, s[2:3]
	v_lshl_add_u64 v[208:209], v[208:209], 2, s[88:89]
	global_load_dwordx2 v[216:217], v[202:203], off
	v_add_u32_e32 v212, v235, v231
	global_load_dwordx4 v[208:211], v[208:209], off
	v_mov_b32_e32 v213, v159
	v_lshl_add_u64 v[212:213], v[212:213], 2, s[88:89]
	global_load_dwordx4 v[212:215], v[212:213], off
	v_add_u32_e32 v218, 0x10000, v194
	v_mov_b32_e32 v219, v159
	v_lshl_add_u64 v[218:219], v[218:219], 2, s[90:91]
	s_waitcnt vmcnt(0)
	v_sub_f32_e32 v137, v137, v204
	v_sub_f32_e32 v136, v136, v204
	v_sub_f32_e32 v139, v139, v204
	v_sub_f32_e32 v138, v138, v204
	v_pk_mul_f32 v[138:139], v[204:205], v[138:139] op_sel:[1,0]
	v_pk_mul_f32 v[136:137], v[204:205], v[136:137] op_sel:[1,0]
	v_pk_fma_f32 v[138:139], v[152:153], v[138:139], v[110:111]
	v_pk_fma_f32 v[136:137], v[154:155], v[136:137], v[108:109]
	v_pk_fma_f32 v[138:139], v[134:135], s[78:79], v[138:139] op_sel_hi:[1,0,1]
	v_pk_fma_f32 v[136:137], v[132:133], s[78:79], v[136:137] op_sel_hi:[1,0,1]
	global_store_dwordx4 v[218:219], v[136:139], off
	s_nop 1
	v_sub_f32_e32 v137, v197, v204
	v_sub_f32_e32 v136, v196, v204
	v_sub_f32_e32 v139, v199, v204
	v_sub_f32_e32 v138, v198, v204
	v_pk_mul_f32 v[138:139], v[204:205], v[138:139] op_sel:[1,0]
	v_pk_mul_f32 v[136:137], v[204:205], v[136:137] op_sel:[1,0]
	v_pk_fma_f32 v[138:139], v[148:149], v[138:139], v[106:107]
	v_pk_fma_f32 v[136:137], v[150:151], v[136:137], v[104:105]
	v_add_u32_e32 v196, 0x10010, v194
	v_mov_b32_e32 v197, v159
	v_pk_fma_f32 v[138:139], v[130:131], s[78:79], v[138:139] op_sel_hi:[1,0,1]
	v_pk_fma_f32 v[136:137], v[128:129], s[78:79], v[136:137] op_sel_hi:[1,0,1]
	v_lshl_add_u64 v[196:197], v[196:197], 2, s[90:91]
	global_store_dwordx4 v[196:197], v[136:139], off
	v_add_u32_e32 v196, 0x18000, v194
	v_mov_b32_e32 v197, v159
	v_sub_f32_e32 v137, v209, v216
	v_sub_f32_e32 v136, v208, v216
	v_sub_f32_e32 v139, v211, v216
	v_sub_f32_e32 v138, v210, v216
	v_pk_mul_f32 v[138:139], v[216:217], v[138:139] op_sel:[1,0]
	v_pk_mul_f32 v[136:137], v[216:217], v[136:137] op_sel:[1,0]
	v_pk_fma_f32 v[138:139], v[152:153], v[138:139], v[102:103]
	v_pk_fma_f32 v[136:137], v[154:155], v[136:137], v[100:101]
	v_pk_fma_f32 v[138:139], v[134:135], s[78:79], v[138:139] op_sel_hi:[1,0,1]
	v_pk_fma_f32 v[136:137], v[132:133], s[78:79], v[136:137] op_sel_hi:[1,0,1]
	v_lshl_add_u64 v[196:197], v[196:197], 2, s[90:91]
	global_store_dwordx4 v[196:197], v[136:139], off
	v_add_u32_e32 v196, 0x18010, v194
	v_mov_b32_e32 v197, v159
	v_sub_f32_e32 v137, v213, v216
	v_sub_f32_e32 v136, v212, v216
	v_sub_f32_e32 v139, v215, v216
	v_sub_f32_e32 v138, v214, v216
	v_pk_mul_f32 v[138:139], v[216:217], v[138:139] op_sel:[1,0]
	v_pk_mul_f32 v[136:137], v[216:217], v[136:137] op_sel:[1,0]
	v_pk_fma_f32 v[138:139], v[148:149], v[138:139], v[98:99]
	v_pk_fma_f32 v[136:137], v[150:151], v[136:137], v[96:97]
	v_pk_fma_f32 v[138:139], v[130:131], s[78:79], v[138:139] op_sel_hi:[1,0,1]
	v_pk_fma_f32 v[136:137], v[128:129], s[78:79], v[136:137] op_sel_hi:[1,0,1]
	v_lshl_add_u64 v[196:197], v[196:197], 2, s[90:91]
	global_store_dwordx4 v[196:197], v[136:139], off
	s_nop 1
	v_add_u32_e32 v138, 0x80, v206
	v_lshlrev_b32_e32 v136, 1, v138
	v_mov_b32_e32 v137, v159
	v_lshlrev_b32_e32 v233, 11, v138
	v_lshl_add_u64 v[196:197], v[136:137], 2, s[2:3]
	v_add_u32_e32 v136, v233, v158
	v_lshl_add_u64 v[136:137], v[136:137], 2, s[88:89]
	global_load_dwordx2 v[204:205], v[196:197], off
	v_add_u32_e32 v198, v233, v231
	global_load_dwordx4 v[136:139], v[136:137], off
	v_mov_b32_e32 v199, v159
	v_add_u32_e32 v207, 0x90, v206
	v_lshl_add_u64 v[198:199], v[198:199], 2, s[88:89]
	v_lshlrev_b32_e32 v234, 11, v207
	global_load_dwordx4 v[208:211], v[198:199], off
	v_add_u32_e32 v212, v234, v158
	v_mov_b32_e32 v213, v159
	v_lshl_add_u64 v[212:213], v[212:213], 2, s[88:89]
	global_load_dwordx4 v[212:215], v[212:213], off
	v_lshlrev_b32_e32 v198, 1, v207
	v_mov_b32_e32 v199, v159
	v_lshl_add_u64 v[198:199], v[198:199], 2, s[2:3]
	global_load_dwordx2 v[220:221], v[198:199], off
	v_add_u32_e32 v216, v234, v231
	v_mov_b32_e32 v217, v159
	v_lshl_add_u64 v[216:217], v[216:217], 2, s[88:89]
	global_load_dwordx4 v[216:219], v[216:217], off
	v_add_u32_e32 v238, 0x40000, v194
	v_mov_b32_e32 v239, v159
	v_lshl_add_u64 v[238:239], v[238:239], 2, s[90:91]
	s_waitcnt vmcnt(0)
;     template <bool LN, int BJ, int LO, int HI> DI void batch(const f32x4 (&acc)[2][2][4][2], unsigned row0, unsigned col0, const f32x4 (&gv)[2], const f32x4 (&bv)[2]) const {
;         f32x4 r[HI - LO]; float mean[(HI - LO) / 2], rstd[(HI - LO) / 2];
; #pragma unroll
;         for (int i = LO; i < HI; ++i) { const int ai = i >> 3, m = (i >> 1) & 3, n = i & 1; const unsigned row = row0 + ai * HALF + m * 16;
;             if (n == 0) { mean[(i - LO) >> 1] = 0.f; rstd[(i - LO) >> 1] = 1.f;
;                 if (LN) { const float2 st = *(const float2*)(stats + row * 2u); mean[(i - LO) >> 1] = st.x; rstd[(i - LO) >> 1] = st.y; } }
;             r[i - LO] = *(const f32x4*)(src + (row * (unsigned)DM + col0 + BJ * HALF + n * 16)); }
; #pragma unroll
;         for (int i = LO; i < HI; ++i) { const int ai = i >> 3, m = (i >> 1) & 3, n = i & 1; const unsigned row = row0 + ai * HALF + m * 16;
;             *(f32x4*)(Y + (row * (unsigned)DM + col0 + BJ * HALF + n * 16)) = acc[ai][BJ][m][n] + ((r[i - LO] - mean[(i - LO) >> 1]) * rstd[(i - LO) >> 1]) * gv[n] + bv[n]; }
;         __builtin_amdgcn_sched_barrier(0);
;     }
;     template <bool LN, int BJ> DI void load_gb(unsigned col0, f32x4 (&gv)[2], f32x4 (&bv)[2]) const {
; #pragma unroll
;         for (int n = 0; n < 2; ++n) {
;             if (LN) { gv[n] = *(const f32x4*)(gam + col0 + BJ * HALF + n * 16) * ALPHA; bv[n] = *(const f32x4*)(bet + col0 + BJ * HALF + n * 16) * ALPHA; }
;             else { gv[n] = (f32x4){ALPHA, ALPHA, ALPHA, ALPHA}; bv[n] = (f32x4){0.f, 0.f, 0.f, 0.f}; }
;         }
;     }
;     template <bool LN> DI void run(const f32x4 (&acc)[2][2][4][2], const Unit& u, int wr, int wc, int fr, int fq) const {
;         const unsigned row0 = u.pm * BM + wr * 64 + fr, col0 = u.pn * BM + wc * 32 + 4 * fq;
;         f32x4 gv[2], bv[2];
;         load_gb<LN, 0>(col0, gv, bv);
;         batch<LN, 0, 0, 4>(acc, row0, col0, gv, bv);
;         batch<LN, 0, 4, 8>(acc, row0, col0, gv, bv);
;         batch<LN, 0, 8, 12>(acc, row0, col0, gv, bv);
;         batch<LN, 0, 12, 16>(acc, row0, col0, gv, bv);
;         load_gb<LN, 1>(col0, gv, bv);
;         batch<LN, 1, 0, 8>(acc, row0, col0, gv, bv);
;         batch<LN, 1, 8, 16>(acc, row0, col0, gv, bv);
	v_sub_f32_e32 v137, v137, v204
	v_sub_f32_e32 v136, v136, v204
	v_sub_f32_e32 v139, v139, v204
	v_sub_f32_e32 v138, v138, v204
	v_pk_mul_f32 v[138:139], v[204:205], v[138:139] op_sel:[1,0]
	v_pk_mul_f32 v[136:137], v[204:205], v[136:137] op_sel:[1,0]
	v_pk_fma_f32 v[138:139], v[152:153], v[138:139], v[94:95]
	v_pk_fma_f32 v[136:137], v[154:155], v[136:137], v[92:93]
	v_pk_fma_f32 v[138:139], v[134:135], s[78:79], v[138:139] op_sel_hi:[1,0,1]
	v_pk_fma_f32 v[136:137], v[132:133], s[78:79], v[136:137] op_sel_hi:[1,0,1]
	global_store_dwordx4 v[238:239], v[136:139], off
	s_nop 1
	v_sub_f32_e32 v137, v209, v204
	v_sub_f32_e32 v136, v208, v204
	v_sub_f32_e32 v139, v211, v204
	v_sub_f32_e32 v138, v210, v204
	v_pk_mul_f32 v[138:139], v[204:205], v[138:139] op_sel:[1,0]
	v_pk_mul_f32 v[136:137], v[204:205], v[136:137] op_sel:[1,0]
	v_pk_fma_f32 v[138:139], v[148:149], v[138:139], v[90:91]
	v_pk_fma_f32 v[136:137], v[150:151], v[136:137], v[88:89]
	v_add_u32_e32 v204, 0x40010, v194
	v_mov_b32_e32 v205, v159
	v_pk_fma_f32 v[138:139], v[130:131], s[78:79], v[138:139] op_sel_hi:[1,0,1]
	v_pk_fma_f32 v[136:137], v[128:129], s[78:79], v[136:137] op_sel_hi:[1,0,1]
	v_lshl_add_u64 v[204:205], v[204:205], 2, s[90:91]
	global_store_dwordx4 v[204:205], v[136:139], off
	v_add_u32_e32 v204, 0x48000, v194
	v_mov_b32_e32 v205, v159
	v_sub_f32_e32 v137, v213, v220
	v_sub_f32_e32 v136, v212, v220
	v_sub_f32_e32 v139, v215, v220
	v_sub_f32_e32 v138, v214, v220
	v_pk_mul_f32 v[138:139], v[220:221], v[138:139] op_sel:[1,0]
	v_pk_mul_f32 v[136:137], v[220:221], v[136:137] op_sel:[1,0]
	v_pk_fma_f32 v[138:139], v[152:153], v[138:139], v[86:87]
	v_pk_fma_f32 v[136:137], v[154:155], v[136:137], v[84:85]
	v_pk_fma_f32 v[138:139], v[134:135], s[78:79], v[138:139] op_sel_hi:[1,0,1]
	v_pk_fma_f32 v[136:137], v[132:133], s[78:79], v[136:137] op_sel_hi:[1,0,1]
	v_lshl_add_u64 v[204:205], v[204:205], 2, s[90:91]
	global_store_dwordx4 v[204:205], v[136:139], off
	v_add_u32_e32 v204, 0x48010, v194
	v_mov_b32_e32 v205, v159
	v_sub_f32_e32 v137, v217, v220
	v_sub_f32_e32 v136, v216, v220
	v_sub_f32_e32 v139, v219, v220
	v_sub_f32_e32 v138, v218, v220
	v_pk_mul_f32 v[138:139], v[220:221], v[138:139] op_sel:[1,0]
	v_pk_mul_f32 v[136:137], v[220:221], v[136:137] op_sel:[1,0]
	v_pk_fma_f32 v[138:139], v[148:149], v[138:139], v[82:83]
	v_pk_fma_f32 v[136:137], v[150:151], v[136:137], v[80:81]
	v_pk_fma_f32 v[138:139], v[130:131], s[78:79], v[138:139] op_sel_hi:[1,0,1]
	v_pk_fma_f32 v[136:137], v[128:129], s[78:79], v[136:137] op_sel_hi:[1,0,1]
	v_lshl_add_u64 v[204:205], v[204:205], 2, s[90:91]
	global_store_dwordx4 v[204:205], v[136:139], off
	s_nop 1
	v_add_u32_e32 v138, 0xa0, v206
	v_lshlrev_b32_e32 v136, 1, v138
	v_mov_b32_e32 v137, v159
	v_lshlrev_b32_e32 v237, 11, v138
	v_lshl_add_u64 v[204:205], v[136:137], 2, s[2:3]
	v_add_u32_e32 v136, v237, v158
	v_lshl_add_u64 v[136:137], v[136:137], 2, s[88:89]
	global_load_dwordx2 v[220:221], v[204:205], off
	v_add_u32_e32 v208, v237, v231
	global_load_dwordx4 v[136:139], v[136:137], off
	v_mov_b32_e32 v209, v159
	v_lshl_add_u64 v[208:209], v[208:209], 2, s[88:89]
	global_load_dwordx4 v[212:215], v[208:209], off
	v_add_u32_e32 v208, 0xb0, v206
	v_lshlrev_b32_e32 v206, 1, v208
	v_mov_b32_e32 v207, v159
	v_lshlrev_b32_e32 v238, 11, v208
	v_lshl_add_u64 v[210:211], v[206:207], 2, s[2:3]
	v_add_u32_e32 v206, v238, v158
	v_lshl_add_u64 v[206:207], v[206:207], 2, s[88:89]
	global_load_dwordx2 v[240:241], v[210:211], off
	v_add_u32_e32 v216, v238, v231
	global_load_dwordx4 v[206:209], v[206:207], off
	v_mov_b32_e32 v217, v159
	v_lshl_add_u64 v[216:217], v[216:217], 2, s[88:89]
	global_load_dwordx4 v[216:219], v[216:217], off
	v_add_u32_e32 v242, 0x50000, v194
	v_mov_b32_e32 v243, v159
	v_lshl_add_u64 v[242:243], v[242:243], 2, s[90:91]
	s_waitcnt vmcnt(0)
	v_sub_f32_e32 v137, v137, v220
	v_sub_f32_e32 v136, v136, v220
	v_sub_f32_e32 v139, v139, v220
	v_sub_f32_e32 v138, v138, v220
	v_pk_mul_f32 v[138:139], v[220:221], v[138:139] op_sel:[1,0]
	v_pk_mul_f32 v[136:137], v[220:221], v[136:137] op_sel:[1,0]
	v_pk_fma_f32 v[138:139], v[152:153], v[138:139], v[78:79]
	v_pk_fma_f32 v[136:137], v[154:155], v[136:137], v[76:77]
	v_pk_fma_f32 v[138:139], v[134:135], s[78:79], v[138:139] op_sel_hi:[1,0,1]
	v_pk_fma_f32 v[136:137], v[132:133], s[78:79], v[136:137] op_sel_hi:[1,0,1]
	global_store_dwordx4 v[242:243], v[136:139], off
	s_nop 1
	v_sub_f32_e32 v137, v213, v220
	v_sub_f32_e32 v136, v212, v220
	v_sub_f32_e32 v139, v215, v220
	v_sub_f32_e32 v138, v214, v220
	v_pk_mul_f32 v[138:139], v[220:221], v[138:139] op_sel:[1,0]
	v_pk_mul_f32 v[136:137], v[220:221], v[136:137] op_sel:[1,0]
	v_pk_fma_f32 v[138:139], v[148:149], v[138:139], v[74:75]
	v_pk_fma_f32 v[136:137], v[150:151], v[136:137], v[72:73]
	v_add_u32_e32 v212, 0x50010, v194
	v_mov_b32_e32 v213, v159
	v_pk_fma_f32 v[138:139], v[130:131], s[78:79], v[138:139] op_sel_hi:[1,0,1]
	v_pk_fma_f32 v[136:137], v[128:129], s[78:79], v[136:137] op_sel_hi:[1,0,1]
	v_lshl_add_u64 v[212:213], v[212:213], 2, s[90:91]
	global_store_dwordx4 v[212:213], v[136:139], off
	s_nop 1
	v_sub_f32_e32 v137, v207, v240
	v_sub_f32_e32 v136, v206, v240
	v_sub_f32_e32 v139, v209, v240
	v_sub_f32_e32 v138, v208, v240
	v_pk_mul_f32 v[136:137], v[240:241], v[136:137] op_sel:[1,0]
	v_pk_mul_f32 v[138:139], v[240:241], v[138:139] op_sel:[1,0]
	v_pk_fma_f32 v[136:137], v[154:155], v[136:137], v[68:69]
	v_pk_fma_f32 v[138:139], v[152:153], v[138:139], v[70:71]
	v_pk_fma_f32 v[132:133], v[132:133], s[78:79], v[136:137] op_sel_hi:[1,0,1]
	v_add_u32_e32 v136, 0x58000, v194
	v_mov_b32_e32 v137, v159
	v_pk_fma_f32 v[134:135], v[134:135], s[78:79], v[138:139] op_sel_hi:[1,0,1]
	v_lshl_add_u64 v[136:137], v[136:137], 2, s[90:91]
	global_store_dwordx4 v[136:137], v[132:135], off
	s_nop 1
	v_sub_f32_e32 v133, v217, v240
	v_sub_f32_e32 v132, v216, v240
	v_sub_f32_e32 v135, v219, v240
	v_sub_f32_e32 v134, v218, v240
	v_pk_mul_f32 v[132:133], v[240:241], v[132:133] op_sel:[1,0]
	v_pk_mul_f32 v[134:135], v[240:241], v[134:135] op_sel:[1,0]
	v_pk_fma_f32 v[132:133], v[150:151], v[132:133], v[64:65]
	v_pk_fma_f32 v[134:135], v[148:149], v[134:135], v[66:67]
	v_pk_fma_f32 v[128:129], v[128:129], s[78:79], v[132:133] op_sel_hi:[1,0,1]
	v_add_u32_e32 v132, 0x58010, v194
	v_mov_b32_e32 v133, v159
	v_pk_fma_f32 v[130:131], v[130:131], s[78:79], v[134:135] op_sel_hi:[1,0,1]
	v_lshl_add_u64 v[132:133], v[132:133], 2, s[90:91]
	global_store_dwordx4 v[132:133], v[128:131], off
	global_load_dwordx4 v[128:131], v[140:141], off offset:512
	v_add_u32_e32 v136, v232, v230
	v_mov_b32_e32 v137, v159
	v_lshl_add_u64 v[136:137], v[136:137], 2, s[88:89]
	s_waitcnt vmcnt(0)
;     template <bool LN, int BJ> DI void load_gb(unsigned col0, f32x4 (&gv)[2], f32x4 (&bv)[2]) const {
; #pragma unroll
;         for (int n = 0; n < 2; ++n) {
;             if (LN) { gv[n] = *(const f32x4*)(gam + col0 + BJ * HALF + n * 16) * ALPHA; bv[n] = *(const f32x4*)(bet + col0 + BJ * HALF + n * 16) * ALPHA; }
;             else { gv[n] = (f32x4){ALPHA, ALPHA, ALPHA, ALPHA}; bv[n] = (f32x4){0.f, 0.f, 0.f, 0.f}; }
;         }
;     }
;     template <bool LN> DI void run(const f32x4 (&acc)[2][2][4][2], const Unit& u, int wr, int wc, int fr, int fq) const {
;         const unsigned row0 = u.pm * BM + wr * 64 + fr, col0 = u.pn * BM + wc * 32 + 4 * fq;
;         f32x4 gv[2], bv[2];
;         load_gb<LN, 0>(col0, gv, bv);
;         batch<LN, 0, 0, 4>(acc, row0, col0, gv, bv);
;         batch<LN, 0, 4, 8>(acc, row0, col0, gv, bv);
;         batch<LN, 0, 8, 12>(acc, row0, col0, gv, bv);
;         batch<LN, 0, 12, 16>(acc, row0, col0, gv, bv);
;         load_gb<LN, 1>(col0, gv, bv);
;         batch<LN, 1, 0, 8>(acc, row0, col0, gv, bv);
;         batch<LN, 1, 8, 16>(acc, row0, col0, gv, bv);
	v_pk_mul_f32 v[212:213], v[130:131], s[78:79] op_sel_hi:[1,0]
	v_pk_mul_f32 v[214:215], v[128:129], s[78:79] op_sel_hi:[1,0]
	global_load_dwordx4 v[132:135], v[142:143], off offset:512
	global_load_dwordx4 v[128:131], v[140:141], off offset:576
	s_waitcnt vmcnt(0)
	v_pk_mul_f32 v[206:207], v[130:131], s[78:79] op_sel_hi:[1,0]
	v_pk_mul_f32 v[208:209], v[128:129], s[78:79] op_sel_hi:[1,0]
	global_load_dwordx4 v[128:131], v[142:143], off offset:576
	global_load_dwordx2 v[220:221], v[144:145], off
	global_load_dwordx4 v[240:243], v[136:137], off
	v_add_u32_e32 v136, v232, v229
	v_mov_b32_e32 v137, v159
	v_lshl_add_u64 v[136:137], v[136:137], 2, s[88:89]
	global_load_dwordx4 v[244:247], v[136:137], off
	global_load_dwordx2 v[218:219], v[146:147], off
	v_add_u32_e32 v136, v195, v230
	v_mov_b32_e32 v137, v159
	v_lshl_add_u64 v[136:137], v[136:137], 2, s[88:89]
	global_load_dwordx4 v[248:251], v[136:137], off
	v_add_u32_e32 v136, v195, v229
	v_mov_b32_e32 v137, v159
	v_lshl_add_u64 v[136:137], v[136:137], 2, s[88:89]
	global_load_dwordx4 v[152:155], v[136:137], off
	global_load_dwordx2 v[216:217], v[200:201], off
	v_add_u32_e32 v136, v236, v230
	v_mov_b32_e32 v137, v159
	v_lshl_add_u64 v[136:137], v[136:137], 2, s[88:89]
	global_load_dwordx4 v[148:151], v[136:137], off
	v_add_u32_e32 v136, v236, v229
	v_mov_b32_e32 v137, v159
	v_lshl_add_u64 v[136:137], v[136:137], 2, s[88:89]
	global_load_dwordx4 v[144:147], v[136:137], off
	global_load_dwordx2 v[200:201], v[202:203], off
	v_add_u32_e32 v136, v235, v230
	v_mov_b32_e32 v137, v159
	v_lshl_add_u64 v[136:137], v[136:137], 2, s[88:89]
	global_load_dwordx4 v[140:143], v[136:137], off
	v_add_u32_e32 v136, v235, v229
	v_mov_b32_e32 v137, v159
	v_lshl_add_u64 v[136:137], v[136:137], 2, s[88:89]
	global_load_dwordx4 v[136:139], v[136:137], off
	v_add_u32_e32 v202, 0x80, v194
	v_mov_b32_e32 v203, v159
	v_lshl_add_u64 v[202:203], v[202:203], 2, s[90:91]
	s_waitcnt vmcnt(0)
	v_sub_f32_e32 v241, v241, v220
	v_sub_f32_e32 v240, v240, v220
	v_sub_f32_e32 v243, v243, v220
	v_sub_f32_e32 v242, v242, v220
	v_pk_mul_f32 v[242:243], v[220:221], v[242:243] op_sel:[1,0]
	v_pk_mul_f32 v[240:241], v[220:221], v[240:241] op_sel:[1,0]
	v_pk_fma_f32 v[242:243], v[212:213], v[242:243], v[62:63]
	v_pk_fma_f32 v[240:241], v[214:215], v[240:241], v[60:61]
	v_pk_fma_f32 v[242:243], v[134:135], s[78:79], v[242:243] op_sel_hi:[1,0,1]
	v_pk_fma_f32 v[240:241], v[132:133], s[78:79], v[240:241] op_sel_hi:[1,0,1]
	global_store_dwordx4 v[202:203], v[240:243], off
	v_sub_f32_e32 v203, v245, v220
	v_sub_f32_e32 v202, v244, v220
	v_sub_f32_e32 v241, v247, v220
	v_sub_f32_e32 v240, v246, v220
	v_pk_mul_f32 v[202:203], v[220:221], v[202:203] op_sel:[1,0]
	v_pk_mul_f32 v[240:241], v[220:221], v[240:241] op_sel:[1,0]
	v_pk_fma_f32 v[202:203], v[208:209], v[202:203], v[56:57]
	v_pk_fma_f32 v[220:221], v[206:207], v[240:241], v[58:59]
	v_pk_fma_f32 v[240:241], v[128:129], s[78:79], v[202:203] op_sel_hi:[1,0,1]
	v_add_u32_e32 v202, 0x90, v194
	v_mov_b32_e32 v203, v159
	v_pk_fma_f32 v[242:243], v[130:131], s[78:79], v[220:221] op_sel_hi:[1,0,1]
	v_lshl_add_u64 v[202:203], v[202:203], 2, s[90:91]
	global_store_dwordx4 v[202:203], v[240:243], off
	v_sub_f32_e32 v203, v249, v218
	v_sub_f32_e32 v202, v248, v218
	v_sub_f32_e32 v221, v251, v218
	v_sub_f32_e32 v220, v250, v218
	v_pk_mul_f32 v[202:203], v[218:219], v[202:203] op_sel:[1,0]
	v_pk_mul_f32 v[220:221], v[218:219], v[220:221] op_sel:[1,0]
	v_pk_fma_f32 v[202:203], v[214:215], v[202:203], v[52:53]
	v_pk_fma_f32 v[220:221], v[212:213], v[220:221], v[54:55]
	v_pk_fma_f32 v[240:241], v[132:133], s[78:79], v[202:203] op_sel_hi:[1,0,1]
	v_add_u32_e32 v202, 0x8080, v194
	v_mov_b32_e32 v203, v159
	v_sub_f32_e32 v153, v153, v218
	v_sub_f32_e32 v152, v152, v218
	v_sub_f32_e32 v155, v155, v218
	v_sub_f32_e32 v154, v154, v218
	v_pk_fma_f32 v[242:243], v[134:135], s[78:79], v[220:221] op_sel_hi:[1,0,1]
	v_lshl_add_u64 v[202:203], v[202:203], 2, s[90:91]
	v_pk_mul_f32 v[154:155], v[218:219], v[154:155] op_sel:[1,0]
	v_pk_mul_f32 v[152:153], v[218:219], v[152:153] op_sel:[1,0]
	global_store_dwordx4 v[202:203], v[240:243], off
	v_pk_fma_f32 v[152:153], v[208:209], v[152:153], v[48:49]
	v_pk_fma_f32 v[154:155], v[206:207], v[154:155], v[50:51]
	v_add_u32_e32 v202, 0x8090, v194
	v_mov_b32_e32 v203, v159
	v_sub_f32_e32 v149, v149, v216
	v_sub_f32_e32 v148, v148, v216
	v_sub_f32_e32 v151, v151, v216
	v_sub_f32_e32 v150, v150, v216
	v_pk_fma_f32 v[154:155], v[130:131], s[78:79], v[154:155] op_sel_hi:[1,0,1]
	v_pk_fma_f32 v[152:153], v[128:129], s[78:79], v[152:153] op_sel_hi:[1,0,1]
	v_lshl_add_u64 v[202:203], v[202:203], 2, s[90:91]
	v_pk_mul_f32 v[150:151], v[216:217], v[150:151] op_sel:[1,0]
	v_pk_mul_f32 v[148:149], v[216:217], v[148:149] op_sel:[1,0]
	global_store_dwordx4 v[202:203], v[152:155], off
	v_pk_fma_f32 v[148:149], v[214:215], v[148:149], v[44:45]
	v_pk_fma_f32 v[150:151], v[212:213], v[150:151], v[46:47]
	v_add_u32_e32 v152, 0x10080, v194
	v_mov_b32_e32 v153, v159
	v_sub_f32_e32 v145, v145, v216
	v_sub_f32_e32 v144, v144, v216
	v_sub_f32_e32 v147, v147, v216
	v_sub_f32_e32 v146, v146, v216
	v_pk_fma_f32 v[150:151], v[134:135], s[78:79], v[150:151] op_sel_hi:[1,0,1]
	v_pk_fma_f32 v[148:149], v[132:133], s[78:79], v[148:149] op_sel_hi:[1,0,1]
	v_lshl_add_u64 v[152:153], v[152:153], 2, s[90:91]
	v_pk_mul_f32 v[146:147], v[216:217], v[146:147] op_sel:[1,0]
	v_pk_mul_f32 v[144:145], v[216:217], v[144:145] op_sel:[1,0]
	global_store_dwordx4 v[152:153], v[148:151], off
	v_pk_fma_f32 v[144:145], v[208:209], v[144:145], v[40:41]
	v_pk_fma_f32 v[146:147], v[206:207], v[146:147], v[42:43]
;     template <bool LN, int BJ, int LO, int HI> DI void batch(const f32x4 (&acc)[2][2][4][2], unsigned row0, unsigned col0, const f32x4 (&gv)[2], const f32x4 (&bv)[2]) const {
;         f32x4 r[HI - LO]; float mean[(HI - LO) / 2], rstd[(HI - LO) / 2];
; #pragma unroll
;         for (int i = LO; i < HI; ++i) { const int ai = i >> 3, m = (i >> 1) & 3, n = i & 1; const unsigned row = row0 + ai * HALF + m * 16;
;             if (n == 0) { mean[(i - LO) >> 1] = 0.f; rstd[(i - LO) >> 1] = 1.f;
;                 if (LN) { const float2 st = *(const float2*)(stats + row * 2u); mean[(i - LO) >> 1] = st.x; rstd[(i - LO) >> 1] = st.y; } }
;             r[i - LO] = *(const f32x4*)(src + (row * (unsigned)DM + col0 + BJ * HALF + n * 16)); }
; #pragma unroll
;         for (int i = LO; i < HI; ++i) { const int ai = i >> 3, m = (i >> 1) & 3, n = i & 1; const unsigned row = row0 + ai * HALF + m * 16;
;             *(f32x4*)(Y + (row * (unsigned)DM + col0 + BJ * HALF + n * 16)) = acc[ai][BJ][m][n] + ((r[i - LO] - mean[(i - LO) >> 1]) * rstd[(i - LO) >> 1]) * gv[n] + bv[n]; }
;         __builtin_amdgcn_sched_barrier(0);
;     }
;     template <bool LN, int BJ> DI void load_gb(unsigned col0, f32x4 (&gv)[2], f32x4 (&bv)[2]) const {
; #pragma unroll
;         for (int n = 0; n < 2; ++n) {
;             if (LN) { gv[n] = *(const f32x4*)(gam + col0 + BJ * HALF + n * 16) * ALPHA; bv[n] = *(const f32x4*)(bet + col0 + BJ * HALF + n * 16) * ALPHA; }
;             else { gv[n] = (f32x4){ALPHA, ALPHA, ALPHA, ALPHA}; bv[n] = (f32x4){0.f, 0.f, 0.f, 0.f}; }
;         }
;     }
;     template <bool LN> DI void run(const f32x4 (&acc)[2][2][4][2], const Unit& u, int wr, int wc, int fr, int fq) const {
;         const unsigned row0 = u.pm * BM + wr * 64 + fr, col0 = u.pn * BM + wc * 32 + 4 * fq;
;         f32x4 gv[2], bv[2];
;         load_gb<LN, 0>(col0, gv, bv);
;         batch<LN, 0, 0, 4>(acc, row0, col0, gv, bv);
;         batch<LN, 0, 4, 8>(acc, row0, col0, gv, bv);
;         batch<LN, 0, 8, 12>(acc, row0, col0, gv, bv);
;         batch<LN, 0, 12, 16>(acc, row0, col0, gv, bv);
;         load_gb<LN, 1>(col0, gv, bv);
;         batch<LN, 1, 0, 8>(acc, row0, col0, gv, bv);
;         batch<LN, 1, 8, 16>(acc, row0, col0, gv, bv);
	v_add_u32_e32 v148, 0x10090, v194
	v_mov_b32_e32 v149, v159
	v_sub_f32_e32 v141, v141, v200
	v_sub_f32_e32 v140, v140, v200
	v_sub_f32_e32 v143, v143, v200
	v_sub_f32_e32 v142, v142, v200
	v_pk_fma_f32 v[146:147], v[130:131], s[78:79], v[146:147] op_sel_hi:[1,0,1]
	v_pk_fma_f32 v[144:145], v[128:129], s[78:79], v[144:145] op_sel_hi:[1,0,1]
	v_lshl_add_u64 v[148:149], v[148:149], 2, s[90:91]
	v_pk_mul_f32 v[142:143], v[200:201], v[142:143] op_sel:[1,0]
	v_pk_mul_f32 v[140:141], v[200:201], v[140:141] op_sel:[1,0]
	global_store_dwordx4 v[148:149], v[144:147], off
	v_pk_fma_f32 v[140:141], v[214:215], v[140:141], v[36:37]
	v_pk_fma_f32 v[142:143], v[212:213], v[142:143], v[38:39]
	v_add_u32_e32 v144, 0x18080, v194
	v_mov_b32_e32 v145, v159
	v_sub_f32_e32 v137, v137, v200
	v_sub_f32_e32 v136, v136, v200
	v_sub_f32_e32 v139, v139, v200
	v_sub_f32_e32 v138, v138, v200
	v_pk_fma_f32 v[142:143], v[134:135], s[78:79], v[142:143] op_sel_hi:[1,0,1]
	v_pk_fma_f32 v[140:141], v[132:133], s[78:79], v[140:141] op_sel_hi:[1,0,1]
	v_lshl_add_u64 v[144:145], v[144:145], 2, s[90:91]
	v_pk_mul_f32 v[138:139], v[200:201], v[138:139] op_sel:[1,0]
	v_pk_mul_f32 v[136:137], v[200:201], v[136:137] op_sel:[1,0]
	global_store_dwordx4 v[144:145], v[140:143], off
	v_pk_fma_f32 v[136:137], v[208:209], v[136:137], v[32:33]
	v_pk_fma_f32 v[138:139], v[206:207], v[138:139], v[34:35]
	v_add_u32_e32 v140, 0x18090, v194
	v_mov_b32_e32 v141, v159
	v_pk_fma_f32 v[138:139], v[130:131], s[78:79], v[138:139] op_sel_hi:[1,0,1]
	v_pk_fma_f32 v[136:137], v[128:129], s[78:79], v[136:137] op_sel_hi:[1,0,1]
	v_lshl_add_u64 v[140:141], v[140:141], 2, s[90:91]
	global_store_dwordx4 v[140:141], v[136:139], off
	s_nop 1
	v_add_u32_e32 v136, v233, v230
	v_mov_b32_e32 v137, v159
	v_lshl_add_u64 v[136:137], v[136:137], 2, s[88:89]
	global_load_dwordx2 v[220:221], v[196:197], off
	global_load_dwordx4 v[216:219], v[136:137], off
	v_add_u32_e32 v136, v233, v229
	v_mov_b32_e32 v137, v159
	v_lshl_add_u64 v[136:137], v[136:137], 2, s[88:89]
	global_load_dwordx4 v[240:243], v[136:137], off
	global_load_dwordx2 v[200:201], v[198:199], off
	v_add_u32_e32 v136, v234, v230
	v_mov_b32_e32 v137, v159
	v_lshl_add_u64 v[136:137], v[136:137], 2, s[88:89]
	global_load_dwordx4 v[244:247], v[136:137], off
	v_add_u32_e32 v136, v234, v229
	v_mov_b32_e32 v137, v159
	v_lshl_add_u64 v[136:137], v[136:137], 2, s[88:89]
	global_load_dwordx4 v[152:155], v[136:137], off
	global_load_dwordx2 v[198:199], v[204:205], off
	v_add_u32_e32 v136, v237, v230
	v_mov_b32_e32 v137, v159
	v_lshl_add_u64 v[136:137], v[136:137], 2, s[88:89]
	global_load_dwordx4 v[148:151], v[136:137], off
	v_add_u32_e32 v136, v237, v229
	v_mov_b32_e32 v137, v159
	v_lshl_add_u64 v[136:137], v[136:137], 2, s[88:89]
	global_load_dwordx4 v[144:147], v[136:137], off
	global_load_dwordx2 v[196:197], v[210:211], off
	v_add_u32_e32 v136, v238, v230
	v_mov_b32_e32 v137, v159
	v_lshl_add_u64 v[136:137], v[136:137], 2, s[88:89]
	global_load_dwordx4 v[140:143], v[136:137], off
	v_add_u32_e32 v136, v238, v229
	v_mov_b32_e32 v137, v159
	v_lshl_add_u64 v[136:137], v[136:137], 2, s[88:89]
	global_load_dwordx4 v[136:139], v[136:137], off
	v_add_u32_e32 v210, 0x40080, v194
	v_mov_b32_e32 v211, v159
	v_lshl_add_u64 v[210:211], v[210:211], 2, s[90:91]
	s_waitcnt vmcnt(0)
;     template <bool LN, int BJ, int LO, int HI> DI void batch(const f32x4 (&acc)[2][2][4][2], unsigned row0, unsigned col0, const f32x4 (&gv)[2], const f32x4 (&bv)[2]) const {
;         f32x4 r[HI - LO]; float mean[(HI - LO) / 2], rstd[(HI - LO) / 2];
; #pragma unroll
;         for (int i = LO; i < HI; ++i) { const int ai = i >> 3, m = (i >> 1) & 3, n = i & 1; const unsigned row = row0 + ai * HALF + m * 16;
;             if (n == 0) { mean[(i - LO) >> 1] = 0.f; rstd[(i - LO) >> 1] = 1.f;
;                 if (LN) { const float2 st = *(const float2*)(stats + row * 2u); mean[(i - LO) >> 1] = st.x; rstd[(i - LO) >> 1] = st.y; } }
;             r[i - LO] = *(const f32x4*)(src + (row * (unsigned)DM + col0 + BJ * HALF + n * 16)); }
; #pragma unroll
;         for (int i = LO; i < HI; ++i) { const int ai = i >> 3, m = (i >> 1) & 3, n = i & 1; const unsigned row = row0 + ai * HALF + m * 16;
;             *(f32x4*)(Y + (row * (unsigned)DM + col0 + BJ * HALF + n * 16)) = acc[ai][BJ][m][n] + ((r[i - LO] - mean[(i - LO) >> 1]) * rstd[(i - LO) >> 1]) * gv[n] + bv[n]; }
;         __builtin_amdgcn_sched_barrier(0);
;     }
;     template <bool LN, int BJ> DI void load_gb(unsigned col0, f32x4 (&gv)[2], f32x4 (&bv)[2]) const {
; #pragma unroll
;         for (int n = 0; n < 2; ++n) {
;             if (LN) { gv[n] = *(const f32x4*)(gam + col0 + BJ * HALF + n * 16) * ALPHA; bv[n] = *(const f32x4*)(bet + col0 + BJ * HALF + n * 16) * ALPHA; }
;             else { gv[n] = (f32x4){ALPHA, ALPHA, ALPHA, ALPHA}; bv[n] = (f32x4){0.f, 0.f, 0.f, 0.f}; }
;         }
;     }
;     template <bool LN> DI void run(const f32x4 (&acc)[2][2][4][2], const Unit& u, int wr, int wc, int fr, int fq) const {
;         const unsigned row0 = u.pm * BM + wr * 64 + fr, col0 = u.pn * BM + wc * 32 + 4 * fq;
;         f32x4 gv[2], bv[2];
;         load_gb<LN, 0>(col0, gv, bv);
;         batch<LN, 0, 0, 4>(acc, row0, col0, gv, bv);
;         batch<LN, 0, 4, 8>(acc, row0, col0, gv, bv);
;         batch<LN, 0, 8, 12>(acc, row0, col0, gv, bv);
;         batch<LN, 0, 12, 16>(acc, row0, col0, gv, bv);
;         load_gb<LN, 1>(col0, gv, bv);
;         batch<LN, 1, 0, 8>(acc, row0, col0, gv, bv);
;         batch<LN, 1, 8, 16>(acc, row0, col0, gv, bv);
	v_sub_f32_e32 v203, v217, v220
	v_sub_f32_e32 v202, v216, v220
	v_sub_f32_e32 v205, v219, v220
	v_sub_f32_e32 v204, v218, v220
	v_pk_mul_f32 v[204:205], v[220:221], v[204:205] op_sel:[1,0]
	v_pk_mul_f32 v[202:203], v[220:221], v[202:203] op_sel:[1,0]
	v_pk_fma_f32 v[204:205], v[212:213], v[204:205], v[30:31]
	v_pk_fma_f32 v[202:203], v[214:215], v[202:203], v[28:29]
	v_pk_fma_f32 v[204:205], v[134:135], s[78:79], v[204:205] op_sel_hi:[1,0,1]
	v_pk_fma_f32 v[202:203], v[132:133], s[78:79], v[202:203] op_sel_hi:[1,0,1]
	global_store_dwordx4 v[210:211], v[202:205], off
	v_add_u32_e32 v210, 0x40090, v194
	v_mov_b32_e32 v211, v159
	v_sub_f32_e32 v203, v241, v220
	v_sub_f32_e32 v202, v240, v220
	v_sub_f32_e32 v205, v243, v220
	v_sub_f32_e32 v204, v242, v220
	v_pk_mul_f32 v[204:205], v[220:221], v[204:205] op_sel:[1,0]
	v_pk_mul_f32 v[202:203], v[220:221], v[202:203] op_sel:[1,0]
	v_pk_fma_f32 v[204:205], v[206:207], v[204:205], v[26:27]
	v_pk_fma_f32 v[202:203], v[208:209], v[202:203], v[24:25]
	v_pk_fma_f32 v[204:205], v[130:131], s[78:79], v[204:205] op_sel_hi:[1,0,1]
	v_pk_fma_f32 v[202:203], v[128:129], s[78:79], v[202:203] op_sel_hi:[1,0,1]
	v_lshl_add_u64 v[210:211], v[210:211], 2, s[90:91]
	global_store_dwordx4 v[210:211], v[202:205], off
	v_sub_f32_e32 v149, v149, v198
	v_sub_f32_e32 v148, v148, v198
	v_sub_f32_e32 v203, v245, v200
	v_sub_f32_e32 v202, v244, v200
	v_sub_f32_e32 v141, v141, v196
	v_sub_f32_e32 v140, v140, v196
	v_sub_f32_e32 v205, v247, v200
	v_sub_f32_e32 v204, v246, v200
	v_pk_mul_f32 v[202:203], v[200:201], v[202:203] op_sel:[1,0]
	v_sub_f32_e32 v151, v151, v198
	v_sub_f32_e32 v150, v150, v198
	v_pk_mul_f32 v[148:149], v[198:199], v[148:149] op_sel:[1,0]
	v_sub_f32_e32 v143, v143, v196
	v_sub_f32_e32 v142, v142, v196
	v_pk_mul_f32 v[140:141], v[196:197], v[140:141] op_sel:[1,0]
	v_pk_mul_f32 v[204:205], v[200:201], v[204:205] op_sel:[1,0]
	v_pk_fma_f32 v[202:203], v[214:215], v[202:203], v[20:21]
	v_sub_f32_e32 v153, v153, v200
	v_sub_f32_e32 v152, v152, v200
	v_sub_f32_e32 v155, v155, v200
	v_sub_f32_e32 v154, v154, v200
	v_pk_mul_f32 v[150:151], v[198:199], v[150:151] op_sel:[1,0]
	v_pk_fma_f32 v[148:149], v[214:215], v[148:149], v[12:13]
	v_pk_mul_f32 v[142:143], v[196:197], v[142:143] op_sel:[1,0]
	v_pk_fma_f32 v[140:141], v[214:215], v[140:141], v[4:5]
	v_pk_fma_f32 v[204:205], v[212:213], v[204:205], v[22:23]
	v_pk_fma_f32 v[202:203], v[132:133], s[78:79], v[202:203] op_sel_hi:[1,0,1]
	v_pk_mul_f32 v[154:155], v[200:201], v[154:155] op_sel:[1,0]
	v_pk_mul_f32 v[152:153], v[200:201], v[152:153] op_sel:[1,0]
	v_pk_fma_f32 v[150:151], v[212:213], v[150:151], v[14:15]
	v_pk_fma_f32 v[148:149], v[132:133], s[78:79], v[148:149] op_sel_hi:[1,0,1]
	v_pk_fma_f32 v[142:143], v[212:213], v[142:143], v[6:7]
	v_pk_fma_f32 v[132:133], v[132:133], s[78:79], v[140:141] op_sel_hi:[1,0,1]
	v_add_u32_e32 v140, 0x58080, v194
	v_mov_b32_e32 v141, v159
	v_pk_fma_f32 v[204:205], v[134:135], s[78:79], v[204:205] op_sel_hi:[1,0,1]
	v_pk_fma_f32 v[152:153], v[208:209], v[152:153], v[16:17]
	v_pk_fma_f32 v[154:155], v[206:207], v[154:155], v[18:19]
	v_add_u32_e32 v200, 0x48090, v194
	v_mov_b32_e32 v201, v159
	v_pk_fma_f32 v[150:151], v[134:135], s[78:79], v[150:151] op_sel_hi:[1,0,1]
	v_pk_fma_f32 v[134:135], v[134:135], s[78:79], v[142:143] op_sel_hi:[1,0,1]
	v_lshl_add_u64 v[140:141], v[140:141], 2, s[90:91]
	v_pk_fma_f32 v[154:155], v[130:131], s[78:79], v[154:155] op_sel_hi:[1,0,1]
	v_pk_fma_f32 v[152:153], v[128:129], s[78:79], v[152:153] op_sel_hi:[1,0,1]
	v_lshl_add_u64 v[200:201], v[200:201], 2, s[90:91]
	v_sub_f32_e32 v145, v145, v198
	v_sub_f32_e32 v144, v144, v198
	global_store_dwordx4 v[140:141], v[132:135], off
	global_store_dwordx4 v[200:201], v[152:155], off
	v_sub_f32_e32 v147, v147, v198
	v_sub_f32_e32 v133, v137, v196
	v_sub_f32_e32 v132, v136, v196
	v_add_u32_e32 v152, 0x50080, v194
	v_mov_b32_e32 v153, v159
	v_sub_f32_e32 v146, v146, v198
	v_pk_mul_f32 v[144:145], v[198:199], v[144:145] op_sel:[1,0]
	v_sub_f32_e32 v135, v139, v196
	v_sub_f32_e32 v134, v138, v196
	v_pk_mul_f32 v[132:133], v[196:197], v[132:133] op_sel:[1,0]
	v_lshl_add_u64 v[152:153], v[152:153], 2, s[90:91]
	v_pk_mul_f32 v[146:147], v[198:199], v[146:147] op_sel:[1,0]
	v_pk_fma_f32 v[144:145], v[208:209], v[144:145], v[8:9]
	v_pk_mul_f32 v[134:135], v[196:197], v[134:135] op_sel:[1,0]
	v_pk_fma_f32 v[132:133], v[208:209], v[132:133], v[0:1]
	v_add_u32_e32 v210, 0x48080, v194
	v_mov_b32_e32 v211, v159
	global_store_dwordx4 v[152:153], v[148:151], off
	v_pk_fma_f32 v[146:147], v[206:207], v[146:147], v[10:11]
	v_pk_fma_f32 v[144:145], v[128:129], s[78:79], v[144:145] op_sel_hi:[1,0,1]
	v_add_u32_e32 v148, 0x50090, v194
	v_mov_b32_e32 v149, v159
	v_pk_fma_f32 v[134:135], v[206:207], v[134:135], v[2:3]
	v_pk_fma_f32 v[128:129], v[128:129], s[78:79], v[132:133] op_sel_hi:[1,0,1]
	v_add_u32_e32 v132, 0x58090, v194
	v_mov_b32_e32 v133, v159
	v_lshl_add_u64 v[210:211], v[210:211], 2, s[90:91]
	v_pk_fma_f32 v[146:147], v[130:131], s[78:79], v[146:147] op_sel_hi:[1,0,1]
	v_lshl_add_u64 v[148:149], v[148:149], 2, s[90:91]
	v_pk_fma_f32 v[130:131], v[130:131], s[78:79], v[134:135] op_sel_hi:[1,0,1]
	v_lshl_add_u64 v[132:133], v[132:133], 2, s[90:91]
	global_store_dwordx4 v[210:211], v[202:205], off
	global_store_dwordx4 v[148:149], v[144:147], off
	global_store_dwordx4 v[132:133], v[128:131], off
	s_mov_b64 s[20:21], 0
	s_branch .LBB0_81

; #define PG8_STAGE(bufoff, gbase) do { _Pragma("unroll") for (int _i = 0; _i < 2; ++_i) \
;         __builtin_amdgcn_global_load_lds((const unsigned*)((const char*)(gbase) + voff[_i]), (LAS unsigned*)(lds + (bufoff) + ldsw + _i * 8192), 16, 0, 0); } while (0)
; #define PG8_LDA(dst, b, h) do { _Pragma("unroll") for (int m = 0; m < 4; ++m) _Pragma("unroll") for (int k = 0; k < 2; ++k) dst[m][k] = *(const LAS bf16x8*)(lds + PG8_SA(b, h) + aoff + m * 2048 + k * 1024); } while (0)
; #define PG8_LDB(dst, b, h) do { _Pragma("unroll") for (int n = 0; n < 2; ++n) _Pragma("unroll") for (int k = 0; k < 2; ++k) dst[n][k] = *(const LAS bf16x8*)(lds + PG8_SB(b, h) + boff + n * 2048 + k * 1024); } while (0)
; #define PG8_MMA(ai, bj, At, Bt) do { __builtin_amdgcn_s_setprio(1); _Pragma("unroll") for (int m = 0; m < 4; ++m) _Pragma("unroll") for (int n = 0; n < 2; ++n) _Pragma("unroll") for (int k = 0; k < 2; ++k) \
;         acc[ai][bj][m][n] = __builtin_amdgcn_mfma_f32_16x16x32_bf16(Bt[n][k], At[m][k], acc[ai][bj][m][n], 0, 0, 0); __builtin_amdgcn_s_setprio(0); } while (0)
; #define PG8_WAIT_L(n) asm volatile("s_waitcnt lgkmcnt(" #n ")" ::: "memory")
; #define PG8_BAR __builtin_amdgcn_s_barrier()
; #define PG8_SCHED __builtin_amdgcn_sched_barrier(0)
; template <class Epi>
; DI void gemm_phase(LAS unsigned char* lds, const Gemm g, const StaticOrder& S, const Epi& E) {
;     ...
;         const char* nA = has_next ? (const char*)g.A + (size_t)nxt.pm * tstep : cA; const char* nB = has_next ? (const char*)g.Bt + (size_t)nxt.pn * tstep : cB;
;         for (int t = 0; t < nt; t += 2) {
;             const bool last = (t == nt - 2);
;             const char* a1 = cA + (size_t)(t + 1) * kstep;
;             const char* a2 = last ? nA : cA + (size_t)(t + 2) * kstep; const char* b2 = last ? nB : cB + (size_t)(t + 2) * kstep;
;             const char* a3 = a2 + kstep; const char* b3 = b2 + kstep;
;             PG8_LDB(B0, 0, 0); PG8_SCHED; PG8_LDA(At, 0, 0); PG8_STAGE(PG8_SA(1, 1), a1 + hstep);
;             PG8_WAIT_L(8); PG8_BAR; PG8_WAIT_L(0); PG8_MMA(0, 0, At, B0); PG8_BAR; PG8_SCHED;
;             PG8_LDB(B1, 0, 1); PG8_STAGE(PG8_SB(0, 0), b2);
;             PG8_BAR; PG8_WAIT_L(0); PG8_MMA(0, 1, At, B1); PG8_BAR;
;             PG8_LDA(At, 0, 1); PG8_STAGE(PG8_SA(0, 0), a2);
;             PG8_BAR; PG8_WAIT_L(0); PG8_MMA(1, 0, At, B0); PG8_BAR; PG8_SCHED;
.LBB0_134:
	s_add_u32 s18, s16, 0x100
	s_addc_u32 s19, s17, 0
	s_add_i32 s39, 0, 0x10000
	v_add_u32_e32 v148, s39, v199
	ds_read_b128 v[96:99], v148
	ds_read_b128 v[100:103], v148 offset:1024
	ds_read_b128 v[136:139], v148 offset:2048
	ds_read_b128 v[148:151], v148 offset:3072
	s_cmpk_eq_i32 s33, 0x54
	s_cselect_b32 s23, s9, s19
	s_cselect_b32 s22, s8, s18
	s_cselect_b32 s21, s11, s5
	s_cselect_b32 s20, s10, s4
	v_lshl_add_u64 v[218:219], s[16:17], 0, v[144:145]
	s_add_i32 m0, s28, 0xc000
	ds_read_b128 v[152:155], v201
	ds_read_b128 v[186:189], v201 offset:1024
	ds_read_b128 v[190:193], v201 offset:2048
	ds_read_b128 v[194:197], v201 offset:3072
	ds_read_b128 v[202:205], v201 offset:4096
	ds_read_b128 v[206:209], v201 offset:5120
	ds_read_b128 v[210:213], v201 offset:6144
	ds_read_b128 v[214:217], v201 offset:7168
	global_load_lds_dwordx4 v[218:219], off
	v_lshl_add_u64 v[218:219], s[16:17], 0, v[146:147]
	s_add_i32 m0, s28, 0xe000
	s_nop 0
	global_load_lds_dwordx4 v[218:219], off
	s_waitcnt lgkmcnt(8)
	s_setprio 1
	s_barrier
	s_waitcnt lgkmcnt(0)
	v_mfma_f32_16x16x32_bf16 v[132:135], v[96:99], v[152:155], v[132:135]
	v_mfma_f32_16x16x32_bf16 v[128:131], v[136:139], v[152:155], v[128:131]
	v_mfma_f32_16x16x32_bf16 v[124:127], v[96:99], v[190:193], v[124:127]
	v_mfma_f32_16x16x32_bf16 v[120:123], v[136:139], v[190:193], v[120:123]
	v_mfma_f32_16x16x32_bf16 v[116:119], v[96:99], v[202:205], v[116:119]
	v_mfma_f32_16x16x32_bf16 v[112:115], v[136:139], v[202:205], v[112:115]
	v_mfma_f32_16x16x32_bf16 v[108:111], v[96:99], v[210:213], v[108:111]
	v_mfma_f32_16x16x32_bf16 v[104:107], v[136:139], v[210:213], v[104:107]
	v_mfma_f32_16x16x32_bf16 v[132:135], v[100:103], v[186:189], v[132:135]
	v_mfma_f32_16x16x32_bf16 v[128:131], v[148:151], v[186:189], v[128:131]
	v_mfma_f32_16x16x32_bf16 v[124:127], v[100:103], v[194:197], v[124:127]
	v_mfma_f32_16x16x32_bf16 v[120:123], v[148:151], v[194:197], v[120:123]
	v_mfma_f32_16x16x32_bf16 v[116:119], v[100:103], v[206:209], v[116:119]
	v_mfma_f32_16x16x32_bf16 v[112:115], v[148:151], v[206:209], v[112:115]
	v_mfma_f32_16x16x32_bf16 v[108:111], v[100:103], v[214:217], v[108:111]
	v_mfma_f32_16x16x32_bf16 v[104:107], v[148:151], v[214:217], v[104:107]
	s_setprio 0
	s_barrier
	s_add_i32 s40, 0, 0x14000
	s_add_i32 s16, s39, s27
	v_add_u32_e32 v158, s40, v199
	v_lshl_add_u64 v[218:219], s[20:21], 0, v[142:143]
	s_mov_b32 m0, s16
	ds_read_b128 v[226:229], v158
	ds_read_b128 v[230:233], v158 offset:1024
	ds_read_b128 v[234:237], v158 offset:2048
	ds_read_b128 v[238:241], v158 offset:3072
	global_load_lds_dwordx4 v[218:219], off
	v_lshl_add_u64 v[220:221], s[20:21], 0, v[140:141]
	s_add_i32 m0, s16, 0x2000
	s_nop 0
	global_load_lds_dwordx4 v[220:221], off
	s_setprio 1
	s_barrier
	s_waitcnt lgkmcnt(0)
	v_mfma_f32_16x16x32_bf16 v[60:63], v[226:229], v[152:155], v[60:63]
	v_mfma_f32_16x16x32_bf16 v[56:59], v[234:237], v[152:155], v[56:59]
	v_mfma_f32_16x16x32_bf16 v[52:55], v[226:229], v[190:193], v[52:55]
	v_mfma_f32_16x16x32_bf16 v[48:51], v[234:237], v[190:193], v[48:51]
	v_mfma_f32_16x16x32_bf16 v[44:47], v[226:229], v[202:205], v[44:47]
	v_mfma_f32_16x16x32_bf16 v[40:43], v[234:237], v[202:205], v[40:43]
	v_mfma_f32_16x16x32_bf16 v[36:39], v[226:229], v[210:213], v[36:39]
	v_mfma_f32_16x16x32_bf16 v[32:35], v[234:237], v[210:213], v[32:35]
	v_mfma_f32_16x16x32_bf16 v[60:63], v[230:233], v[186:189], v[60:63]
	v_mfma_f32_16x16x32_bf16 v[56:59], v[238:241], v[186:189], v[56:59]
	v_mfma_f32_16x16x32_bf16 v[52:55], v[230:233], v[194:197], v[52:55]
	v_mfma_f32_16x16x32_bf16 v[48:51], v[238:241], v[194:197], v[48:51]
	v_mfma_f32_16x16x32_bf16 v[44:47], v[230:233], v[206:209], v[44:47]
	v_mfma_f32_16x16x32_bf16 v[40:43], v[238:241], v[206:209], v[40:43]
	v_mfma_f32_16x16x32_bf16 v[36:39], v[230:233], v[214:217], v[36:39]
	v_mfma_f32_16x16x32_bf16 v[32:35], v[238:241], v[214:217], v[32:35]
	s_setprio 0
	s_mov_b32 m0, s28
	v_lshl_add_u64 v[242:243], s[22:23], 0, v[142:143]
	s_barrier
	ds_read_b128 v[152:155], v201 offset:16384
	ds_read_b128 v[186:189], v201 offset:17408
	ds_read_b128 v[190:193], v201 offset:18432
	ds_read_b128 v[194:197], v201 offset:19456
	ds_read_b128 v[202:205], v201 offset:20480
	ds_read_b128 v[206:209], v201 offset:21504
	ds_read_b128 v[210:213], v201 offset:22528
	ds_read_b128 v[214:217], v201 offset:23552
	global_load_lds_dwordx4 v[242:243], off
	v_lshl_add_u64 v[244:245], s[22:23], 0, v[140:141]
	s_mov_b32 m0, s29
	s_nop 0
	global_load_lds_dwordx4 v[244:245], off
	s_setprio 1
	s_barrier
	s_waitcnt lgkmcnt(0)
	v_mfma_f32_16x16x32_bf16 v[92:95], v[96:99], v[152:155], v[92:95]
	v_mfma_f32_16x16x32_bf16 v[88:91], v[136:139], v[152:155], v[88:91]
	v_mfma_f32_16x16x32_bf16 v[84:87], v[96:99], v[190:193], v[84:87]
	v_mfma_f32_16x16x32_bf16 v[80:83], v[136:139], v[190:193], v[80:83]
	v_mfma_f32_16x16x32_bf16 v[76:79], v[96:99], v[202:205], v[76:79]
	v_mfma_f32_16x16x32_bf16 v[72:75], v[136:139], v[202:205], v[72:75]
	v_mfma_f32_16x16x32_bf16 v[68:71], v[96:99], v[210:213], v[68:71]
	v_mfma_f32_16x16x32_bf16 v[64:67], v[136:139], v[210:213], v[64:67]
	v_mfma_f32_16x16x32_bf16 v[92:95], v[100:103], v[186:189], v[92:95]
	v_mfma_f32_16x16x32_bf16 v[88:91], v[148:151], v[186:189], v[88:91]
	v_mfma_f32_16x16x32_bf16 v[84:87], v[100:103], v[194:197], v[84:87]
	v_mfma_f32_16x16x32_bf16 v[80:83], v[148:151], v[194:197], v[80:83]
	v_mfma_f32_16x16x32_bf16 v[76:79], v[100:103], v[206:209], v[76:79]
	v_mfma_f32_16x16x32_bf16 v[72:75], v[148:151], v[206:209], v[72:75]
	v_mfma_f32_16x16x32_bf16 v[68:71], v[100:103], v[214:217], v[68:71]
	v_mfma_f32_16x16x32_bf16 v[64:67], v[148:151], v[214:217], v[64:67]
	s_setprio 0
	s_barrier
; #define PG8_STAGE(bufoff, gbase) do { _Pragma("unroll") for (int _i = 0; _i < 2; ++_i) \
;         __builtin_amdgcn_global_load_lds((const unsigned*)((const char*)(gbase) + voff[_i]), (LAS unsigned*)(lds + (bufoff) + ldsw + _i * 8192), 16, 0, 0); } while (0)
; #define PG8_LDA(dst, b, h) do { _Pragma("unroll") for (int m = 0; m < 4; ++m) _Pragma("unroll") for (int k = 0; k < 2; ++k) dst[m][k] = *(const LAS bf16x8*)(lds + PG8_SA(b, h) + aoff + m * 2048 + k * 1024); } while (0)
; #define PG8_LDB(dst, b, h) do { _Pragma("unroll") for (int n = 0; n < 2; ++n) _Pragma("unroll") for (int k = 0; k < 2; ++k) dst[n][k] = *(const LAS bf16x8*)(lds + PG8_SB(b, h) + boff + n * 2048 + k * 1024); } while (0)
; #define PG8_MMA(ai, bj, At, Bt) do { __builtin_amdgcn_s_setprio(1); _Pragma("unroll") for (int m = 0; m < 4; ++m) _Pragma("unroll") for (int n = 0; n < 2; ++n) _Pragma("unroll") for (int k = 0; k < 2; ++k) \
;         acc[ai][bj][m][n] = __builtin_amdgcn_mfma_f32_16x16x32_bf16(Bt[n][k], At[m][k], acc[ai][bj][m][n], 0, 0, 0); __builtin_amdgcn_s_setprio(0); } while (0)
; #define PG8_WAIT_V(n) asm volatile("s_waitcnt vmcnt(" #n ")" ::: "memory")
; #define PG8_WAIT_L(n) asm volatile("s_waitcnt lgkmcnt(" #n ")" ::: "memory")
; #define PG8_BAR __builtin_amdgcn_s_barrier()
; #define PG8_SCHED __builtin_amdgcn_sched_barrier(0)
; template <class Epi>
; DI void gemm_phase(LAS unsigned char* lds, const Gemm g, const StaticOrder& S, const Epi& E) {
;     ...
;             PG8_STAGE(PG8_SB(0, 1), b2 + hstep);
;             PG8_WAIT_V(6); PG8_BAR; PG8_MMA(1, 1, At, B1); PG8_BAR;
;             PG8_LDB(B0, 1, 0); PG8_SCHED; PG8_LDA(At, 1, 0); PG8_STAGE(PG8_SA(0, 1), a2 + hstep);
;             PG8_WAIT_L(8); PG8_BAR; PG8_WAIT_L(0); PG8_MMA(0, 0, At, B0); PG8_BAR; PG8_SCHED;
;             PG8_LDB(B1, 1, 1); PG8_STAGE(PG8_SB(1, 0), b3);
;             PG8_BAR; PG8_WAIT_L(0); PG8_MMA(0, 1, At, B1); PG8_BAR;
;             PG8_LDA(At, 1, 1); PG8_STAGE(PG8_SA(1, 0), a3);
;             PG8_BAR; PG8_WAIT_L(0); PG8_MMA(1, 0, At, B0); PG8_BAR; PG8_SCHED;
	s_add_u32 s16, s20, 0x160000
	s_addc_u32 s17, s21, 0
	s_add_i32 s39, s40, s27
	v_lshl_add_u64 v[96:97], s[16:17], 0, v[142:143]
	s_mov_b32 m0, s39
	s_nop 0
	global_load_lds_dwordx4 v[96:97], off
	v_lshl_add_u64 v[96:97], s[16:17], 0, v[140:141]
	s_add_i32 m0, s39, 0x2000
	s_nop 0
	global_load_lds_dwordx4 v[96:97], off
	s_waitcnt vmcnt(6)
	s_setprio 1
	s_barrier
	v_mfma_f32_16x16x32_bf16 v[28:31], v[226:229], v[152:155], v[28:31]
	v_mfma_f32_16x16x32_bf16 v[24:27], v[234:237], v[152:155], v[24:27]
	v_mfma_f32_16x16x32_bf16 v[20:23], v[226:229], v[190:193], v[20:23]
	v_mfma_f32_16x16x32_bf16 v[16:19], v[234:237], v[190:193], v[16:19]
	v_mfma_f32_16x16x32_bf16 v[12:15], v[226:229], v[202:205], v[12:15]
	v_mfma_f32_16x16x32_bf16 v[8:11], v[234:237], v[202:205], v[8:11]
	v_mfma_f32_16x16x32_bf16 v[4:7], v[226:229], v[210:213], v[4:7]
	v_mfma_f32_16x16x32_bf16 v[0:3], v[234:237], v[210:213], v[0:3]
	v_mfma_f32_16x16x32_bf16 v[28:31], v[230:233], v[186:189], v[28:31]
	v_mfma_f32_16x16x32_bf16 v[24:27], v[238:241], v[186:189], v[24:27]
	v_mfma_f32_16x16x32_bf16 v[20:23], v[230:233], v[194:197], v[20:23]
	v_mfma_f32_16x16x32_bf16 v[16:19], v[238:241], v[194:197], v[16:19]
	v_mfma_f32_16x16x32_bf16 v[12:15], v[230:233], v[206:209], v[12:15]
	v_mfma_f32_16x16x32_bf16 v[8:11], v[238:241], v[206:209], v[8:11]
	v_mfma_f32_16x16x32_bf16 v[4:7], v[230:233], v[214:217], v[4:7]
	v_mfma_f32_16x16x32_bf16 v[0:3], v[238:241], v[214:217], v[0:3]
	s_setprio 0
	s_add_i32 s39, 0, 0x18000
	v_add_u32_e32 v148, s39, v199
	s_barrier
	ds_read_b128 v[96:99], v148
	ds_read_b128 v[100:103], v148 offset:1024
	ds_read_b128 v[136:139], v148 offset:2048
	ds_read_b128 v[148:151], v148 offset:3072
	s_add_u32 s16, s22, 0x160000
	s_addc_u32 s17, s23, 0
	s_mov_b32 m0, s30
	v_lshl_add_u64 v[226:227], s[16:17], 0, v[142:143]
	ds_read_b128 v[152:155], v201 offset:32768
	ds_read_b128 v[186:189], v201 offset:33792
	ds_read_b128 v[190:193], v201 offset:34816
	ds_read_b128 v[194:197], v201 offset:35840
	ds_read_b128 v[202:205], v201 offset:36864
	ds_read_b128 v[206:209], v201 offset:37888
	ds_read_b128 v[210:213], v201 offset:38912
	ds_read_b128 v[214:217], v201 offset:39936
	global_load_lds_dwordx4 v[226:227], off
	v_lshl_add_u64 v[226:227], s[16:17], 0, v[140:141]
	s_mov_b32 m0, s31
	s_nop 0
	global_load_lds_dwordx4 v[226:227], off
	s_waitcnt lgkmcnt(8)
	s_setprio 1
	s_barrier
	s_waitcnt lgkmcnt(0)
	v_mfma_f32_16x16x32_bf16 v[132:135], v[96:99], v[152:155], v[132:135]
	v_mfma_f32_16x16x32_bf16 v[128:131], v[136:139], v[152:155], v[128:131]
	v_mfma_f32_16x16x32_bf16 v[124:127], v[96:99], v[190:193], v[124:127]
	v_mfma_f32_16x16x32_bf16 v[120:123], v[136:139], v[190:193], v[120:123]
	v_mfma_f32_16x16x32_bf16 v[116:119], v[96:99], v[202:205], v[116:119]
	v_mfma_f32_16x16x32_bf16 v[112:115], v[136:139], v[202:205], v[112:115]
	v_mfma_f32_16x16x32_bf16 v[108:111], v[96:99], v[210:213], v[108:111]
	v_mfma_f32_16x16x32_bf16 v[104:107], v[136:139], v[210:213], v[104:107]
	v_mfma_f32_16x16x32_bf16 v[132:135], v[100:103], v[186:189], v[132:135]
	v_mfma_f32_16x16x32_bf16 v[128:131], v[148:151], v[186:189], v[128:131]
	v_mfma_f32_16x16x32_bf16 v[124:127], v[100:103], v[194:197], v[124:127]
	v_mfma_f32_16x16x32_bf16 v[120:123], v[148:151], v[194:197], v[120:123]
	v_mfma_f32_16x16x32_bf16 v[116:119], v[100:103], v[206:209], v[116:119]
	v_mfma_f32_16x16x32_bf16 v[112:115], v[148:151], v[206:209], v[112:115]
	v_mfma_f32_16x16x32_bf16 v[108:111], v[100:103], v[214:217], v[108:111]
	v_mfma_f32_16x16x32_bf16 v[104:107], v[148:151], v[214:217], v[104:107]
	s_setprio 0
	s_barrier
	s_add_i32 s22, 0, 0x1c000
	s_add_i32 s16, s39, s27
	v_add_u32_e32 v158, s22, v199
	v_lshl_add_u64 v[218:219], v[218:219], 0, s[94:95]
	s_mov_b32 m0, s16
	ds_read_b128 v[226:229], v158
	ds_read_b128 v[230:233], v158 offset:1024
	ds_read_b128 v[234:237], v158 offset:2048
	ds_read_b128 v[238:241], v158 offset:3072
	global_load_lds_dwordx4 v[218:219], off
	v_lshl_add_u64 v[218:219], v[220:221], 0, s[94:95]
	s_add_i32 m0, s16, 0x2000
	s_nop 0
	global_load_lds_dwordx4 v[218:219], off
	s_setprio 1
	s_barrier
	s_waitcnt lgkmcnt(0)
	v_mfma_f32_16x16x32_bf16 v[60:63], v[226:229], v[152:155], v[60:63]
	v_mfma_f32_16x16x32_bf16 v[56:59], v[234:237], v[152:155], v[56:59]
	v_mfma_f32_16x16x32_bf16 v[52:55], v[226:229], v[190:193], v[52:55]
	v_mfma_f32_16x16x32_bf16 v[48:51], v[234:237], v[190:193], v[48:51]
	v_mfma_f32_16x16x32_bf16 v[44:47], v[226:229], v[202:205], v[44:47]
	v_mfma_f32_16x16x32_bf16 v[40:43], v[234:237], v[202:205], v[40:43]
	v_mfma_f32_16x16x32_bf16 v[36:39], v[226:229], v[210:213], v[36:39]
	v_mfma_f32_16x16x32_bf16 v[32:35], v[234:237], v[210:213], v[32:35]
	v_mfma_f32_16x16x32_bf16 v[60:63], v[230:233], v[186:189], v[60:63]
	v_mfma_f32_16x16x32_bf16 v[56:59], v[238:241], v[186:189], v[56:59]
	v_mfma_f32_16x16x32_bf16 v[52:55], v[230:233], v[194:197], v[52:55]
	v_mfma_f32_16x16x32_bf16 v[48:51], v[238:241], v[194:197], v[48:51]
	v_mfma_f32_16x16x32_bf16 v[44:47], v[230:233], v[206:209], v[44:47]
	v_mfma_f32_16x16x32_bf16 v[40:43], v[238:241], v[206:209], v[40:43]
	v_mfma_f32_16x16x32_bf16 v[36:39], v[230:233], v[214:217], v[36:39]
	v_mfma_f32_16x16x32_bf16 v[32:35], v[238:241], v[214:217], v[32:35]
	s_setprio 0
	s_mov_b32 m0, s34
	v_lshl_add_u64 v[218:219], v[242:243], 0, s[94:95]
	s_barrier
	ds_read_b128 v[152:155], v201 offset:49152
	ds_read_b128 v[186:189], v201 offset:50176
	ds_read_b128 v[190:193], v201 offset:51200
	ds_read_b128 v[194:197], v201 offset:52224
	ds_read_b128 v[202:205], v201 offset:53248
	ds_read_b128 v[206:209], v201 offset:54272
	ds_read_b128 v[210:213], v201 offset:55296
	ds_read_b128 v[214:217], v201 offset:56320
	global_load_lds_dwordx4 v[218:219], off
	v_lshl_add_u64 v[218:219], v[244:245], 0, s[94:95]
	s_mov_b32 m0, s35
	s_nop 0
	global_load_lds_dwordx4 v[218:219], off
	s_setprio 1
	s_barrier
; #define PG8_STAGE(bufoff, gbase) do { _Pragma("unroll") for (int _i = 0; _i < 2; ++_i) \
;         __builtin_amdgcn_global_load_lds((const unsigned*)((const char*)(gbase) + voff[_i]), (LAS unsigned*)(lds + (bufoff) + ldsw + _i * 8192), 16, 0, 0); } while (0)
; #define PG8_MMA(ai, bj, At, Bt) do { __builtin_amdgcn_s_setprio(1); _Pragma("unroll") for (int m = 0; m < 4; ++m) _Pragma("unroll") for (int n = 0; n < 2; ++n) _Pragma("unroll") for (int k = 0; k < 2; ++k) \
;         acc[ai][bj][m][n] = __builtin_amdgcn_mfma_f32_16x16x32_bf16(Bt[n][k], At[m][k], acc[ai][bj][m][n], 0, 0, 0); __builtin_amdgcn_s_setprio(0); } while (0)
; #define PG8_WAIT_V(n) asm volatile("s_waitcnt vmcnt(" #n ")" ::: "memory")
; #define PG8_WAIT_L(n) asm volatile("s_waitcnt lgkmcnt(" #n ")" ::: "memory")
; #define PG8_BAR __builtin_amdgcn_s_barrier()
; #define PG8_SCHED __builtin_amdgcn_sched_barrier(0)
; template <class Epi>
; DI void gemm_phase(LAS unsigned char* lds, const Gemm g, const StaticOrder& S, const Epi& E) {
;     ...
;             PG8_BAR; PG8_WAIT_L(0); PG8_MMA(1, 0, At, B0); PG8_BAR; PG8_SCHED;
;             PG8_STAGE(PG8_SB(1, 1), b3 + hstep);
;             PG8_WAIT_V(6); PG8_BAR; PG8_MMA(1, 1, At, B1); PG8_BAR;
;     template <bool LN, int BJ> DI void load_gb(unsigned col0, f32x4 (&gv)[2], f32x4 (&bv)[2]) const {
; #pragma unroll
;         for (int n = 0; n < 2; ++n) {
;             if (LN) { gv[n] = *(const f32x4*)(gam + col0 + BJ * HALF + n * 16) * ALPHA; bv[n] = *(const f32x4*)(bet + col0 + BJ * HALF + n * 16) * ALPHA; }
;             else { gv[n] = (f32x4){ALPHA, ALPHA, ALPHA, ALPHA}; bv[n] = (f32x4){0.f, 0.f, 0.f, 0.f}; }
;         }
;     }
;     template <bool LN> DI void run(const f32x4 (&acc)[2][2][4][2], const Unit& u, int wr, int wc, int fr, int fq) const {
;         const unsigned row0 = u.pm * BM + wr * 64 + fr, col0 = u.pn * BM + wc * 32 + 4 * fq;
;         f32x4 gv[2], bv[2];
;         load_gb<LN, 0>(col0, gv, bv);
;         batch<LN, 0, 0, 4>(acc, row0, col0, gv, bv);
	s_waitcnt lgkmcnt(0)
	v_mfma_f32_16x16x32_bf16 v[92:95], v[96:99], v[152:155], v[92:95]
	v_mfma_f32_16x16x32_bf16 v[88:91], v[136:139], v[152:155], v[88:91]
	v_mfma_f32_16x16x32_bf16 v[84:87], v[96:99], v[190:193], v[84:87]
	v_mfma_f32_16x16x32_bf16 v[80:83], v[136:139], v[190:193], v[80:83]
	v_mfma_f32_16x16x32_bf16 v[76:79], v[96:99], v[202:205], v[76:79]
	v_mfma_f32_16x16x32_bf16 v[72:75], v[136:139], v[202:205], v[72:75]
	v_mfma_f32_16x16x32_bf16 v[68:71], v[96:99], v[210:213], v[68:71]
	v_mfma_f32_16x16x32_bf16 v[64:67], v[136:139], v[210:213], v[64:67]
	v_mfma_f32_16x16x32_bf16 v[92:95], v[100:103], v[186:189], v[92:95]
	v_mfma_f32_16x16x32_bf16 v[88:91], v[148:151], v[186:189], v[88:91]
	v_mfma_f32_16x16x32_bf16 v[84:87], v[100:103], v[194:197], v[84:87]
	v_mfma_f32_16x16x32_bf16 v[80:83], v[148:151], v[194:197], v[80:83]
	v_mfma_f32_16x16x32_bf16 v[76:79], v[100:103], v[206:209], v[76:79]
	v_mfma_f32_16x16x32_bf16 v[72:75], v[148:151], v[206:209], v[72:75]
	v_mfma_f32_16x16x32_bf16 v[68:71], v[100:103], v[214:217], v[68:71]
	v_mfma_f32_16x16x32_bf16 v[64:67], v[148:151], v[214:217], v[64:67]
	s_setprio 0
	s_barrier
	s_add_u32 s16, s20, 0x160080
	s_addc_u32 s17, s21, 0
	s_add_i32 s20, s22, s27
	v_lshl_add_u64 v[96:97], s[16:17], 0, v[142:143]
	s_mov_b32 m0, s20
	s_nop 0
	global_load_lds_dwordx4 v[96:97], off
	v_lshl_add_u64 v[96:97], s[16:17], 0, v[140:141]
	s_add_i32 m0, s20, 0x2000
	s_nop 0
	global_load_lds_dwordx4 v[96:97], off
	s_waitcnt vmcnt(6)
	s_setprio 1
	s_barrier
	v_mfma_f32_16x16x32_bf16 v[28:31], v[226:229], v[152:155], v[28:31]
	v_mfma_f32_16x16x32_bf16 v[24:27], v[234:237], v[152:155], v[24:27]
	v_mfma_f32_16x16x32_bf16 v[20:23], v[226:229], v[190:193], v[20:23]
	v_mfma_f32_16x16x32_bf16 v[16:19], v[234:237], v[190:193], v[16:19]
	v_mfma_f32_16x16x32_bf16 v[12:15], v[226:229], v[202:205], v[12:15]
	v_mfma_f32_16x16x32_bf16 v[8:11], v[234:237], v[202:205], v[8:11]
	v_mfma_f32_16x16x32_bf16 v[4:7], v[226:229], v[210:213], v[4:7]
	v_mfma_f32_16x16x32_bf16 v[0:3], v[234:237], v[210:213], v[0:3]
	v_mfma_f32_16x16x32_bf16 v[28:31], v[230:233], v[186:189], v[28:31]
	v_mfma_f32_16x16x32_bf16 v[24:27], v[238:241], v[186:189], v[24:27]
	v_mfma_f32_16x16x32_bf16 v[20:23], v[230:233], v[194:197], v[20:23]
	v_mfma_f32_16x16x32_bf16 v[16:19], v[238:241], v[194:197], v[16:19]
	v_mfma_f32_16x16x32_bf16 v[12:15], v[230:233], v[206:209], v[12:15]
	v_mfma_f32_16x16x32_bf16 v[8:11], v[238:241], v[206:209], v[8:11]
	v_mfma_f32_16x16x32_bf16 v[4:7], v[230:233], v[214:217], v[4:7]
	v_mfma_f32_16x16x32_bf16 v[0:3], v[238:241], v[214:217], v[0:3]
	s_setprio 0
	s_add_i32 s33, s33, 2
	s_add_u32 s4, s4, 0x100
	s_addc_u32 s5, s5, 0
	s_cmpk_gt_u32 s33, 0x55
	s_mov_b64 s[16:17], s[18:19]
	s_barrier
	s_cbranch_scc0 .LBB0_134
	v_lshl_or_b32 v158, s2, 8, v200
	v_lshlrev_b64 v[100:101], 2, v[158:159]
	v_lshl_add_u64 v[150:151], s[12:13], 0, v[100:101]
	global_load_dwordx4 v[96:99], v[150:151], off
	v_lshl_add_u64 v[152:153], s[14:15], 0, v[100:101]
	v_lshl_add_u32 v203, s3, 8, v198
	v_lshlrev_b32_e32 v202, 11, v203
	v_add_u32_e32 v148, v202, v158
	v_mov_b32_e32 v149, v159
	v_lshlrev_b32_e32 v136, 1, v203
	v_mov_b32_e32 v137, v159
	v_lshlrev_b64 v[220:221], 2, v[148:149]
	v_lshl_add_u64 v[154:155], v[136:137], 2, s[96:97]
	v_lshl_add_u64 v[136:137], s[90:91], 0, v[220:221]
	v_or_b32_e32 v204, 16, v158
	v_or_b32_e32 v138, 16, v203
	v_lshlrev_b32_e32 v149, 11, v138
	s_waitcnt vmcnt(0)
	v_pk_mul_f32 v[192:193], v[98:99], s[78:79] op_sel_hi:[1,0]
	v_pk_mul_f32 v[194:195], v[96:97], s[78:79] op_sel_hi:[1,0]
	global_load_dwordx4 v[100:103], v[152:153], off
	global_load_dwordx4 v[96:99], v[150:151], off offset:64
	global_load_dwordx2 v[218:219], v[154:155], off
	global_load_dwordx4 v[206:209], v[136:137], off
	v_add_u32_e32 v136, v202, v204
	v_mov_b32_e32 v137, v159
	v_lshl_add_u64 v[136:137], v[136:137], 2, s[90:91]
	global_load_dwordx4 v[210:213], v[136:137], off
	v_lshlrev_b32_e32 v136, 1, v138
	v_mov_b32_e32 v137, v159
	v_lshl_add_u64 v[186:187], v[136:137], 2, s[96:97]
	v_add_u32_e32 v136, v149, v158
	v_lshl_add_u64 v[136:137], v[136:137], 2, s[90:91]
	global_load_dwordx2 v[196:197], v[186:187], off
	global_load_dwordx4 v[214:217], v[136:137], off
	v_add_u32_e32 v136, v149, v204
	v_mov_b32_e32 v137, v159
	v_lshl_add_u64 v[136:137], v[136:137], 2, s[90:91]
	global_load_dwordx4 v[136:139], v[136:137], off
	s_waitcnt vmcnt(0)
	v_pk_mul_f32 v[188:189], v[98:99], s[78:79] op_sel_hi:[1,0]
	v_pk_mul_f32 v[190:191], v[96:97], s[78:79] op_sel_hi:[1,0]
	global_load_dwordx4 v[96:99], v[152:153], off offset:64
	v_sub_f32_e32 v207, v207, v218
	v_sub_f32_e32 v206, v206, v218
	v_sub_f32_e32 v209, v209, v218
	v_sub_f32_e32 v208, v208, v218
	v_pk_mul_f32 v[208:209], v[218:219], v[208:209] op_sel:[1,0]
	v_pk_mul_f32 v[206:207], v[218:219], v[206:207] op_sel:[1,0]
	v_pk_fma_f32 v[134:135], v[192:193], v[208:209], v[134:135]
	v_pk_fma_f32 v[132:133], v[194:195], v[206:207], v[132:133]
	v_pk_fma_f32 v[134:135], v[102:103], s[78:79], v[134:135] op_sel_hi:[1,0,1]
	v_pk_fma_f32 v[132:133], v[100:101], s[78:79], v[132:133] op_sel_hi:[1,0,1]
	v_lshl_add_u64 v[206:207], s[88:89], 0, v[220:221]
	global_store_dwordx4 v[206:207], v[132:135], off
	s_nop 1
	v_sub_f32_e32 v133, v211, v218
	v_sub_f32_e32 v132, v210, v218
	v_sub_f32_e32 v135, v213, v218
	v_sub_f32_e32 v134, v212, v218
	v_pk_mul_f32 v[134:135], v[218:219], v[134:135] op_sel:[1,0]
	v_pk_mul_f32 v[132:133], v[218:219], v[132:133] op_sel:[1,0]
	v_pk_fma_f32 v[130:131], v[188:189], v[134:135], v[130:131]
	v_pk_fma_f32 v[128:129], v[190:191], v[132:133], v[128:129]
	v_or_b32_e32 v132, 16, v148
	v_mov_b32_e32 v133, v159
	v_lshl_add_u64 v[132:133], v[132:133], 2, s[88:89]
	s_waitcnt vmcnt(0)
;     template <bool LN, int BJ, int LO, int HI> DI void batch(const f32x4 (&acc)[2][2][4][2], unsigned row0, unsigned col0, const f32x4 (&gv)[2], const f32x4 (&bv)[2]) const {
;         f32x4 r[HI - LO]; float mean[(HI - LO) / 2], rstd[(HI - LO) / 2];
; #pragma unroll
;         for (int i = LO; i < HI; ++i) { const int ai = i >> 3, m = (i >> 1) & 3, n = i & 1; const unsigned row = row0 + ai * HALF + m * 16;
;             if (n == 0) { mean[(i - LO) >> 1] = 0.f; rstd[(i - LO) >> 1] = 1.f;
;                 if (LN) { const float2 st = *(const float2*)(stats + row * 2u); mean[(i - LO) >> 1] = st.x; rstd[(i - LO) >> 1] = st.y; } }
;             r[i - LO] = *(const f32x4*)(src + (row * (unsigned)DM + col0 + BJ * HALF + n * 16)); }
; #pragma unroll
;         for (int i = LO; i < HI; ++i) { const int ai = i >> 3, m = (i >> 1) & 3, n = i & 1; const unsigned row = row0 + ai * HALF + m * 16;
;             *(f32x4*)(Y + (row * (unsigned)DM + col0 + BJ * HALF + n * 16)) = acc[ai][BJ][m][n] + ((r[i - LO] - mean[(i - LO) >> 1]) * rstd[(i - LO) >> 1]) * gv[n] + bv[n]; }
;         __builtin_amdgcn_sched_barrier(0);
;     }
;     template <bool LN, int BJ> DI void load_gb(unsigned col0, f32x4 (&gv)[2], f32x4 (&bv)[2]) const {
; #pragma unroll
;         for (int n = 0; n < 2; ++n) {
;             if (LN) { gv[n] = *(const f32x4*)(gam + col0 + BJ * HALF + n * 16) * ALPHA; bv[n] = *(const f32x4*)(bet + col0 + BJ * HALF + n * 16) * ALPHA; }
;             else { gv[n] = (f32x4){ALPHA, ALPHA, ALPHA, ALPHA}; bv[n] = (f32x4){0.f, 0.f, 0.f, 0.f}; }
;         }
;     }
;     template <bool LN> DI void run(const f32x4 (&acc)[2][2][4][2], const Unit& u, int wr, int wc, int fr, int fq) const {
;         const unsigned row0 = u.pm * BM + wr * 64 + fr, col0 = u.pn * BM + wc * 32 + 4 * fq;
;         f32x4 gv[2], bv[2];
;         load_gb<LN, 0>(col0, gv, bv);
;         batch<LN, 0, 0, 4>(acc, row0, col0, gv, bv);
;         batch<LN, 0, 4, 8>(acc, row0, col0, gv, bv);
;         batch<LN, 0, 8, 12>(acc, row0, col0, gv, bv);
;         batch<LN, 0, 12, 16>(acc, row0, col0, gv, bv);
;         load_gb<LN, 1>(col0, gv, bv);
;         batch<LN, 1, 0, 8>(acc, row0, col0, gv, bv);
;         batch<LN, 1, 8, 16>(acc, row0, col0, gv, bv);
	v_pk_fma_f32 v[130:131], v[98:99], s[78:79], v[130:131] op_sel_hi:[1,0,1]
	v_pk_fma_f32 v[128:129], v[96:97], s[78:79], v[128:129] op_sel_hi:[1,0,1]
	global_store_dwordx4 v[132:133], v[128:131], off
	s_nop 1
	v_sub_f32_e32 v129, v215, v196
	v_sub_f32_e32 v128, v214, v196
	v_sub_f32_e32 v131, v217, v196
	v_sub_f32_e32 v130, v216, v196
	v_pk_mul_f32 v[130:131], v[196:197], v[130:131] op_sel:[1,0]
	v_pk_mul_f32 v[128:129], v[196:197], v[128:129] op_sel:[1,0]
	v_pk_fma_f32 v[126:127], v[192:193], v[130:131], v[126:127]
	v_pk_fma_f32 v[124:125], v[194:195], v[128:129], v[124:125]
	v_add_u32_e32 v128, 0x8000, v148
	v_mov_b32_e32 v129, v159
	v_pk_fma_f32 v[126:127], v[102:103], s[78:79], v[126:127] op_sel_hi:[1,0,1]
	v_pk_fma_f32 v[124:125], v[100:101], s[78:79], v[124:125] op_sel_hi:[1,0,1]
	v_lshl_add_u64 v[128:129], v[128:129], 2, s[88:89]
	global_store_dwordx4 v[128:129], v[124:127], off
	s_nop 1
	v_sub_f32_e32 v125, v137, v196
	v_sub_f32_e32 v124, v136, v196
	v_sub_f32_e32 v127, v139, v196
	v_sub_f32_e32 v126, v138, v196
	v_pk_mul_f32 v[126:127], v[196:197], v[126:127] op_sel:[1,0]
	v_pk_mul_f32 v[124:125], v[196:197], v[124:125] op_sel:[1,0]
	v_pk_fma_f32 v[122:123], v[188:189], v[126:127], v[122:123]
	v_pk_fma_f32 v[120:121], v[190:191], v[124:125], v[120:121]
	v_add_u32_e32 v124, 0x8010, v148
	v_mov_b32_e32 v125, v159
	v_pk_fma_f32 v[122:123], v[98:99], s[78:79], v[122:123] op_sel_hi:[1,0,1]
	v_pk_fma_f32 v[120:121], v[96:97], s[78:79], v[120:121] op_sel_hi:[1,0,1]
	v_lshl_add_u64 v[124:125], v[124:125], 2, s[88:89]
	global_store_dwordx4 v[124:125], v[120:123], off
	s_nop 1
	v_or_b32_e32 v122, 32, v203
	v_lshlrev_b32_e32 v124, 11, v122
	v_lshlrev_b32_e32 v120, 1, v122
	v_mov_b32_e32 v121, v159
	v_add_u32_e32 v122, v124, v158
	v_mov_b32_e32 v123, v159
	v_lshl_add_u64 v[120:121], v[120:121], 2, s[96:97]
	v_lshl_add_u64 v[122:123], v[122:123], 2, s[90:91]
	global_load_dwordx2 v[138:139], v[120:121], off
	global_load_dwordx4 v[126:129], v[122:123], off
	v_add_u32_e32 v122, v124, v204
	v_mov_b32_e32 v123, v159
	v_lshl_add_u64 v[122:123], v[122:123], 2, s[90:91]
	global_load_dwordx4 v[130:133], v[122:123], off
	v_or_b32_e32 v125, 48, v203
	v_lshlrev_b32_e32 v122, 1, v125
	v_lshlrev_b32_e32 v125, 11, v125
	v_mov_b32_e32 v123, v159
	v_add_u32_e32 v134, v125, v158
	v_mov_b32_e32 v135, v159
	v_lshl_add_u64 v[122:123], v[122:123], 2, s[96:97]
	v_lshl_add_u64 v[134:135], v[134:135], 2, s[90:91]
	global_load_dwordx2 v[196:197], v[122:123], off
	v_add_u32_e32 v206, v125, v204
	global_load_dwordx4 v[134:137], v[134:135], off
	v_mov_b32_e32 v207, v159
	v_lshl_add_u64 v[206:207], v[206:207], 2, s[90:91]
	global_load_dwordx4 v[206:209], v[206:207], off
	s_waitcnt vmcnt(0)
	v_sub_f32_e32 v127, v127, v138
	v_sub_f32_e32 v126, v126, v138
	v_sub_f32_e32 v129, v129, v138
	v_sub_f32_e32 v128, v128, v138
	v_pk_mul_f32 v[128:129], v[138:139], v[128:129] op_sel:[1,0]
	v_pk_mul_f32 v[126:127], v[138:139], v[126:127] op_sel:[1,0]
	v_pk_fma_f32 v[118:119], v[192:193], v[128:129], v[118:119]
	v_pk_fma_f32 v[116:117], v[194:195], v[126:127], v[116:117]
	v_add_u32_e32 v126, 0x10000, v148
	v_mov_b32_e32 v127, v159
	v_pk_fma_f32 v[118:119], v[102:103], s[78:79], v[118:119] op_sel_hi:[1,0,1]
	v_pk_fma_f32 v[116:117], v[100:101], s[78:79], v[116:117] op_sel_hi:[1,0,1]
	v_lshl_add_u64 v[126:127], v[126:127], 2, s[88:89]
	global_store_dwordx4 v[126:127], v[116:119], off
	s_nop 1
	v_sub_f32_e32 v117, v131, v138
	v_sub_f32_e32 v116, v130, v138
	v_sub_f32_e32 v119, v133, v138
	v_sub_f32_e32 v118, v132, v138
	v_pk_mul_f32 v[118:119], v[138:139], v[118:119] op_sel:[1,0]
	v_pk_mul_f32 v[116:117], v[138:139], v[116:117] op_sel:[1,0]
	v_pk_fma_f32 v[114:115], v[188:189], v[118:119], v[114:115]
	v_pk_fma_f32 v[112:113], v[190:191], v[116:117], v[112:113]
	v_add_u32_e32 v116, 0x10010, v148
	v_mov_b32_e32 v117, v159
	v_pk_fma_f32 v[114:115], v[98:99], s[78:79], v[114:115] op_sel_hi:[1,0,1]
	v_pk_fma_f32 v[112:113], v[96:97], s[78:79], v[112:113] op_sel_hi:[1,0,1]
	v_lshl_add_u64 v[116:117], v[116:117], 2, s[88:89]
	global_store_dwordx4 v[116:117], v[112:115], off
	s_nop 1
	v_sub_f32_e32 v113, v135, v196
	v_sub_f32_e32 v112, v134, v196
	v_sub_f32_e32 v115, v137, v196
	v_sub_f32_e32 v114, v136, v196
	v_pk_mul_f32 v[114:115], v[196:197], v[114:115] op_sel:[1,0]
	v_pk_mul_f32 v[112:113], v[196:197], v[112:113] op_sel:[1,0]
	v_pk_fma_f32 v[110:111], v[192:193], v[114:115], v[110:111]
	v_pk_fma_f32 v[108:109], v[194:195], v[112:113], v[108:109]
	v_add_u32_e32 v112, 0x18000, v148
	v_mov_b32_e32 v113, v159
	v_pk_fma_f32 v[110:111], v[102:103], s[78:79], v[110:111] op_sel_hi:[1,0,1]
	v_pk_fma_f32 v[108:109], v[100:101], s[78:79], v[108:109] op_sel_hi:[1,0,1]
	v_lshl_add_u64 v[112:113], v[112:113], 2, s[88:89]
	global_store_dwordx4 v[112:113], v[108:111], off
	s_nop 1
	v_sub_f32_e32 v109, v207, v196
	v_sub_f32_e32 v108, v206, v196
	v_sub_f32_e32 v111, v209, v196
	v_sub_f32_e32 v110, v208, v196
	v_pk_mul_f32 v[110:111], v[196:197], v[110:111] op_sel:[1,0]
	v_pk_mul_f32 v[108:109], v[196:197], v[108:109] op_sel:[1,0]
	v_pk_fma_f32 v[106:107], v[188:189], v[110:111], v[106:107]
	v_pk_fma_f32 v[104:105], v[190:191], v[108:109], v[104:105]
	v_add_u32_e32 v108, 0x18010, v148
	v_mov_b32_e32 v109, v159
	v_pk_fma_f32 v[106:107], v[98:99], s[78:79], v[106:107] op_sel_hi:[1,0,1]
	v_pk_fma_f32 v[104:105], v[96:97], s[78:79], v[104:105] op_sel_hi:[1,0,1]
	v_lshl_add_u64 v[108:109], v[108:109], 2, s[88:89]
	global_store_dwordx4 v[108:109], v[104:107], off
	s_nop 1
	v_add_u32_e32 v106, 0x80, v203
	v_lshlrev_b32_e32 v114, 11, v106
	v_lshlrev_b32_e32 v104, 1, v106
	v_mov_b32_e32 v105, v159
	v_add_u32_e32 v106, v114, v158
	v_mov_b32_e32 v107, v159
	v_lshl_add_u64 v[104:105], v[104:105], 2, s[96:97]
	v_lshl_add_u64 v[106:107], v[106:107], 2, s[90:91]
	global_load_dwordx2 v[112:113], v[104:105], off
	global_load_dwordx4 v[108:111], v[106:107], off
	v_add_u32_e32 v106, v114, v204
	v_mov_b32_e32 v107, v159
	v_lshl_add_u64 v[106:107], v[106:107], 2, s[90:91]
	global_load_dwordx4 v[116:119], v[106:107], off
	v_add_u32_e32 v115, 0x90, v203
	v_lshlrev_b32_e32 v106, 1, v115
	v_lshlrev_b32_e32 v115, 11, v115
	v_mov_b32_e32 v107, v159
	v_add_u32_e32 v126, v115, v158
	v_mov_b32_e32 v127, v159
	v_lshl_add_u64 v[106:107], v[106:107], 2, s[96:97]
	v_lshl_add_u64 v[126:127], v[126:127], 2, s[90:91]
	global_load_dwordx2 v[134:135], v[106:107], off
	v_add_u32_e32 v130, v115, v204
	global_load_dwordx4 v[126:129], v[126:127], off
	v_mov_b32_e32 v131, v159
	v_lshl_add_u64 v[130:131], v[130:131], 2, s[90:91]
	global_load_dwordx4 v[130:133], v[130:131], off
	s_waitcnt vmcnt(0)
;     template <bool LN, int BJ, int LO, int HI> DI void batch(const f32x4 (&acc)[2][2][4][2], unsigned row0, unsigned col0, const f32x4 (&gv)[2], const f32x4 (&bv)[2]) const {
;         f32x4 r[HI - LO]; float mean[(HI - LO) / 2], rstd[(HI - LO) / 2];
; #pragma unroll
;         for (int i = LO; i < HI; ++i) { const int ai = i >> 3, m = (i >> 1) & 3, n = i & 1; const unsigned row = row0 + ai * HALF + m * 16;
;             if (n == 0) { mean[(i - LO) >> 1] = 0.f; rstd[(i - LO) >> 1] = 1.f;
;                 if (LN) { const float2 st = *(const float2*)(stats + row * 2u); mean[(i - LO) >> 1] = st.x; rstd[(i - LO) >> 1] = st.y; } }
;             r[i - LO] = *(const f32x4*)(src + (row * (unsigned)DM + col0 + BJ * HALF + n * 16)); }
; #pragma unroll
;         for (int i = LO; i < HI; ++i) { const int ai = i >> 3, m = (i >> 1) & 3, n = i & 1; const unsigned row = row0 + ai * HALF + m * 16;
;             *(f32x4*)(Y + (row * (unsigned)DM + col0 + BJ * HALF + n * 16)) = acc[ai][BJ][m][n] + ((r[i - LO] - mean[(i - LO) >> 1]) * rstd[(i - LO) >> 1]) * gv[n] + bv[n]; }
;         __builtin_amdgcn_sched_barrier(0);
;     }
;     template <bool LN, int BJ> DI void load_gb(unsigned col0, f32x4 (&gv)[2], f32x4 (&bv)[2]) const {
; #pragma unroll
;         for (int n = 0; n < 2; ++n) {
;             if (LN) { gv[n] = *(const f32x4*)(gam + col0 + BJ * HALF + n * 16) * ALPHA; bv[n] = *(const f32x4*)(bet + col0 + BJ * HALF + n * 16) * ALPHA; }
;             else { gv[n] = (f32x4){ALPHA, ALPHA, ALPHA, ALPHA}; bv[n] = (f32x4){0.f, 0.f, 0.f, 0.f}; }
;         }
;     }
;     template <bool LN> DI void run(const f32x4 (&acc)[2][2][4][2], const Unit& u, int wr, int wc, int fr, int fq) const {
;         const unsigned row0 = u.pm * BM + wr * 64 + fr, col0 = u.pn * BM + wc * 32 + 4 * fq;
;         f32x4 gv[2], bv[2];
;         load_gb<LN, 0>(col0, gv, bv);
;         batch<LN, 0, 0, 4>(acc, row0, col0, gv, bv);
;         batch<LN, 0, 4, 8>(acc, row0, col0, gv, bv);
;         batch<LN, 0, 8, 12>(acc, row0, col0, gv, bv);
;         batch<LN, 0, 12, 16>(acc, row0, col0, gv, bv);
;         load_gb<LN, 1>(col0, gv, bv);
;         batch<LN, 1, 0, 8>(acc, row0, col0, gv, bv);
;         batch<LN, 1, 8, 16>(acc, row0, col0, gv, bv);
	v_sub_f32_e32 v109, v109, v112
	v_sub_f32_e32 v108, v108, v112
	v_sub_f32_e32 v111, v111, v112
	v_sub_f32_e32 v110, v110, v112
	v_pk_mul_f32 v[110:111], v[112:113], v[110:111] op_sel:[1,0]
	v_pk_mul_f32 v[108:109], v[112:113], v[108:109] op_sel:[1,0]
	v_pk_fma_f32 v[94:95], v[192:193], v[110:111], v[94:95]
	v_pk_fma_f32 v[92:93], v[194:195], v[108:109], v[92:93]
	v_add_u32_e32 v108, 0x40000, v148
	v_mov_b32_e32 v109, v159
	v_pk_fma_f32 v[94:95], v[102:103], s[78:79], v[94:95] op_sel_hi:[1,0,1]
	v_pk_fma_f32 v[92:93], v[100:101], s[78:79], v[92:93] op_sel_hi:[1,0,1]
	v_lshl_add_u64 v[108:109], v[108:109], 2, s[88:89]
	global_store_dwordx4 v[108:109], v[92:95], off
	s_nop 1
	v_sub_f32_e32 v93, v117, v112
	v_sub_f32_e32 v92, v116, v112
	v_sub_f32_e32 v95, v119, v112
	v_sub_f32_e32 v94, v118, v112
	v_pk_mul_f32 v[94:95], v[112:113], v[94:95] op_sel:[1,0]
	v_pk_mul_f32 v[92:93], v[112:113], v[92:93] op_sel:[1,0]
	v_pk_fma_f32 v[90:91], v[188:189], v[94:95], v[90:91]
	v_pk_fma_f32 v[88:89], v[190:191], v[92:93], v[88:89]
	v_add_u32_e32 v92, 0x40010, v148
	v_mov_b32_e32 v93, v159
	v_pk_fma_f32 v[90:91], v[98:99], s[78:79], v[90:91] op_sel_hi:[1,0,1]
	v_pk_fma_f32 v[88:89], v[96:97], s[78:79], v[88:89] op_sel_hi:[1,0,1]
	v_lshl_add_u64 v[92:93], v[92:93], 2, s[88:89]
	global_store_dwordx4 v[92:93], v[88:91], off
	s_nop 1
	v_sub_f32_e32 v89, v127, v134
	v_sub_f32_e32 v88, v126, v134
	v_sub_f32_e32 v91, v129, v134
	v_sub_f32_e32 v90, v128, v134
	v_pk_mul_f32 v[90:91], v[134:135], v[90:91] op_sel:[1,0]
	v_pk_mul_f32 v[88:89], v[134:135], v[88:89] op_sel:[1,0]
	v_pk_fma_f32 v[86:87], v[192:193], v[90:91], v[86:87]
	v_pk_fma_f32 v[84:85], v[194:195], v[88:89], v[84:85]
	v_add_u32_e32 v88, 0x48000, v148
	v_mov_b32_e32 v89, v159
	v_pk_fma_f32 v[86:87], v[102:103], s[78:79], v[86:87] op_sel_hi:[1,0,1]
	v_pk_fma_f32 v[84:85], v[100:101], s[78:79], v[84:85] op_sel_hi:[1,0,1]
	v_lshl_add_u64 v[88:89], v[88:89], 2, s[88:89]
	global_store_dwordx4 v[88:89], v[84:87], off
	s_nop 1
	v_sub_f32_e32 v85, v131, v134
	v_sub_f32_e32 v84, v130, v134
	v_sub_f32_e32 v87, v133, v134
	v_sub_f32_e32 v86, v132, v134
	v_pk_mul_f32 v[86:87], v[134:135], v[86:87] op_sel:[1,0]
	v_pk_mul_f32 v[84:85], v[134:135], v[84:85] op_sel:[1,0]
	v_pk_fma_f32 v[82:83], v[188:189], v[86:87], v[82:83]
	v_pk_fma_f32 v[80:81], v[190:191], v[84:85], v[80:81]
	v_add_u32_e32 v84, 0x48010, v148
	v_mov_b32_e32 v85, v159
	v_pk_fma_f32 v[82:83], v[98:99], s[78:79], v[82:83] op_sel_hi:[1,0,1]
	v_pk_fma_f32 v[80:81], v[96:97], s[78:79], v[80:81] op_sel_hi:[1,0,1]
	v_lshl_add_u64 v[84:85], v[84:85], 2, s[88:89]
	global_store_dwordx4 v[84:85], v[80:83], off
	s_nop 1
	v_add_u32_e32 v82, 0xa0, v203
	v_lshlrev_b32_e32 v80, 1, v82
	v_mov_b32_e32 v81, v159
	v_lshlrev_b32_e32 v116, 11, v82
	v_lshl_add_u64 v[108:109], v[80:81], 2, s[96:97]
	v_add_u32_e32 v80, v116, v158
	v_lshl_add_u64 v[80:81], v[80:81], 2, s[90:91]
	global_load_dwordx2 v[112:113], v[108:109], off
	v_add_u32_e32 v84, v116, v204
	global_load_dwordx4 v[80:83], v[80:81], off
	v_mov_b32_e32 v85, v159
	v_lshl_add_u64 v[84:85], v[84:85], 2, s[90:91]
	global_load_dwordx4 v[84:87], v[84:85], off
	v_add_u32_e32 v90, 0xb0, v203
	v_lshlrev_b32_e32 v88, 1, v90
	v_mov_b32_e32 v89, v159
	v_lshlrev_b32_e32 v117, 11, v90
	v_lshl_add_u64 v[110:111], v[88:89], 2, s[96:97]
	v_add_u32_e32 v88, v117, v158
	v_lshl_add_u64 v[88:89], v[88:89], 2, s[90:91]
	global_load_dwordx2 v[118:119], v[110:111], off
	v_add_u32_e32 v92, v117, v204
	global_load_dwordx4 v[88:91], v[88:89], off
	v_mov_b32_e32 v93, v159
	v_lshl_add_u64 v[92:93], v[92:93], 2, s[90:91]
	global_load_dwordx4 v[92:95], v[92:93], off
	s_waitcnt vmcnt(0)
	v_sub_f32_e32 v81, v81, v112
	v_sub_f32_e32 v80, v80, v112
	v_sub_f32_e32 v83, v83, v112
	v_sub_f32_e32 v82, v82, v112
	v_pk_mul_f32 v[82:83], v[112:113], v[82:83] op_sel:[1,0]
	v_pk_mul_f32 v[80:81], v[112:113], v[80:81] op_sel:[1,0]
	v_pk_fma_f32 v[78:79], v[192:193], v[82:83], v[78:79]
	v_pk_fma_f32 v[76:77], v[194:195], v[80:81], v[76:77]
	v_add_u32_e32 v80, 0x50000, v148
	v_mov_b32_e32 v81, v159
	v_pk_fma_f32 v[78:79], v[102:103], s[78:79], v[78:79] op_sel_hi:[1,0,1]
	v_pk_fma_f32 v[76:77], v[100:101], s[78:79], v[76:77] op_sel_hi:[1,0,1]
	v_lshl_add_u64 v[80:81], v[80:81], 2, s[88:89]
	global_store_dwordx4 v[80:81], v[76:79], off
	s_nop 1
	v_sub_f32_e32 v77, v85, v112
	v_sub_f32_e32 v76, v84, v112
	v_sub_f32_e32 v79, v87, v112
	v_sub_f32_e32 v78, v86, v112
	v_pk_mul_f32 v[78:79], v[112:113], v[78:79] op_sel:[1,0]
	v_pk_mul_f32 v[76:77], v[112:113], v[76:77] op_sel:[1,0]
	v_pk_fma_f32 v[74:75], v[188:189], v[78:79], v[74:75]
	v_pk_fma_f32 v[72:73], v[190:191], v[76:77], v[72:73]
	v_add_u32_e32 v76, 0x50010, v148
	v_mov_b32_e32 v77, v159
	v_pk_fma_f32 v[74:75], v[98:99], s[78:79], v[74:75] op_sel_hi:[1,0,1]
	v_pk_fma_f32 v[72:73], v[96:97], s[78:79], v[72:73] op_sel_hi:[1,0,1]
	v_lshl_add_u64 v[76:77], v[76:77], 2, s[88:89]
	global_store_dwordx4 v[76:77], v[72:75], off
	s_nop 1
	v_sub_f32_e32 v73, v89, v118
	v_sub_f32_e32 v72, v88, v118
	v_sub_f32_e32 v75, v91, v118
	v_sub_f32_e32 v74, v90, v118
	v_pk_mul_f32 v[74:75], v[118:119], v[74:75] op_sel:[1,0]
	v_pk_mul_f32 v[72:73], v[118:119], v[72:73] op_sel:[1,0]
	v_pk_fma_f32 v[70:71], v[192:193], v[74:75], v[70:71]
	v_pk_fma_f32 v[68:69], v[194:195], v[72:73], v[68:69]
	v_add_u32_e32 v72, 0x58000, v148
	v_mov_b32_e32 v73, v159
	v_pk_fma_f32 v[70:71], v[102:103], s[78:79], v[70:71] op_sel_hi:[1,0,1]
	v_pk_fma_f32 v[68:69], v[100:101], s[78:79], v[68:69] op_sel_hi:[1,0,1]
	v_lshl_add_u64 v[72:73], v[72:73], 2, s[88:89]
	global_store_dwordx4 v[72:73], v[68:71], off
	s_nop 1
	v_sub_f32_e32 v69, v93, v118
	v_sub_f32_e32 v68, v92, v118
	v_sub_f32_e32 v71, v95, v118
	v_sub_f32_e32 v70, v94, v118
	v_pk_mul_f32 v[70:71], v[118:119], v[70:71] op_sel:[1,0]
	v_pk_mul_f32 v[68:69], v[118:119], v[68:69] op_sel:[1,0]
	v_pk_fma_f32 v[66:67], v[188:189], v[70:71], v[66:67]
	v_pk_fma_f32 v[64:65], v[190:191], v[68:69], v[64:65]
	v_add_u32_e32 v68, 0x58010, v148
	v_mov_b32_e32 v69, v159
	v_pk_fma_f32 v[66:67], v[98:99], s[78:79], v[66:67] op_sel_hi:[1,0,1]
	v_pk_fma_f32 v[64:65], v[96:97], s[78:79], v[64:65] op_sel_hi:[1,0,1]
	v_lshl_add_u64 v[68:69], v[68:69], 2, s[88:89]
	global_store_dwordx4 v[68:69], v[64:67], off
	global_load_dwordx4 v[64:67], v[150:151], off offset:512
	v_or_b32_e32 v119, 0x80, v158
	v_add_u32_e32 v72, v202, v119
	v_mov_b32_e32 v73, v159
	v_lshl_add_u64 v[72:73], v[72:73], 2, s[90:91]
	v_or_b32_e32 v118, 0x90, v158
	v_add_u32_e32 v158, v202, v118
	s_waitcnt vmcnt(0)
;     template <bool LN, int BJ> DI void load_gb(unsigned col0, f32x4 (&gv)[2], f32x4 (&bv)[2]) const {
; #pragma unroll
;         for (int n = 0; n < 2; ++n) {
;             if (LN) { gv[n] = *(const f32x4*)(gam + col0 + BJ * HALF + n * 16) * ALPHA; bv[n] = *(const f32x4*)(bet + col0 + BJ * HALF + n * 16) * ALPHA; }
;             else { gv[n] = (f32x4){ALPHA, ALPHA, ALPHA, ALPHA}; bv[n] = (f32x4){0.f, 0.f, 0.f, 0.f}; }
;         }
;     }
;     template <bool LN> DI void run(const f32x4 (&acc)[2][2][4][2], const Unit& u, int wr, int wc, int fr, int fq) const {
;         const unsigned row0 = u.pm * BM + wr * 64 + fr, col0 = u.pn * BM + wc * 32 + 4 * fq;
;         f32x4 gv[2], bv[2];
;         load_gb<LN, 0>(col0, gv, bv);
;         batch<LN, 0, 0, 4>(acc, row0, col0, gv, bv);
;         batch<LN, 0, 4, 8>(acc, row0, col0, gv, bv);
;         batch<LN, 0, 8, 12>(acc, row0, col0, gv, bv);
;         batch<LN, 0, 12, 16>(acc, row0, col0, gv, bv);
;         load_gb<LN, 1>(col0, gv, bv);
;         batch<LN, 1, 0, 8>(acc, row0, col0, gv, bv);
;         batch<LN, 1, 8, 16>(acc, row0, col0, gv, bv);
	v_pk_mul_f32 v[96:97], v[66:67], s[78:79] op_sel_hi:[1,0]
	v_pk_mul_f32 v[98:99], v[64:65], s[78:79] op_sel_hi:[1,0]
	global_load_dwordx4 v[68:71], v[152:153], off offset:512
	global_load_dwordx4 v[64:67], v[150:151], off offset:576
	global_load_dwordx2 v[138:139], v[154:155], off
	global_load_dwordx4 v[126:129], v[72:73], off
	v_lshl_add_u64 v[72:73], v[158:159], 2, s[90:91]
	v_add_u32_e32 v158, v149, v119
	s_waitcnt vmcnt(0)
	v_pk_mul_f32 v[92:93], v[66:67], s[78:79] op_sel_hi:[1,0]
	v_pk_mul_f32 v[94:95], v[64:65], s[78:79] op_sel_hi:[1,0]
	global_load_dwordx4 v[64:67], v[152:153], off offset:576
	global_load_dwordx4 v[130:133], v[72:73], off
	global_load_dwordx2 v[112:113], v[186:187], off
	v_lshl_add_u64 v[72:73], v[158:159], 2, s[90:91]
	global_load_dwordx4 v[134:137], v[72:73], off
	v_add_u32_e32 v158, v149, v118
	v_lshl_add_u64 v[72:73], v[158:159], 2, s[90:91]
	global_load_dwordx4 v[88:91], v[72:73], off
	global_load_dwordx2 v[102:103], v[120:121], off
	v_add_u32_e32 v158, v124, v119
	v_lshl_add_u64 v[72:73], v[158:159], 2, s[90:91]
	global_load_dwordx4 v[84:87], v[72:73], off
	v_add_u32_e32 v158, v124, v118
	v_lshl_add_u64 v[72:73], v[158:159], 2, s[90:91]
	global_load_dwordx4 v[80:83], v[72:73], off
	global_load_dwordx2 v[100:101], v[122:123], off
	v_add_u32_e32 v158, v125, v119
	v_lshl_add_u64 v[72:73], v[158:159], 2, s[90:91]
	global_load_dwordx4 v[76:79], v[72:73], off
	v_add_u32_e32 v158, v125, v118
	v_lshl_add_u64 v[72:73], v[158:159], 2, s[90:91]
	global_load_dwordx4 v[72:75], v[72:73], off
	v_sub_f32_e32 v121, v127, v138
	v_sub_f32_e32 v120, v126, v138
	v_sub_f32_e32 v123, v129, v138
	v_sub_f32_e32 v122, v128, v138
	v_pk_mul_f32 v[122:123], v[138:139], v[122:123] op_sel:[1,0]
	v_pk_mul_f32 v[120:121], v[138:139], v[120:121] op_sel:[1,0]
	v_or_b32_e32 v158, 0x80, v148
	v_pk_fma_f32 v[60:61], v[98:99], v[120:121], v[60:61]
	v_pk_fma_f32 v[62:63], v[96:97], v[122:123], v[62:63]
	v_pk_fma_f32 v[60:61], v[68:69], s[78:79], v[60:61] op_sel_hi:[1,0,1]
	v_pk_fma_f32 v[62:63], v[70:71], s[78:79], v[62:63] op_sel_hi:[1,0,1]
	v_lshl_add_u64 v[120:121], v[158:159], 2, s[88:89]
	global_store_dwordx4 v[120:121], v[60:63], off
	v_or_b32_e32 v158, 0x90, v148
	s_waitcnt vmcnt(0)
	v_sub_f32_e32 v61, v131, v138
	v_sub_f32_e32 v60, v130, v138
	v_sub_f32_e32 v63, v133, v138
	v_sub_f32_e32 v62, v132, v138
	v_pk_mul_f32 v[62:63], v[138:139], v[62:63] op_sel:[1,0]
	v_pk_mul_f32 v[60:61], v[138:139], v[60:61] op_sel:[1,0]
	v_pk_fma_f32 v[58:59], v[92:93], v[62:63], v[58:59]
	v_pk_fma_f32 v[56:57], v[94:95], v[60:61], v[56:57]
	v_pk_fma_f32 v[58:59], v[66:67], s[78:79], v[58:59] op_sel_hi:[1,0,1]
	v_pk_fma_f32 v[56:57], v[64:65], s[78:79], v[56:57] op_sel_hi:[1,0,1]
	v_lshl_add_u64 v[60:61], v[158:159], 2, s[88:89]
	global_store_dwordx4 v[60:61], v[56:59], off
	v_add_u32_e32 v158, 0x8080, v148
	s_nop 0
	v_sub_f32_e32 v57, v135, v112
	v_sub_f32_e32 v56, v134, v112
	v_sub_f32_e32 v59, v137, v112
	v_sub_f32_e32 v58, v136, v112
	v_pk_mul_f32 v[58:59], v[112:113], v[58:59] op_sel:[1,0]
	v_pk_mul_f32 v[56:57], v[112:113], v[56:57] op_sel:[1,0]
	v_pk_fma_f32 v[54:55], v[96:97], v[58:59], v[54:55]
	v_pk_fma_f32 v[52:53], v[98:99], v[56:57], v[52:53]
	v_pk_fma_f32 v[54:55], v[70:71], s[78:79], v[54:55] op_sel_hi:[1,0,1]
	v_pk_fma_f32 v[52:53], v[68:69], s[78:79], v[52:53] op_sel_hi:[1,0,1]
	v_lshl_add_u64 v[56:57], v[158:159], 2, s[88:89]
	global_store_dwordx4 v[56:57], v[52:55], off
	v_add_u32_e32 v158, 0x8090, v148
	s_nop 0
	v_sub_f32_e32 v53, v89, v112
	v_sub_f32_e32 v52, v88, v112
	v_sub_f32_e32 v55, v91, v112
	v_sub_f32_e32 v54, v90, v112
	v_pk_mul_f32 v[54:55], v[112:113], v[54:55] op_sel:[1,0]
	v_pk_mul_f32 v[52:53], v[112:113], v[52:53] op_sel:[1,0]
	v_pk_fma_f32 v[50:51], v[92:93], v[54:55], v[50:51]
	v_pk_fma_f32 v[48:49], v[94:95], v[52:53], v[48:49]
	v_pk_fma_f32 v[50:51], v[66:67], s[78:79], v[50:51] op_sel_hi:[1,0,1]
	v_pk_fma_f32 v[48:49], v[64:65], s[78:79], v[48:49] op_sel_hi:[1,0,1]
	v_lshl_add_u64 v[52:53], v[158:159], 2, s[88:89]
	global_store_dwordx4 v[52:53], v[48:51], off
	v_add_u32_e32 v158, 0x10080, v148
	s_nop 0
	v_sub_f32_e32 v49, v85, v102
	v_sub_f32_e32 v48, v84, v102
	v_sub_f32_e32 v51, v87, v102
	v_sub_f32_e32 v50, v86, v102
	v_pk_mul_f32 v[50:51], v[102:103], v[50:51] op_sel:[1,0]
	v_pk_mul_f32 v[48:49], v[102:103], v[48:49] op_sel:[1,0]
	v_pk_fma_f32 v[46:47], v[96:97], v[50:51], v[46:47]
	v_pk_fma_f32 v[44:45], v[98:99], v[48:49], v[44:45]
	v_pk_fma_f32 v[46:47], v[70:71], s[78:79], v[46:47] op_sel_hi:[1,0,1]
	v_pk_fma_f32 v[44:45], v[68:69], s[78:79], v[44:45] op_sel_hi:[1,0,1]
	v_lshl_add_u64 v[48:49], v[158:159], 2, s[88:89]
	global_store_dwordx4 v[48:49], v[44:47], off
	v_add_u32_e32 v158, 0x10090, v148
	s_nop 0
	v_sub_f32_e32 v45, v81, v102
	v_sub_f32_e32 v44, v80, v102
	v_sub_f32_e32 v47, v83, v102
	v_sub_f32_e32 v46, v82, v102
	v_pk_mul_f32 v[46:47], v[102:103], v[46:47] op_sel:[1,0]
	v_pk_mul_f32 v[44:45], v[102:103], v[44:45] op_sel:[1,0]
	v_pk_fma_f32 v[42:43], v[92:93], v[46:47], v[42:43]
	v_pk_fma_f32 v[40:41], v[94:95], v[44:45], v[40:41]
	v_pk_fma_f32 v[42:43], v[66:67], s[78:79], v[42:43] op_sel_hi:[1,0,1]
	v_pk_fma_f32 v[40:41], v[64:65], s[78:79], v[40:41] op_sel_hi:[1,0,1]
	v_lshl_add_u64 v[44:45], v[158:159], 2, s[88:89]
	global_store_dwordx4 v[44:45], v[40:43], off
	v_add_u32_e32 v158, 0x18080, v148
	s_nop 0
	v_sub_f32_e32 v41, v77, v100
	v_sub_f32_e32 v40, v76, v100
	v_sub_f32_e32 v43, v79, v100
	v_sub_f32_e32 v42, v78, v100
	v_pk_mul_f32 v[42:43], v[100:101], v[42:43] op_sel:[1,0]
	v_pk_mul_f32 v[40:41], v[100:101], v[40:41] op_sel:[1,0]
	v_pk_fma_f32 v[38:39], v[96:97], v[42:43], v[38:39]
;     template <bool LN, int BJ, int LO, int HI> DI void batch(const f32x4 (&acc)[2][2][4][2], unsigned row0, unsigned col0, const f32x4 (&gv)[2], const f32x4 (&bv)[2]) const {
;         f32x4 r[HI - LO]; float mean[(HI - LO) / 2], rstd[(HI - LO) / 2];
; #pragma unroll
;         for (int i = LO; i < HI; ++i) { const int ai = i >> 3, m = (i >> 1) & 3, n = i & 1; const unsigned row = row0 + ai * HALF + m * 16;
;             if (n == 0) { mean[(i - LO) >> 1] = 0.f; rstd[(i - LO) >> 1] = 1.f;
;                 if (LN) { const float2 st = *(const float2*)(stats + row * 2u); mean[(i - LO) >> 1] = st.x; rstd[(i - LO) >> 1] = st.y; } }
;             r[i - LO] = *(const f32x4*)(src + (row * (unsigned)DM + col0 + BJ * HALF + n * 16)); }
; #pragma unroll
;         for (int i = LO; i < HI; ++i) { const int ai = i >> 3, m = (i >> 1) & 3, n = i & 1; const unsigned row = row0 + ai * HALF + m * 16;
;             *(f32x4*)(Y + (row * (unsigned)DM + col0 + BJ * HALF + n * 16)) = acc[ai][BJ][m][n] + ((r[i - LO] - mean[(i - LO) >> 1]) * rstd[(i - LO) >> 1]) * gv[n] + bv[n]; }
;         __builtin_amdgcn_sched_barrier(0);
;     }
;     template <bool LN, int BJ> DI void load_gb(unsigned col0, f32x4 (&gv)[2], f32x4 (&bv)[2]) const {
; #pragma unroll
;         for (int n = 0; n < 2; ++n) {
;             if (LN) { gv[n] = *(const f32x4*)(gam + col0 + BJ * HALF + n * 16) * ALPHA; bv[n] = *(const f32x4*)(bet + col0 + BJ * HALF + n * 16) * ALPHA; }
;             else { gv[n] = (f32x4){ALPHA, ALPHA, ALPHA, ALPHA}; bv[n] = (f32x4){0.f, 0.f, 0.f, 0.f}; }
;         }
;     }
;     template <bool LN> DI void run(const f32x4 (&acc)[2][2][4][2], const Unit& u, int wr, int wc, int fr, int fq) const {
;         const unsigned row0 = u.pm * BM + wr * 64 + fr, col0 = u.pn * BM + wc * 32 + 4 * fq;
;         f32x4 gv[2], bv[2];
;         load_gb<LN, 0>(col0, gv, bv);
;         batch<LN, 0, 0, 4>(acc, row0, col0, gv, bv);
;         batch<LN, 0, 4, 8>(acc, row0, col0, gv, bv);
;         batch<LN, 0, 8, 12>(acc, row0, col0, gv, bv);
;         batch<LN, 0, 12, 16>(acc, row0, col0, gv, bv);
;         load_gb<LN, 1>(col0, gv, bv);
;         batch<LN, 1, 0, 8>(acc, row0, col0, gv, bv);
;         batch<LN, 1, 8, 16>(acc, row0, col0, gv, bv);
	v_pk_fma_f32 v[36:37], v[98:99], v[40:41], v[36:37]
	v_pk_fma_f32 v[38:39], v[70:71], s[78:79], v[38:39] op_sel_hi:[1,0,1]
	v_pk_fma_f32 v[36:37], v[68:69], s[78:79], v[36:37] op_sel_hi:[1,0,1]
	v_lshl_add_u64 v[40:41], v[158:159], 2, s[88:89]
	global_store_dwordx4 v[40:41], v[36:39], off
	v_add_u32_e32 v158, 0x18090, v148
	s_nop 0
	v_sub_f32_e32 v37, v73, v100
	v_sub_f32_e32 v36, v72, v100
	v_sub_f32_e32 v39, v75, v100
	v_sub_f32_e32 v38, v74, v100
	v_pk_mul_f32 v[38:39], v[100:101], v[38:39] op_sel:[1,0]
	v_pk_mul_f32 v[36:37], v[100:101], v[36:37] op_sel:[1,0]
	v_pk_fma_f32 v[34:35], v[92:93], v[38:39], v[34:35]
	v_pk_fma_f32 v[32:33], v[94:95], v[36:37], v[32:33]
	v_pk_fma_f32 v[34:35], v[66:67], s[78:79], v[34:35] op_sel_hi:[1,0,1]
	v_pk_fma_f32 v[32:33], v[64:65], s[78:79], v[32:33] op_sel_hi:[1,0,1]
	v_lshl_add_u64 v[36:37], v[158:159], 2, s[88:89]
	global_store_dwordx4 v[36:37], v[32:35], off
	v_add_u32_e32 v158, v114, v119
	s_nop 0
	v_lshl_add_u64 v[32:33], v[158:159], 2, s[90:91]
	global_load_dwordx2 v[62:63], v[104:105], off
	global_load_dwordx4 v[54:57], v[32:33], off
	v_add_u32_e32 v158, v114, v118
	v_lshl_add_u64 v[32:33], v[158:159], 2, s[90:91]
	global_load_dwordx4 v[58:61], v[32:33], off
	global_load_dwordx2 v[52:53], v[106:107], off
	v_add_u32_e32 v158, v115, v119
	v_lshl_add_u64 v[32:33], v[158:159], 2, s[90:91]
	global_load_dwordx4 v[72:75], v[32:33], off
	v_add_u32_e32 v158, v115, v118
	v_lshl_add_u64 v[32:33], v[158:159], 2, s[90:91]
	global_load_dwordx4 v[76:79], v[32:33], off
	global_load_dwordx2 v[50:51], v[108:109], off
	v_add_u32_e32 v158, v116, v119
	v_lshl_add_u64 v[32:33], v[158:159], 2, s[90:91]
	global_load_dwordx4 v[44:47], v[32:33], off
	v_add_u32_e32 v158, v116, v118
	v_lshl_add_u64 v[32:33], v[158:159], 2, s[90:91]
	global_load_dwordx4 v[40:43], v[32:33], off
	global_load_dwordx2 v[48:49], v[110:111], off
	v_add_u32_e32 v158, v117, v119
	v_lshl_add_u64 v[32:33], v[158:159], 2, s[90:91]
	global_load_dwordx4 v[36:39], v[32:33], off
	v_add_u32_e32 v158, v117, v118
	v_lshl_add_u64 v[32:33], v[158:159], 2, s[90:91]
	global_load_dwordx4 v[32:35], v[32:33], off
	v_add_u32_e32 v158, 0x40080, v148
	s_waitcnt vmcnt(0)
; template <class Epi>
; DI void gemm_phase(LAS unsigned char* lds, const Gemm g, const StaticOrder& S, const Epi& E) {
;     ...
;         if (!has_next) break;
;     template <bool LN, int BJ, int LO, int HI> DI void batch(const f32x4 (&acc)[2][2][4][2], unsigned row0, unsigned col0, const f32x4 (&gv)[2], const f32x4 (&bv)[2]) const {
;         f32x4 r[HI - LO]; float mean[(HI - LO) / 2], rstd[(HI - LO) / 2];
; #pragma unroll
;         for (int i = LO; i < HI; ++i) { const int ai = i >> 3, m = (i >> 1) & 3, n = i & 1; const unsigned row = row0 + ai * HALF + m * 16;
;             if (n == 0) { mean[(i - LO) >> 1] = 0.f; rstd[(i - LO) >> 1] = 1.f;
;                 if (LN) { const float2 st = *(const float2*)(stats + row * 2u); mean[(i - LO) >> 1] = st.x; rstd[(i - LO) >> 1] = st.y; } }
;             r[i - LO] = *(const f32x4*)(src + (row * (unsigned)DM + col0 + BJ * HALF + n * 16)); }
; #pragma unroll
;         for (int i = LO; i < HI; ++i) { const int ai = i >> 3, m = (i >> 1) & 3, n = i & 1; const unsigned row = row0 + ai * HALF + m * 16;
;             *(f32x4*)(Y + (row * (unsigned)DM + col0 + BJ * HALF + n * 16)) = acc[ai][BJ][m][n] + ((r[i - LO] - mean[(i - LO) >> 1]) * rstd[(i - LO) >> 1]) * gv[n] + bv[n]; }
;         __builtin_amdgcn_sched_barrier(0);
;     }
;     template <bool LN, int BJ> DI void load_gb(unsigned col0, f32x4 (&gv)[2], f32x4 (&bv)[2]) const {
; #pragma unroll
;         for (int n = 0; n < 2; ++n) {
;             if (LN) { gv[n] = *(const f32x4*)(gam + col0 + BJ * HALF + n * 16) * ALPHA; bv[n] = *(const f32x4*)(bet + col0 + BJ * HALF + n * 16) * ALPHA; }
;             else { gv[n] = (f32x4){ALPHA, ALPHA, ALPHA, ALPHA}; bv[n] = (f32x4){0.f, 0.f, 0.f, 0.f}; }
;         }
;     }
;     template <bool LN> DI void run(const f32x4 (&acc)[2][2][4][2], const Unit& u, int wr, int wc, int fr, int fq) const {
;         const unsigned row0 = u.pm * BM + wr * 64 + fr, col0 = u.pn * BM + wc * 32 + 4 * fq;
;         f32x4 gv[2], bv[2];
;         load_gb<LN, 0>(col0, gv, bv);
;         batch<LN, 0, 0, 4>(acc, row0, col0, gv, bv);
;         batch<LN, 0, 4, 8>(acc, row0, col0, gv, bv);
;         batch<LN, 0, 8, 12>(acc, row0, col0, gv, bv);
;         batch<LN, 0, 12, 16>(acc, row0, col0, gv, bv);
;         load_gb<LN, 1>(col0, gv, bv);
;         batch<LN, 1, 0, 8>(acc, row0, col0, gv, bv);
;         batch<LN, 1, 8, 16>(acc, row0, col0, gv, bv);
	v_sub_f32_e32 v55, v55, v62
	v_sub_f32_e32 v54, v54, v62
	v_sub_f32_e32 v57, v57, v62
	v_sub_f32_e32 v56, v56, v62
	v_pk_mul_f32 v[56:57], v[62:63], v[56:57] op_sel:[1,0]
	v_pk_mul_f32 v[54:55], v[62:63], v[54:55] op_sel:[1,0]
	v_pk_fma_f32 v[30:31], v[96:97], v[56:57], v[30:31]
	v_pk_fma_f32 v[28:29], v[98:99], v[54:55], v[28:29]
	v_pk_fma_f32 v[30:31], v[70:71], s[78:79], v[30:31] op_sel_hi:[1,0,1]
	v_pk_fma_f32 v[28:29], v[68:69], s[78:79], v[28:29] op_sel_hi:[1,0,1]
	v_lshl_add_u64 v[54:55], v[158:159], 2, s[88:89]
	global_store_dwordx4 v[54:55], v[28:31], off
	v_add_u32_e32 v158, 0x40090, v148
	s_nop 0
	v_sub_f32_e32 v29, v59, v62
	v_sub_f32_e32 v28, v58, v62
	v_sub_f32_e32 v31, v61, v62
	v_sub_f32_e32 v30, v60, v62
	v_pk_mul_f32 v[30:31], v[62:63], v[30:31] op_sel:[1,0]
	v_pk_mul_f32 v[28:29], v[62:63], v[28:29] op_sel:[1,0]
	v_pk_fma_f32 v[26:27], v[92:93], v[30:31], v[26:27]
	v_pk_fma_f32 v[24:25], v[94:95], v[28:29], v[24:25]
	v_pk_fma_f32 v[26:27], v[66:67], s[78:79], v[26:27] op_sel_hi:[1,0,1]
	v_pk_fma_f32 v[24:25], v[64:65], s[78:79], v[24:25] op_sel_hi:[1,0,1]
	v_lshl_add_u64 v[28:29], v[158:159], 2, s[88:89]
	global_store_dwordx4 v[28:29], v[24:27], off
	v_add_u32_e32 v158, 0x48080, v148
	s_nop 0
	v_sub_f32_e32 v25, v73, v52
	v_sub_f32_e32 v24, v72, v52
	v_sub_f32_e32 v27, v75, v52
	v_sub_f32_e32 v26, v74, v52
	v_pk_mul_f32 v[26:27], v[52:53], v[26:27] op_sel:[1,0]
	v_pk_mul_f32 v[24:25], v[52:53], v[24:25] op_sel:[1,0]
	v_pk_fma_f32 v[22:23], v[96:97], v[26:27], v[22:23]
	v_pk_fma_f32 v[20:21], v[98:99], v[24:25], v[20:21]
	v_pk_fma_f32 v[22:23], v[70:71], s[78:79], v[22:23] op_sel_hi:[1,0,1]
	v_pk_fma_f32 v[20:21], v[68:69], s[78:79], v[20:21] op_sel_hi:[1,0,1]
	v_lshl_add_u64 v[24:25], v[158:159], 2, s[88:89]
	global_store_dwordx4 v[24:25], v[20:23], off
	v_add_u32_e32 v158, 0x48090, v148
	s_nop 0
	v_sub_f32_e32 v21, v77, v52
	v_sub_f32_e32 v20, v76, v52
	v_sub_f32_e32 v23, v79, v52
	v_sub_f32_e32 v22, v78, v52
	v_pk_mul_f32 v[22:23], v[52:53], v[22:23] op_sel:[1,0]
	v_pk_mul_f32 v[20:21], v[52:53], v[20:21] op_sel:[1,0]
	v_pk_fma_f32 v[18:19], v[92:93], v[22:23], v[18:19]
	v_pk_fma_f32 v[16:17], v[94:95], v[20:21], v[16:17]
	v_pk_fma_f32 v[18:19], v[66:67], s[78:79], v[18:19] op_sel_hi:[1,0,1]
	v_pk_fma_f32 v[16:17], v[64:65], s[78:79], v[16:17] op_sel_hi:[1,0,1]
	v_lshl_add_u64 v[20:21], v[158:159], 2, s[88:89]
	global_store_dwordx4 v[20:21], v[16:19], off
	v_add_u32_e32 v158, 0x50080, v148
	s_nop 0
	v_sub_f32_e32 v17, v45, v50
	v_sub_f32_e32 v16, v44, v50
	v_sub_f32_e32 v19, v47, v50
	v_sub_f32_e32 v18, v46, v50
	v_pk_mul_f32 v[18:19], v[50:51], v[18:19] op_sel:[1,0]
	v_pk_mul_f32 v[16:17], v[50:51], v[16:17] op_sel:[1,0]
	v_pk_fma_f32 v[14:15], v[96:97], v[18:19], v[14:15]
	v_pk_fma_f32 v[12:13], v[98:99], v[16:17], v[12:13]
	v_pk_fma_f32 v[14:15], v[70:71], s[78:79], v[14:15] op_sel_hi:[1,0,1]
	v_pk_fma_f32 v[12:13], v[68:69], s[78:79], v[12:13] op_sel_hi:[1,0,1]
	v_lshl_add_u64 v[16:17], v[158:159], 2, s[88:89]
	global_store_dwordx4 v[16:17], v[12:15], off
	v_add_u32_e32 v158, 0x50090, v148
	s_nop 0
	v_sub_f32_e32 v13, v41, v50
	v_sub_f32_e32 v12, v40, v50
	v_sub_f32_e32 v15, v43, v50
	v_sub_f32_e32 v14, v42, v50
	v_pk_mul_f32 v[14:15], v[50:51], v[14:15] op_sel:[1,0]
	v_pk_mul_f32 v[12:13], v[50:51], v[12:13] op_sel:[1,0]
	v_pk_fma_f32 v[10:11], v[92:93], v[14:15], v[10:11]
	v_pk_fma_f32 v[8:9], v[94:95], v[12:13], v[8:9]
	v_pk_fma_f32 v[10:11], v[66:67], s[78:79], v[10:11] op_sel_hi:[1,0,1]
	v_pk_fma_f32 v[8:9], v[64:65], s[78:79], v[8:9] op_sel_hi:[1,0,1]
	v_lshl_add_u64 v[12:13], v[158:159], 2, s[88:89]
	global_store_dwordx4 v[12:13], v[8:11], off
	v_add_u32_e32 v158, 0x58080, v148
	s_nop 0
	v_sub_f32_e32 v9, v37, v48
	v_sub_f32_e32 v8, v36, v48
	v_sub_f32_e32 v11, v39, v48
	v_sub_f32_e32 v10, v38, v48
	v_pk_mul_f32 v[10:11], v[48:49], v[10:11] op_sel:[1,0]
	v_pk_mul_f32 v[8:9], v[48:49], v[8:9] op_sel:[1,0]
	v_pk_fma_f32 v[6:7], v[96:97], v[10:11], v[6:7]
	v_pk_fma_f32 v[4:5], v[98:99], v[8:9], v[4:5]
	v_pk_fma_f32 v[6:7], v[70:71], s[78:79], v[6:7] op_sel_hi:[1,0,1]
	v_pk_fma_f32 v[4:5], v[68:69], s[78:79], v[4:5] op_sel_hi:[1,0,1]
	v_lshl_add_u64 v[8:9], v[158:159], 2, s[88:89]
	global_store_dwordx4 v[8:9], v[4:7], off
	v_add_u32_e32 v158, 0x58090, v148
	s_nop 0
	v_sub_f32_e32 v5, v33, v48
	v_sub_f32_e32 v4, v32, v48
	v_sub_f32_e32 v7, v35, v48
	v_sub_f32_e32 v6, v34, v48
	v_pk_mul_f32 v[6:7], v[48:49], v[6:7] op_sel:[1,0]
	v_pk_mul_f32 v[4:5], v[48:49], v[4:5] op_sel:[1,0]
	v_pk_fma_f32 v[2:3], v[92:93], v[6:7], v[2:3]
	v_pk_fma_f32 v[0:1], v[94:95], v[4:5], v[0:1]
	v_pk_fma_f32 v[2:3], v[66:67], s[78:79], v[2:3] op_sel_hi:[1,0,1]
	v_pk_fma_f32 v[0:1], v[64:65], s[78:79], v[0:1] op_sel_hi:[1,0,1]
	v_lshl_add_u64 v[4:5], v[158:159], 2, s[88:89]
	global_store_dwordx4 v[4:5], v[0:3], off
	s_and_b64 vcc, exec, s[6:7]
	s_mov_b32 s2, s37
	s_mov_b32 s3, s38
	s_mov_b64 s[18:19], s[10:11]
	s_mov_b64 s[16:17], s[8:9]
	v_readlane_b32 s33, v255, 39
	s_cbranch_vccz .LBB0_123
	s_waitcnt vmcnt(0)
	s_cmpk_gt_u32 s24, 0xff
	s_cbranch_scc1 .LBB0_138
	s_barrier

; #define PG8_STAGE(bufoff, gbase) do { _Pragma("unroll") for (int _i = 0; _i < 2; ++_i) \
;         __builtin_amdgcn_global_load_lds((const unsigned*)((const char*)(gbase) + voff[_i]), (LAS unsigned*)(lds + (bufoff) + ldsw + _i * 8192), 16, 0, 0); } while (0)
; #define PG8_LDA(dst, b, h) do { _Pragma("unroll") for (int m = 0; m < 4; ++m) _Pragma("unroll") for (int k = 0; k < 2; ++k) dst[m][k] = *(const LAS bf16x8*)(lds + PG8_SA(b, h) + aoff + m * 2048 + k * 1024); } while (0)
; #define PG8_LDB(dst, b, h) do { _Pragma("unroll") for (int n = 0; n < 2; ++n) _Pragma("unroll") for (int k = 0; k < 2; ++k) dst[n][k] = *(const LAS bf16x8*)(lds + PG8_SB(b, h) + boff + n * 2048 + k * 1024); } while (0)
; #define PG8_MMA(ai, bj, At, Bt) do { __builtin_amdgcn_s_setprio(1); _Pragma("unroll") for (int m = 0; m < 4; ++m) _Pragma("unroll") for (int n = 0; n < 2; ++n) _Pragma("unroll") for (int k = 0; k < 2; ++k) \
;         acc[ai][bj][m][n] = __builtin_amdgcn_mfma_f32_16x16x32_bf16(Bt[n][k], At[m][k], acc[ai][bj][m][n], 0, 0, 0); __builtin_amdgcn_s_setprio(0); } while (0)
; #define PG8_WAIT_L(n) asm volatile("s_waitcnt lgkmcnt(" #n ")" ::: "memory")
; #define PG8_BAR __builtin_amdgcn_s_barrier()
; #define PG8_SCHED __builtin_amdgcn_sched_barrier(0)
; template <class Epi>
; DI void gemm_phase(LAS unsigned char* lds, const Gemm g, const StaticOrder& S, const Epi& E) {
;     ...
;         const char* nA = has_next ? (const char*)g.A + (size_t)nxt.pm * tstep : cA; const char* nB = has_next ? (const char*)g.Bt + (size_t)nxt.pn * tstep : cB;
;         for (int t = 0; t < nt; t += 2) {
;             const bool last = (t == nt - 2);
;             const char* a1 = cA + (size_t)(t + 1) * kstep;
;             const char* a2 = last ? nA : cA + (size_t)(t + 2) * kstep; const char* b2 = last ? nB : cB + (size_t)(t + 2) * kstep;
;             const char* a3 = a2 + kstep; const char* b3 = b2 + kstep;
;             PG8_LDB(B0, 0, 0); PG8_SCHED; PG8_LDA(At, 0, 0); PG8_STAGE(PG8_SA(1, 1), a1 + hstep);
;             PG8_WAIT_L(8); PG8_BAR; PG8_WAIT_L(0); PG8_MMA(0, 0, At, B0); PG8_BAR; PG8_SCHED;
;             PG8_LDB(B1, 0, 1); PG8_STAGE(PG8_SB(0, 0), b2);
;             PG8_BAR; PG8_WAIT_L(0); PG8_MMA(0, 1, At, B1); PG8_BAR;
;             PG8_LDA(At, 0, 1); PG8_STAGE(PG8_SA(0, 0), a2);
;             PG8_BAR; PG8_WAIT_L(0); PG8_MMA(1, 0, At, B0); PG8_BAR; PG8_SCHED;
.LBB0_202:
	s_add_u32 s18, s8, 0xfff80080
	s_addc_u32 s19, s9, -1
	s_add_i32 s37, 0, 0x10000
	v_add_u32_e32 v140, s37, v187
	s_waitcnt lgkmcnt(0)
	ds_read_b128 v[128:131], v140
	ds_read_b128 v[132:135], v140 offset:1024
	ds_read_b128 v[136:139], v140 offset:2048
	ds_read_b128 v[190:193], v140 offset:3072
	s_cmp_eq_u32 s36, 28
	s_cselect_b32 s21, s4, s19
	s_cselect_b32 s20, s5, s18
	s_cselect_b32 s19, s11, s35
	s_cselect_b32 s18, s13, s33
	v_lshl_add_u64 v[140:141], s[8:9], 0, v[150:151]
	s_add_i32 m0, s26, 0xc000
	ds_read_b128 v[194:197], v189
	ds_read_b128 v[198:201], v189 offset:1024
	ds_read_b128 v[202:205], v189 offset:2048
	ds_read_b128 v[206:209], v189 offset:3072
	ds_read_b128 v[210:213], v189 offset:4096
	ds_read_b128 v[214:217], v189 offset:5120
	ds_read_b128 v[226:229], v189 offset:6144
	ds_read_b128 v[230:233], v189 offset:7168
	global_load_lds_dwordx4 v[140:141], off
	v_lshl_add_u64 v[140:141], s[8:9], 0, v[152:153]
	s_add_i32 m0, s26, 0xe000
	s_nop 0
	global_load_lds_dwordx4 v[140:141], off
	s_waitcnt lgkmcnt(8)
	s_setprio 1
	s_barrier
	s_waitcnt lgkmcnt(0)
	v_mfma_f32_16x16x32_bf16 v[124:127], v[128:131], v[194:197], v[124:127]
	v_mfma_f32_16x16x32_bf16 v[120:123], v[136:139], v[194:197], v[120:123]
	v_mfma_f32_16x16x32_bf16 v[108:111], v[128:131], v[202:205], v[108:111]
	v_mfma_f32_16x16x32_bf16 v[104:107], v[136:139], v[202:205], v[104:107]
	v_mfma_f32_16x16x32_bf16 v[92:95], v[128:131], v[210:213], v[92:95]
	v_mfma_f32_16x16x32_bf16 v[88:91], v[136:139], v[210:213], v[88:91]
	v_mfma_f32_16x16x32_bf16 v[76:79], v[128:131], v[226:229], v[76:79]
	v_mfma_f32_16x16x32_bf16 v[72:75], v[136:139], v[226:229], v[72:75]
	v_mfma_f32_16x16x32_bf16 v[124:127], v[132:135], v[198:201], v[124:127]
	v_mfma_f32_16x16x32_bf16 v[120:123], v[190:193], v[198:201], v[120:123]
	v_mfma_f32_16x16x32_bf16 v[108:111], v[132:135], v[206:209], v[108:111]
	v_mfma_f32_16x16x32_bf16 v[104:107], v[190:193], v[206:209], v[104:107]
	v_mfma_f32_16x16x32_bf16 v[92:95], v[132:135], v[214:217], v[92:95]
	v_mfma_f32_16x16x32_bf16 v[88:91], v[190:193], v[214:217], v[88:91]
	v_mfma_f32_16x16x32_bf16 v[76:79], v[132:135], v[230:233], v[76:79]
	v_mfma_f32_16x16x32_bf16 v[72:75], v[190:193], v[230:233], v[72:75]
	s_setprio 0
	s_barrier
	s_add_i32 s40, 0, 0x14000
	v_add_u32_e32 v140, s40, v187
	s_add_i32 s37, s37, s25
	ds_read_b128 v[234:237], v140
	ds_read_b128 v[238:241], v140 offset:1024
	ds_read_b128 v[242:245], v140 offset:2048
	ds_read_b128 v[246:249], v140 offset:3072
	v_lshl_add_u64 v[140:141], s[18:19], 0, v[144:145]
	s_mov_b32 m0, s37
	v_lshl_add_u64 v[154:155], s[18:19], 0, v[142:143]
	global_load_lds_dwordx4 v[140:141], off
	s_add_i32 m0, s37, 0x2000
	s_nop 0
	global_load_lds_dwordx4 v[154:155], off
	s_setprio 1
	s_barrier
	s_waitcnt lgkmcnt(0)
	v_mfma_f32_16x16x32_bf16 v[116:119], v[234:237], v[194:197], v[116:119]
	v_mfma_f32_16x16x32_bf16 v[112:115], v[242:245], v[194:197], v[112:115]
	v_mfma_f32_16x16x32_bf16 v[100:103], v[234:237], v[202:205], v[100:103]
	v_mfma_f32_16x16x32_bf16 v[96:99], v[242:245], v[202:205], v[96:99]
	v_mfma_f32_16x16x32_bf16 v[84:87], v[234:237], v[210:213], v[84:87]
	v_mfma_f32_16x16x32_bf16 v[80:83], v[242:245], v[210:213], v[80:83]
	v_mfma_f32_16x16x32_bf16 v[68:71], v[234:237], v[226:229], v[68:71]
	v_mfma_f32_16x16x32_bf16 v[64:67], v[242:245], v[226:229], v[64:67]
	v_mfma_f32_16x16x32_bf16 v[116:119], v[238:241], v[198:201], v[116:119]
	v_mfma_f32_16x16x32_bf16 v[112:115], v[246:249], v[198:201], v[112:115]
	v_mfma_f32_16x16x32_bf16 v[100:103], v[238:241], v[206:209], v[100:103]
	v_mfma_f32_16x16x32_bf16 v[96:99], v[246:249], v[206:209], v[96:99]
	v_mfma_f32_16x16x32_bf16 v[84:87], v[238:241], v[214:217], v[84:87]
	v_mfma_f32_16x16x32_bf16 v[80:83], v[246:249], v[214:217], v[80:83]
	v_mfma_f32_16x16x32_bf16 v[68:71], v[238:241], v[230:233], v[68:71]
	v_mfma_f32_16x16x32_bf16 v[64:67], v[246:249], v[230:233], v[64:67]
	s_setprio 0
	s_mov_b32 m0, s26
	v_lshl_add_u64 v[218:219], s[20:21], 0, v[144:145]
	s_barrier
	ds_read_b128 v[194:197], v189 offset:16384
	ds_read_b128 v[198:201], v189 offset:17408
	ds_read_b128 v[202:205], v189 offset:18432
	ds_read_b128 v[206:209], v189 offset:19456
	ds_read_b128 v[210:213], v189 offset:20480
	ds_read_b128 v[214:217], v189 offset:21504
	ds_read_b128 v[226:229], v189 offset:22528
	ds_read_b128 v[230:233], v189 offset:23552
	global_load_lds_dwordx4 v[218:219], off
	v_lshl_add_u64 v[250:251], s[20:21], 0, v[142:143]
	s_mov_b32 m0, s27
	s_nop 0
	global_load_lds_dwordx4 v[250:251], off
	s_setprio 1
	s_barrier
	s_waitcnt lgkmcnt(0)
	v_mfma_f32_16x16x32_bf16 v[60:63], v[128:131], v[194:197], v[60:63]
	v_mfma_f32_16x16x32_bf16 v[56:59], v[136:139], v[194:197], v[56:59]
	v_mfma_f32_16x16x32_bf16 v[44:47], v[128:131], v[202:205], v[44:47]
	v_mfma_f32_16x16x32_bf16 v[40:43], v[136:139], v[202:205], v[40:43]
	v_mfma_f32_16x16x32_bf16 v[28:31], v[128:131], v[210:213], v[28:31]
	v_mfma_f32_16x16x32_bf16 v[24:27], v[136:139], v[210:213], v[24:27]
	v_mfma_f32_16x16x32_bf16 v[12:15], v[128:131], v[226:229], v[12:15]
	v_mfma_f32_16x16x32_bf16 v[8:11], v[136:139], v[226:229], v[8:11]
	v_mfma_f32_16x16x32_bf16 v[60:63], v[132:135], v[198:201], v[60:63]
	v_mfma_f32_16x16x32_bf16 v[56:59], v[190:193], v[198:201], v[56:59]
	v_mfma_f32_16x16x32_bf16 v[44:47], v[132:135], v[206:209], v[44:47]
	v_mfma_f32_16x16x32_bf16 v[40:43], v[190:193], v[206:209], v[40:43]
	v_mfma_f32_16x16x32_bf16 v[28:31], v[132:135], v[214:217], v[28:31]
	v_mfma_f32_16x16x32_bf16 v[24:27], v[190:193], v[214:217], v[24:27]
	v_mfma_f32_16x16x32_bf16 v[12:15], v[132:135], v[230:233], v[12:15]
	v_mfma_f32_16x16x32_bf16 v[8:11], v[190:193], v[230:233], v[8:11]
	s_setprio 0
	s_barrier
; #define PG8_STAGE(bufoff, gbase) do { _Pragma("unroll") for (int _i = 0; _i < 2; ++_i) \
;         __builtin_amdgcn_global_load_lds((const unsigned*)((const char*)(gbase) + voff[_i]), (LAS unsigned*)(lds + (bufoff) + ldsw + _i * 8192), 16, 0, 0); } while (0)
; #define PG8_LDA(dst, b, h) do { _Pragma("unroll") for (int m = 0; m < 4; ++m) _Pragma("unroll") for (int k = 0; k < 2; ++k) dst[m][k] = *(const LAS bf16x8*)(lds + PG8_SA(b, h) + aoff + m * 2048 + k * 1024); } while (0)
; #define PG8_LDB(dst, b, h) do { _Pragma("unroll") for (int n = 0; n < 2; ++n) _Pragma("unroll") for (int k = 0; k < 2; ++k) dst[n][k] = *(const LAS bf16x8*)(lds + PG8_SB(b, h) + boff + n * 2048 + k * 1024); } while (0)
; #define PG8_MMA(ai, bj, At, Bt) do { __builtin_amdgcn_s_setprio(1); _Pragma("unroll") for (int m = 0; m < 4; ++m) _Pragma("unroll") for (int n = 0; n < 2; ++n) _Pragma("unroll") for (int k = 0; k < 2; ++k) \
;         acc[ai][bj][m][n] = __builtin_amdgcn_mfma_f32_16x16x32_bf16(Bt[n][k], At[m][k], acc[ai][bj][m][n], 0, 0, 0); __builtin_amdgcn_s_setprio(0); } while (0)
; #define PG8_WAIT_V(n) asm volatile("s_waitcnt vmcnt(" #n ")" ::: "memory")
; #define PG8_WAIT_L(n) asm volatile("s_waitcnt lgkmcnt(" #n ")" ::: "memory")
; #define PG8_BAR __builtin_amdgcn_s_barrier()
; #define PG8_SCHED __builtin_amdgcn_sched_barrier(0)
; template <class Epi>
; DI void gemm_phase(LAS unsigned char* lds, const Gemm g, const StaticOrder& S, const Epi& E) {
;     ...
;             PG8_STAGE(PG8_SB(0, 1), b2 + hstep);
;             PG8_WAIT_V(6); PG8_BAR; PG8_MMA(1, 1, At, B1); PG8_BAR;
;             PG8_LDB(B0, 1, 0); PG8_SCHED; PG8_LDA(At, 1, 0); PG8_STAGE(PG8_SA(0, 1), a2 + hstep);
;             PG8_WAIT_L(8); PG8_BAR; PG8_WAIT_L(0); PG8_MMA(0, 0, At, B0); PG8_BAR; PG8_SCHED;
;             PG8_LDB(B1, 1, 1); PG8_STAGE(PG8_SB(1, 0), b3);
;             PG8_BAR; PG8_WAIT_L(0); PG8_MMA(0, 1, At, B1); PG8_BAR;
;             PG8_LDA(At, 1, 1); PG8_STAGE(PG8_SA(1, 0), a3);
;             PG8_BAR; PG8_WAIT_L(0); PG8_MMA(1, 0, At, B0); PG8_BAR; PG8_SCHED;
	s_add_u32 s38, s18, 0x80000
	s_addc_u32 s39, s19, 0
	s_add_i32 s37, s40, s25
	v_lshl_add_u64 v[128:129], s[38:39], 0, v[144:145]
	s_mov_b32 m0, s37
	s_nop 0
	global_load_lds_dwordx4 v[128:129], off
	v_lshl_add_u64 v[128:129], s[38:39], 0, v[142:143]
	s_add_i32 m0, s37, 0x2000
	s_nop 0
	global_load_lds_dwordx4 v[128:129], off
	s_waitcnt vmcnt(6)
	s_setprio 1
	s_barrier
	v_mfma_f32_16x16x32_bf16 v[52:55], v[234:237], v[194:197], v[52:55]
	v_mfma_f32_16x16x32_bf16 v[48:51], v[242:245], v[194:197], v[48:51]
	v_mfma_f32_16x16x32_bf16 v[36:39], v[234:237], v[202:205], v[36:39]
	v_mfma_f32_16x16x32_bf16 v[32:35], v[242:245], v[202:205], v[32:35]
	v_mfma_f32_16x16x32_bf16 v[20:23], v[234:237], v[210:213], v[20:23]
	v_mfma_f32_16x16x32_bf16 v[16:19], v[242:245], v[210:213], v[16:19]
	v_mfma_f32_16x16x32_bf16 v[4:7], v[234:237], v[226:229], v[4:7]
	v_mfma_f32_16x16x32_bf16 v[0:3], v[242:245], v[226:229], v[0:3]
	v_mfma_f32_16x16x32_bf16 v[52:55], v[238:241], v[198:201], v[52:55]
	v_mfma_f32_16x16x32_bf16 v[48:51], v[246:249], v[198:201], v[48:51]
	v_mfma_f32_16x16x32_bf16 v[36:39], v[238:241], v[206:209], v[36:39]
	v_mfma_f32_16x16x32_bf16 v[32:35], v[246:249], v[206:209], v[32:35]
	v_mfma_f32_16x16x32_bf16 v[20:23], v[238:241], v[214:217], v[20:23]
	v_mfma_f32_16x16x32_bf16 v[16:19], v[246:249], v[214:217], v[16:19]
	v_mfma_f32_16x16x32_bf16 v[4:7], v[238:241], v[230:233], v[4:7]
	v_mfma_f32_16x16x32_bf16 v[0:3], v[246:249], v[230:233], v[0:3]
	s_setprio 0
	s_add_i32 s37, 0, 0x18000
	v_add_u32_e32 v158, s37, v187
	s_barrier
	ds_read_b128 v[128:131], v158
	ds_read_b128 v[132:135], v158 offset:1024
	ds_read_b128 v[136:139], v158 offset:2048
	ds_read_b128 v[190:193], v158 offset:3072
	s_add_u32 s20, s20, 0x80000
	s_addc_u32 s21, s21, 0
	s_mov_b32 m0, s28
	v_lshl_add_u64 v[234:235], s[20:21], 0, v[144:145]
	ds_read_b128 v[194:197], v189 offset:32768
	ds_read_b128 v[198:201], v189 offset:33792
	ds_read_b128 v[202:205], v189 offset:34816
	ds_read_b128 v[206:209], v189 offset:35840
	ds_read_b128 v[210:213], v189 offset:36864
	ds_read_b128 v[214:217], v189 offset:37888
	ds_read_b128 v[226:229], v189 offset:38912
	ds_read_b128 v[230:233], v189 offset:39936
	global_load_lds_dwordx4 v[234:235], off
	v_lshl_add_u64 v[234:235], s[20:21], 0, v[142:143]
	s_mov_b32 m0, s29
	s_nop 0
	global_load_lds_dwordx4 v[234:235], off
	s_waitcnt lgkmcnt(8)
	s_setprio 1
	s_barrier
	s_waitcnt lgkmcnt(0)
	v_mfma_f32_16x16x32_bf16 v[124:127], v[128:131], v[194:197], v[124:127]
	v_mfma_f32_16x16x32_bf16 v[120:123], v[136:139], v[194:197], v[120:123]
	v_mfma_f32_16x16x32_bf16 v[108:111], v[128:131], v[202:205], v[108:111]
	v_mfma_f32_16x16x32_bf16 v[104:107], v[136:139], v[202:205], v[104:107]
	v_mfma_f32_16x16x32_bf16 v[92:95], v[128:131], v[210:213], v[92:95]
	v_mfma_f32_16x16x32_bf16 v[88:91], v[136:139], v[210:213], v[88:91]
	v_mfma_f32_16x16x32_bf16 v[76:79], v[128:131], v[226:229], v[76:79]
	v_mfma_f32_16x16x32_bf16 v[72:75], v[136:139], v[226:229], v[72:75]
	v_mfma_f32_16x16x32_bf16 v[124:127], v[132:135], v[198:201], v[124:127]
	v_mfma_f32_16x16x32_bf16 v[120:123], v[190:193], v[198:201], v[120:123]
	v_mfma_f32_16x16x32_bf16 v[108:111], v[132:135], v[206:209], v[108:111]
	v_mfma_f32_16x16x32_bf16 v[104:107], v[190:193], v[206:209], v[104:107]
	v_mfma_f32_16x16x32_bf16 v[92:95], v[132:135], v[214:217], v[92:95]
	v_mfma_f32_16x16x32_bf16 v[88:91], v[190:193], v[214:217], v[88:91]
	v_mfma_f32_16x16x32_bf16 v[76:79], v[132:135], v[230:233], v[76:79]
	v_mfma_f32_16x16x32_bf16 v[72:75], v[190:193], v[230:233], v[72:75]
	s_setprio 0
	s_barrier
	s_add_i32 s20, 0, 0x1c000
	s_add_i32 s21, s37, s25
	v_add_u32_e32 v158, s20, v187
	v_lshl_add_u64 v[140:141], v[140:141], 0, s[94:95]
	s_mov_b32 m0, s21
	ds_read_b128 v[234:237], v158
	ds_read_b128 v[238:241], v158 offset:1024
	ds_read_b128 v[242:245], v158 offset:2048
	ds_read_b128 v[246:249], v158 offset:3072
	global_load_lds_dwordx4 v[140:141], off
	v_lshl_add_u64 v[140:141], v[154:155], 0, s[94:95]
	s_add_i32 m0, s21, 0x2000
	s_nop 0
	global_load_lds_dwordx4 v[140:141], off
	s_setprio 1
	s_barrier
; #define PG8_STAGE(bufoff, gbase) do { _Pragma("unroll") for (int _i = 0; _i < 2; ++_i) \
;         __builtin_amdgcn_global_load_lds((const unsigned*)((const char*)(gbase) + voff[_i]), (LAS unsigned*)(lds + (bufoff) + ldsw + _i * 8192), 16, 0, 0); } while (0)
; #define PG8_MMA(ai, bj, At, Bt) do { __builtin_amdgcn_s_setprio(1); _Pragma("unroll") for (int m = 0; m < 4; ++m) _Pragma("unroll") for (int n = 0; n < 2; ++n) _Pragma("unroll") for (int k = 0; k < 2; ++k) \
;         acc[ai][bj][m][n] = __builtin_amdgcn_mfma_f32_16x16x32_bf16(Bt[n][k], At[m][k], acc[ai][bj][m][n], 0, 0, 0); __builtin_amdgcn_s_setprio(0); } while (0)
; #define PG8_WAIT_V(n) asm volatile("s_waitcnt vmcnt(" #n ")" ::: "memory")
; #define PG8_WAIT_L(n) asm volatile("s_waitcnt lgkmcnt(" #n ")" ::: "memory")
; #define PG8_BAR __builtin_amdgcn_s_barrier()
; #define PG8_SCHED __builtin_amdgcn_sched_barrier(0)
; template <class Epi>
; DI void gemm_phase(LAS unsigned char* lds, const Gemm g, const StaticOrder& S, const Epi& E) {
;     ...
;             PG8_BAR; PG8_WAIT_L(0); PG8_MMA(1, 0, At, B0); PG8_BAR; PG8_SCHED;
;             PG8_STAGE(PG8_SB(1, 1), b3 + hstep);
;             PG8_WAIT_V(6); PG8_BAR; PG8_MMA(1, 1, At, B1); PG8_BAR;
;     DI void operator()(const f32x4 (&acc)[2][2][4][2], const Unit& u, int wr, int wc, int fr, int fq) const {
;         const int row0 = u.pm * BM + wr * 64 + fr, col0 = u.pn * BM + wc * 16 + 4 * fq;
;         const bool rot = u.pn < 18;
; #pragma unroll
;         for (int ai = 0; ai < 2; ++ai)
; #pragma unroll
;             for (int m = 0; m < 4; ++m) { const int row = row0 + ai * HALF + m * 16; u16* rowp = O + (size_t)row * NQKV_DIL + col0;
;                 f32x4 c4 = (f32x4){1.f, 1.f, 1.f, 1.f}, s4 = (f32x4){0.f, 0.f, 0.f, 0.f};
;                 if (rot) { const int pos = row & (SEQ - 1); c4 = *(const f32x4*)(cs + pos * 64 + wc * 16 + 4 * fq); s4 = *(const f32x4*)(sn + pos * 64 + wc * 16 + 4 * fq); }
	s_waitcnt lgkmcnt(0)
	v_mfma_f32_16x16x32_bf16 v[116:119], v[234:237], v[194:197], v[116:119]
	v_mfma_f32_16x16x32_bf16 v[112:115], v[242:245], v[194:197], v[112:115]
	v_mfma_f32_16x16x32_bf16 v[100:103], v[234:237], v[202:205], v[100:103]
	v_mfma_f32_16x16x32_bf16 v[96:99], v[242:245], v[202:205], v[96:99]
	v_mfma_f32_16x16x32_bf16 v[84:87], v[234:237], v[210:213], v[84:87]
	v_mfma_f32_16x16x32_bf16 v[80:83], v[242:245], v[210:213], v[80:83]
	v_mfma_f32_16x16x32_bf16 v[68:71], v[234:237], v[226:229], v[68:71]
	v_mfma_f32_16x16x32_bf16 v[64:67], v[242:245], v[226:229], v[64:67]
	v_mfma_f32_16x16x32_bf16 v[116:119], v[238:241], v[198:201], v[116:119]
	v_mfma_f32_16x16x32_bf16 v[112:115], v[246:249], v[198:201], v[112:115]
	v_mfma_f32_16x16x32_bf16 v[100:103], v[238:241], v[206:209], v[100:103]
	v_mfma_f32_16x16x32_bf16 v[96:99], v[246:249], v[206:209], v[96:99]
	v_mfma_f32_16x16x32_bf16 v[84:87], v[238:241], v[214:217], v[84:87]
	v_mfma_f32_16x16x32_bf16 v[80:83], v[246:249], v[214:217], v[80:83]
	v_mfma_f32_16x16x32_bf16 v[68:71], v[238:241], v[230:233], v[68:71]
	v_mfma_f32_16x16x32_bf16 v[64:67], v[246:249], v[230:233], v[64:67]
	s_setprio 0
	s_mov_b32 m0, s30
	v_lshl_add_u64 v[140:141], v[218:219], 0, s[94:95]
	s_barrier
	ds_read_b128 v[194:197], v189 offset:49152
	ds_read_b128 v[198:201], v189 offset:50176
	ds_read_b128 v[202:205], v189 offset:51200
	ds_read_b128 v[206:209], v189 offset:52224
	ds_read_b128 v[210:213], v189 offset:53248
	ds_read_b128 v[214:217], v189 offset:54272
	ds_read_b128 v[226:229], v189 offset:55296
	ds_read_b128 v[230:233], v189 offset:56320
	global_load_lds_dwordx4 v[140:141], off
	v_lshl_add_u64 v[140:141], v[250:251], 0, s[94:95]
	s_mov_b32 m0, s31
	s_nop 0
	global_load_lds_dwordx4 v[140:141], off
	s_setprio 1
	s_barrier
	s_waitcnt lgkmcnt(0)
	v_mfma_f32_16x16x32_bf16 v[60:63], v[128:131], v[194:197], v[60:63]
	v_mfma_f32_16x16x32_bf16 v[56:59], v[136:139], v[194:197], v[56:59]
	v_mfma_f32_16x16x32_bf16 v[44:47], v[128:131], v[202:205], v[44:47]
	v_mfma_f32_16x16x32_bf16 v[40:43], v[136:139], v[202:205], v[40:43]
	v_mfma_f32_16x16x32_bf16 v[28:31], v[128:131], v[210:213], v[28:31]
	v_mfma_f32_16x16x32_bf16 v[24:27], v[136:139], v[210:213], v[24:27]
	v_mfma_f32_16x16x32_bf16 v[12:15], v[128:131], v[226:229], v[12:15]
	v_mfma_f32_16x16x32_bf16 v[8:11], v[136:139], v[226:229], v[8:11]
	v_mfma_f32_16x16x32_bf16 v[60:63], v[132:135], v[198:201], v[60:63]
	v_mfma_f32_16x16x32_bf16 v[56:59], v[190:193], v[198:201], v[56:59]
	v_mfma_f32_16x16x32_bf16 v[44:47], v[132:135], v[206:209], v[44:47]
	v_mfma_f32_16x16x32_bf16 v[40:43], v[190:193], v[206:209], v[40:43]
	v_mfma_f32_16x16x32_bf16 v[28:31], v[132:135], v[214:217], v[28:31]
	v_mfma_f32_16x16x32_bf16 v[24:27], v[190:193], v[214:217], v[24:27]
	v_mfma_f32_16x16x32_bf16 v[12:15], v[132:135], v[230:233], v[12:15]
	v_mfma_f32_16x16x32_bf16 v[8:11], v[190:193], v[230:233], v[8:11]
	s_setprio 0
	s_barrier
	s_add_u32 s18, s18, 0x80080
	s_addc_u32 s19, s19, 0
	s_add_i32 s20, s20, s25
	v_lshl_add_u64 v[128:129], s[18:19], 0, v[144:145]
	s_mov_b32 m0, s20
	s_nop 0
	global_load_lds_dwordx4 v[128:129], off
	v_lshl_add_u64 v[128:129], s[18:19], 0, v[142:143]
	s_add_i32 m0, s20, 0x2000
	s_nop 0
	global_load_lds_dwordx4 v[128:129], off
	s_waitcnt vmcnt(6)
	s_setprio 1
	s_barrier
	v_mfma_f32_16x16x32_bf16 v[52:55], v[234:237], v[194:197], v[52:55]
	v_mfma_f32_16x16x32_bf16 v[48:51], v[242:245], v[194:197], v[48:51]
	v_mfma_f32_16x16x32_bf16 v[36:39], v[234:237], v[202:205], v[36:39]
	v_mfma_f32_16x16x32_bf16 v[32:35], v[242:245], v[202:205], v[32:35]
	v_mfma_f32_16x16x32_bf16 v[20:23], v[234:237], v[210:213], v[20:23]
	v_mfma_f32_16x16x32_bf16 v[16:19], v[242:245], v[210:213], v[16:19]
	v_mfma_f32_16x16x32_bf16 v[4:7], v[234:237], v[226:229], v[4:7]
	v_mfma_f32_16x16x32_bf16 v[0:3], v[242:245], v[226:229], v[0:3]
	v_mfma_f32_16x16x32_bf16 v[52:55], v[238:241], v[198:201], v[52:55]
	v_mfma_f32_16x16x32_bf16 v[48:51], v[246:249], v[198:201], v[48:51]
	v_mfma_f32_16x16x32_bf16 v[36:39], v[238:241], v[206:209], v[36:39]
	v_mfma_f32_16x16x32_bf16 v[32:35], v[246:249], v[206:209], v[32:35]
	v_mfma_f32_16x16x32_bf16 v[20:23], v[238:241], v[214:217], v[20:23]
	v_mfma_f32_16x16x32_bf16 v[16:19], v[246:249], v[214:217], v[16:19]
	v_mfma_f32_16x16x32_bf16 v[4:7], v[238:241], v[230:233], v[4:7]
	v_mfma_f32_16x16x32_bf16 v[0:3], v[246:249], v[230:233], v[0:3]
	s_setprio 0
	s_add_i32 s36, s36, 2
	s_add_u32 s8, s8, 0x100
	s_addc_u32 s9, s9, 0
	s_add_u32 s33, s33, 0x100
	s_addc_u32 s35, s35, 0
	s_cmp_gt_u32 s36, 29
	s_barrier
	s_cbranch_scc0 .LBB0_202
	s_cmp_lt_i32 s2, 18
	v_lshl_add_u32 v190, s3, 8, v186
	v_mov_b32_e32 v128, 1.0
	v_mov_b32_e32 v132, 0
	s_cselect_b64 s[18:19], -1, 0
	s_cmp_gt_i32 s2, 17
	v_mov_b32_e32 v134, 0
	v_mov_b32_e32 v135, 0
	v_mov_b32_e32 v136, 0
	v_mov_b32_e32 v137, 0
	v_mov_b32_e32 v138, 1.0
	v_mov_b32_e32 v139, 1.0
	v_mov_b32_e32 v140, 1.0
	v_mov_b32_e32 v141, 1.0
	s_cbranch_scc1 .LBB0_205
	v_lshlrev_b32_e32 v129, 8, v190
	v_and_b32_e32 v158, 0xfcf00, v129
	v_lshl_add_u64 v[130:131], v[146:147], 0, v[158:159]
	v_lshl_add_u64 v[134:135], v[148:149], 0, v[158:159]
	global_load_dwordx4 v[138:141], v[130:131], off
	s_nop 0
	global_load_dwordx4 v[134:137], v[134:135], off

; #define PG8_STAGE(bufoff, gbase) do { _Pragma("unroll") for (int _i = 0; _i < 2; ++_i) \
;         __builtin_amdgcn_global_load_lds((const unsigned*)((const char*)(gbase) + voff[_i]), (LAS unsigned*)(lds + (bufoff) + ldsw + _i * 8192), 16, 0, 0); } while (0)
; #define PG8_LDA(dst, b, h) do { _Pragma("unroll") for (int m = 0; m < 4; ++m) _Pragma("unroll") for (int k = 0; k < 2; ++k) dst[m][k] = *(const LAS bf16x8*)(lds + PG8_SA(b, h) + aoff + m * 2048 + k * 1024); } while (0)
; #define PG8_LDB(dst, b, h) do { _Pragma("unroll") for (int n = 0; n < 2; ++n) _Pragma("unroll") for (int k = 0; k < 2; ++k) dst[n][k] = *(const LAS bf16x8*)(lds + PG8_SB(b, h) + boff + n * 2048 + k * 1024); } while (0)
; #define PG8_MMA(ai, bj, At, Bt) do { __builtin_amdgcn_s_setprio(1); _Pragma("unroll") for (int m = 0; m < 4; ++m) _Pragma("unroll") for (int n = 0; n < 2; ++n) _Pragma("unroll") for (int k = 0; k < 2; ++k) \
;         acc[ai][bj][m][n] = __builtin_amdgcn_mfma_f32_16x16x32_bf16(Bt[n][k], At[m][k], acc[ai][bj][m][n], 0, 0, 0); __builtin_amdgcn_s_setprio(0); } while (0)
; #define PG8_WAIT_L(n) asm volatile("s_waitcnt lgkmcnt(" #n ")" ::: "memory")
; #define PG8_BAR __builtin_amdgcn_s_barrier()
; #define PG8_SCHED __builtin_amdgcn_sched_barrier(0)
; template <class Epi>
; DI void gemm_phase(LAS unsigned char* lds, const Gemm g, const StaticOrder& S, const Epi& E) {
;     ...
;         const char* nA = has_next ? (const char*)g.A + (size_t)nxt.pm * tstep : cA; const char* nB = has_next ? (const char*)g.Bt + (size_t)nxt.pn * tstep : cB;
;         for (int t = 0; t < nt; t += 2) {
;             const bool last = (t == nt - 2);
;             const char* a1 = cA + (size_t)(t + 1) * kstep;
;             const char* a2 = last ? nA : cA + (size_t)(t + 2) * kstep; const char* b2 = last ? nB : cB + (size_t)(t + 2) * kstep;
;             const char* a3 = a2 + kstep; const char* b3 = b2 + kstep;
;             PG8_LDB(B0, 0, 0); PG8_SCHED; PG8_LDA(At, 0, 0); PG8_STAGE(PG8_SA(1, 1), a1 + hstep);
;             PG8_WAIT_L(8); PG8_BAR; PG8_WAIT_L(0); PG8_MMA(0, 0, At, B0); PG8_BAR; PG8_SCHED;
;             PG8_LDB(B1, 0, 1); PG8_STAGE(PG8_SB(0, 0), b2);
;             PG8_BAR; PG8_WAIT_L(0); PG8_MMA(0, 1, At, B1); PG8_BAR;
;             PG8_LDA(At, 0, 1); PG8_STAGE(PG8_SA(0, 0), a2);
;             PG8_BAR; PG8_WAIT_L(0); PG8_MMA(1, 0, At, B0); PG8_BAR; PG8_SCHED;
.LBB0_231:
	s_add_u32 s18, s16, 0xfff80080
	s_addc_u32 s19, s17, -1
	s_add_i32 s37, 0, 0x10000
	v_add_u32_e32 v150, s37, v135
	ds_read_b128 v[138:141], v150
	ds_read_b128 v[142:145], v150 offset:1024
	ds_read_b128 v[146:149], v150 offset:2048
	ds_read_b128 v[150:153], v150 offset:3072
	s_cmp_eq_u32 s36, 28
	s_cselect_b32 s21, s4, s19
	s_cselect_b32 s20, s5, s18
	s_cselect_b32 s19, s9, s35
	s_cselect_b32 s18, s11, s34
	v_lshl_add_u64 v[154:155], s[16:17], 0, v[130:131]
	s_add_i32 m0, s24, 0xc000
	ds_read_b128 v[186:189], v137
	ds_read_b128 v[190:193], v137 offset:1024
	ds_read_b128 v[194:197], v137 offset:2048
	ds_read_b128 v[198:201], v137 offset:3072
	ds_read_b128 v[202:205], v137 offset:4096
	ds_read_b128 v[206:209], v137 offset:5120
	ds_read_b128 v[210:213], v137 offset:6144
	ds_read_b128 v[214:217], v137 offset:7168
	global_load_lds_dwordx4 v[154:155], off
	v_lshl_add_u64 v[154:155], s[16:17], 0, v[132:133]
	s_add_i32 m0, s24, 0xe000
	s_nop 0
	global_load_lds_dwordx4 v[154:155], off
	s_waitcnt lgkmcnt(8)
	s_setprio 1
	s_barrier
	s_waitcnt lgkmcnt(0)
	v_mfma_f32_16x16x32_bf16 v[124:127], v[138:141], v[186:189], v[124:127]
	v_mfma_f32_16x16x32_bf16 v[120:123], v[146:149], v[186:189], v[120:123]
	v_mfma_f32_16x16x32_bf16 v[116:119], v[138:141], v[194:197], v[116:119]
	v_mfma_f32_16x16x32_bf16 v[112:115], v[146:149], v[194:197], v[112:115]
	v_mfma_f32_16x16x32_bf16 v[100:103], v[138:141], v[202:205], v[100:103]
	v_mfma_f32_16x16x32_bf16 v[96:99], v[146:149], v[202:205], v[96:99]
	v_mfma_f32_16x16x32_bf16 v[84:87], v[138:141], v[210:213], v[84:87]
	v_mfma_f32_16x16x32_bf16 v[80:83], v[146:149], v[210:213], v[80:83]
	v_mfma_f32_16x16x32_bf16 v[124:127], v[142:145], v[190:193], v[124:127]
	v_mfma_f32_16x16x32_bf16 v[120:123], v[150:153], v[190:193], v[120:123]
	v_mfma_f32_16x16x32_bf16 v[116:119], v[142:145], v[198:201], v[116:119]
	v_mfma_f32_16x16x32_bf16 v[112:115], v[150:153], v[198:201], v[112:115]
	v_mfma_f32_16x16x32_bf16 v[100:103], v[142:145], v[206:209], v[100:103]
	v_mfma_f32_16x16x32_bf16 v[96:99], v[150:153], v[206:209], v[96:99]
	v_mfma_f32_16x16x32_bf16 v[84:87], v[142:145], v[214:217], v[84:87]
	v_mfma_f32_16x16x32_bf16 v[80:83], v[150:153], v[214:217], v[80:83]
	s_setprio 0
	s_barrier
	s_add_i32 s40, 0, 0x14000
	v_add_u32_e32 v154, s40, v135
	s_add_i32 s37, s37, s23
	ds_read_b128 v[226:229], v154
	ds_read_b128 v[230:233], v154 offset:1024
	ds_read_b128 v[234:237], v154 offset:2048
	ds_read_b128 v[238:241], v154 offset:3072
	v_lshl_add_u64 v[154:155], s[18:19], 0, v[158:159]
	s_mov_b32 m0, s37
	v_lshl_add_u64 v[218:219], s[18:19], 0, v[128:129]
	global_load_lds_dwordx4 v[154:155], off
	s_add_i32 m0, s37, 0x2000
	s_nop 0
	global_load_lds_dwordx4 v[218:219], off
	s_setprio 1
	s_barrier
	s_waitcnt lgkmcnt(0)
	v_mfma_f32_16x16x32_bf16 v[108:111], v[226:229], v[186:189], v[108:111]
	v_mfma_f32_16x16x32_bf16 v[104:107], v[234:237], v[186:189], v[104:107]
	v_mfma_f32_16x16x32_bf16 v[92:95], v[226:229], v[194:197], v[92:95]
	v_mfma_f32_16x16x32_bf16 v[88:91], v[234:237], v[194:197], v[88:91]
	v_mfma_f32_16x16x32_bf16 v[76:79], v[226:229], v[202:205], v[76:79]
	v_mfma_f32_16x16x32_bf16 v[72:75], v[234:237], v[202:205], v[72:75]
	v_mfma_f32_16x16x32_bf16 v[68:71], v[226:229], v[210:213], v[68:71]
	v_mfma_f32_16x16x32_bf16 v[64:67], v[234:237], v[210:213], v[64:67]
	v_mfma_f32_16x16x32_bf16 v[108:111], v[230:233], v[190:193], v[108:111]
	v_mfma_f32_16x16x32_bf16 v[104:107], v[238:241], v[190:193], v[104:107]
	v_mfma_f32_16x16x32_bf16 v[92:95], v[230:233], v[198:201], v[92:95]
	v_mfma_f32_16x16x32_bf16 v[88:91], v[238:241], v[198:201], v[88:91]
	v_mfma_f32_16x16x32_bf16 v[76:79], v[230:233], v[206:209], v[76:79]
	v_mfma_f32_16x16x32_bf16 v[72:75], v[238:241], v[206:209], v[72:75]
	v_mfma_f32_16x16x32_bf16 v[68:71], v[230:233], v[214:217], v[68:71]
	v_mfma_f32_16x16x32_bf16 v[64:67], v[238:241], v[214:217], v[64:67]
	s_setprio 0
	s_mov_b32 m0, s24
	v_lshl_add_u64 v[242:243], s[20:21], 0, v[158:159]
	s_barrier
	ds_read_b128 v[186:189], v137 offset:16384
	ds_read_b128 v[190:193], v137 offset:17408
	ds_read_b128 v[194:197], v137 offset:18432
	ds_read_b128 v[198:201], v137 offset:19456
	ds_read_b128 v[202:205], v137 offset:20480
	ds_read_b128 v[206:209], v137 offset:21504
	ds_read_b128 v[210:213], v137 offset:22528
	ds_read_b128 v[214:217], v137 offset:23552
	global_load_lds_dwordx4 v[242:243], off
	v_lshl_add_u64 v[244:245], s[20:21], 0, v[128:129]
	s_mov_b32 m0, s25
	s_nop 0
	global_load_lds_dwordx4 v[244:245], off
	s_setprio 1
	s_barrier
	s_waitcnt lgkmcnt(0)
	v_mfma_f32_16x16x32_bf16 v[60:63], v[138:141], v[186:189], v[60:63]
	v_mfma_f32_16x16x32_bf16 v[56:59], v[146:149], v[186:189], v[56:59]
	v_mfma_f32_16x16x32_bf16 v[52:55], v[138:141], v[194:197], v[52:55]
	v_mfma_f32_16x16x32_bf16 v[48:51], v[146:149], v[194:197], v[48:51]
	v_mfma_f32_16x16x32_bf16 v[36:39], v[138:141], v[202:205], v[36:39]
	v_mfma_f32_16x16x32_bf16 v[32:35], v[146:149], v[202:205], v[32:35]
	v_mfma_f32_16x16x32_bf16 v[20:23], v[138:141], v[210:213], v[20:23]
	v_mfma_f32_16x16x32_bf16 v[16:19], v[146:149], v[210:213], v[16:19]
	v_mfma_f32_16x16x32_bf16 v[60:63], v[142:145], v[190:193], v[60:63]
	v_mfma_f32_16x16x32_bf16 v[56:59], v[150:153], v[190:193], v[56:59]
	v_mfma_f32_16x16x32_bf16 v[52:55], v[142:145], v[198:201], v[52:55]
	v_mfma_f32_16x16x32_bf16 v[48:51], v[150:153], v[198:201], v[48:51]
	v_mfma_f32_16x16x32_bf16 v[36:39], v[142:145], v[206:209], v[36:39]
	v_mfma_f32_16x16x32_bf16 v[32:35], v[150:153], v[206:209], v[32:35]
	v_mfma_f32_16x16x32_bf16 v[20:23], v[142:145], v[214:217], v[20:23]
	v_mfma_f32_16x16x32_bf16 v[16:19], v[150:153], v[214:217], v[16:19]
	s_setprio 0
	s_barrier
; #define PG8_STAGE(bufoff, gbase) do { _Pragma("unroll") for (int _i = 0; _i < 2; ++_i) \
;         __builtin_amdgcn_global_load_lds((const unsigned*)((const char*)(gbase) + voff[_i]), (LAS unsigned*)(lds + (bufoff) + ldsw + _i * 8192), 16, 0, 0); } while (0)
; #define PG8_LDA(dst, b, h) do { _Pragma("unroll") for (int m = 0; m < 4; ++m) _Pragma("unroll") for (int k = 0; k < 2; ++k) dst[m][k] = *(const LAS bf16x8*)(lds + PG8_SA(b, h) + aoff + m * 2048 + k * 1024); } while (0)
; #define PG8_LDB(dst, b, h) do { _Pragma("unroll") for (int n = 0; n < 2; ++n) _Pragma("unroll") for (int k = 0; k < 2; ++k) dst[n][k] = *(const LAS bf16x8*)(lds + PG8_SB(b, h) + boff + n * 2048 + k * 1024); } while (0)
; #define PG8_MMA(ai, bj, At, Bt) do { __builtin_amdgcn_s_setprio(1); _Pragma("unroll") for (int m = 0; m < 4; ++m) _Pragma("unroll") for (int n = 0; n < 2; ++n) _Pragma("unroll") for (int k = 0; k < 2; ++k) \
;         acc[ai][bj][m][n] = __builtin_amdgcn_mfma_f32_16x16x32_bf16(Bt[n][k], At[m][k], acc[ai][bj][m][n], 0, 0, 0); __builtin_amdgcn_s_setprio(0); } while (0)
; #define PG8_WAIT_V(n) asm volatile("s_waitcnt vmcnt(" #n ")" ::: "memory")
; #define PG8_WAIT_L(n) asm volatile("s_waitcnt lgkmcnt(" #n ")" ::: "memory")
; #define PG8_BAR __builtin_amdgcn_s_barrier()
; #define PG8_SCHED __builtin_amdgcn_sched_barrier(0)
; template <class Epi>
; DI void gemm_phase(LAS unsigned char* lds, const Gemm g, const StaticOrder& S, const Epi& E) {
;     ...
;             PG8_STAGE(PG8_SB(0, 1), b2 + hstep);
;             PG8_WAIT_V(6); PG8_BAR; PG8_MMA(1, 1, At, B1); PG8_BAR;
;             PG8_LDB(B0, 1, 0); PG8_SCHED; PG8_LDA(At, 1, 0); PG8_STAGE(PG8_SA(0, 1), a2 + hstep);
;             PG8_WAIT_L(8); PG8_BAR; PG8_WAIT_L(0); PG8_MMA(0, 0, At, B0); PG8_BAR; PG8_SCHED;
;             PG8_LDB(B1, 1, 1); PG8_STAGE(PG8_SB(1, 0), b3);
;             PG8_BAR; PG8_WAIT_L(0); PG8_MMA(0, 1, At, B1); PG8_BAR;
;             PG8_LDA(At, 1, 1); PG8_STAGE(PG8_SA(1, 0), a3);
;             PG8_BAR; PG8_WAIT_L(0); PG8_MMA(1, 0, At, B0); PG8_BAR; PG8_SCHED;
	s_add_u32 s38, s18, 0x80000
	s_addc_u32 s39, s19, 0
	s_add_i32 s37, s40, s23
	v_lshl_add_u64 v[138:139], s[38:39], 0, v[158:159]
	s_mov_b32 m0, s37
	s_nop 0
	global_load_lds_dwordx4 v[138:139], off
	v_lshl_add_u64 v[138:139], s[38:39], 0, v[128:129]
	s_add_i32 m0, s37, 0x2000
	s_nop 0
	global_load_lds_dwordx4 v[138:139], off
	s_waitcnt vmcnt(6)
	s_setprio 1
	s_barrier
	v_mfma_f32_16x16x32_bf16 v[44:47], v[226:229], v[186:189], v[44:47]
	v_mfma_f32_16x16x32_bf16 v[40:43], v[234:237], v[186:189], v[40:43]
	v_mfma_f32_16x16x32_bf16 v[28:31], v[226:229], v[194:197], v[28:31]
	v_mfma_f32_16x16x32_bf16 v[24:27], v[234:237], v[194:197], v[24:27]
	v_mfma_f32_16x16x32_bf16 v[12:15], v[226:229], v[202:205], v[12:15]
	v_mfma_f32_16x16x32_bf16 v[8:11], v[234:237], v[202:205], v[8:11]
	v_mfma_f32_16x16x32_bf16 v[4:7], v[226:229], v[210:213], v[4:7]
	v_mfma_f32_16x16x32_bf16 v[0:3], v[234:237], v[210:213], v[0:3]
	v_mfma_f32_16x16x32_bf16 v[44:47], v[230:233], v[190:193], v[44:47]
	v_mfma_f32_16x16x32_bf16 v[40:43], v[238:241], v[190:193], v[40:43]
	v_mfma_f32_16x16x32_bf16 v[28:31], v[230:233], v[198:201], v[28:31]
	v_mfma_f32_16x16x32_bf16 v[24:27], v[238:241], v[198:201], v[24:27]
	v_mfma_f32_16x16x32_bf16 v[12:15], v[230:233], v[206:209], v[12:15]
	v_mfma_f32_16x16x32_bf16 v[8:11], v[238:241], v[206:209], v[8:11]
	v_mfma_f32_16x16x32_bf16 v[4:7], v[230:233], v[214:217], v[4:7]
	v_mfma_f32_16x16x32_bf16 v[0:3], v[238:241], v[214:217], v[0:3]
	s_setprio 0
	s_add_i32 s37, 0, 0x18000
	v_add_u32_e32 v150, s37, v135
	s_barrier
	ds_read_b128 v[138:141], v150
	ds_read_b128 v[142:145], v150 offset:1024
	ds_read_b128 v[146:149], v150 offset:2048
	ds_read_b128 v[150:153], v150 offset:3072
	s_add_u32 s20, s20, 0x80000
	s_addc_u32 s21, s21, 0
	s_mov_b32 m0, s26
	v_lshl_add_u64 v[226:227], s[20:21], 0, v[158:159]
	ds_read_b128 v[186:189], v137 offset:32768
	ds_read_b128 v[190:193], v137 offset:33792
	ds_read_b128 v[194:197], v137 offset:34816
	ds_read_b128 v[198:201], v137 offset:35840
	ds_read_b128 v[202:205], v137 offset:36864
	ds_read_b128 v[206:209], v137 offset:37888
	ds_read_b128 v[210:213], v137 offset:38912
	ds_read_b128 v[214:217], v137 offset:39936
	global_load_lds_dwordx4 v[226:227], off
	v_lshl_add_u64 v[226:227], s[20:21], 0, v[128:129]
	s_mov_b32 m0, s27
	s_nop 0
	global_load_lds_dwordx4 v[226:227], off
	s_waitcnt lgkmcnt(8)
	s_setprio 1
	s_barrier
	s_waitcnt lgkmcnt(0)
	v_mfma_f32_16x16x32_bf16 v[124:127], v[138:141], v[186:189], v[124:127]
	v_mfma_f32_16x16x32_bf16 v[120:123], v[146:149], v[186:189], v[120:123]
	v_mfma_f32_16x16x32_bf16 v[116:119], v[138:141], v[194:197], v[116:119]
	v_mfma_f32_16x16x32_bf16 v[112:115], v[146:149], v[194:197], v[112:115]
	v_mfma_f32_16x16x32_bf16 v[100:103], v[138:141], v[202:205], v[100:103]
	v_mfma_f32_16x16x32_bf16 v[96:99], v[146:149], v[202:205], v[96:99]
	v_mfma_f32_16x16x32_bf16 v[84:87], v[138:141], v[210:213], v[84:87]
	v_mfma_f32_16x16x32_bf16 v[80:83], v[146:149], v[210:213], v[80:83]
	v_mfma_f32_16x16x32_bf16 v[124:127], v[142:145], v[190:193], v[124:127]
	v_mfma_f32_16x16x32_bf16 v[120:123], v[150:153], v[190:193], v[120:123]
	v_mfma_f32_16x16x32_bf16 v[116:119], v[142:145], v[198:201], v[116:119]
	v_mfma_f32_16x16x32_bf16 v[112:115], v[150:153], v[198:201], v[112:115]
	v_mfma_f32_16x16x32_bf16 v[100:103], v[142:145], v[206:209], v[100:103]
	v_mfma_f32_16x16x32_bf16 v[96:99], v[150:153], v[206:209], v[96:99]
	v_mfma_f32_16x16x32_bf16 v[84:87], v[142:145], v[214:217], v[84:87]
	v_mfma_f32_16x16x32_bf16 v[80:83], v[150:153], v[214:217], v[80:83]
	s_setprio 0
	s_barrier
	s_add_i32 s20, 0, 0x1c000
	s_add_i32 s21, s37, s23
	v_add_u32_e32 v220, s20, v135
	v_lshl_add_u64 v[154:155], v[154:155], 0, s[94:95]
	s_mov_b32 m0, s21
	ds_read_b128 v[226:229], v220
	ds_read_b128 v[230:233], v220 offset:1024
	ds_read_b128 v[234:237], v220 offset:2048
	ds_read_b128 v[238:241], v220 offset:3072
	global_load_lds_dwordx4 v[154:155], off
	v_lshl_add_u64 v[154:155], v[218:219], 0, s[94:95]
	s_add_i32 m0, s21, 0x2000
	s_nop 0
	global_load_lds_dwordx4 v[154:155], off
	s_setprio 1
	s_barrier
	s_waitcnt lgkmcnt(0)
	v_mfma_f32_16x16x32_bf16 v[108:111], v[226:229], v[186:189], v[108:111]
	v_mfma_f32_16x16x32_bf16 v[104:107], v[234:237], v[186:189], v[104:107]
	v_mfma_f32_16x16x32_bf16 v[92:95], v[226:229], v[194:197], v[92:95]
	v_mfma_f32_16x16x32_bf16 v[88:91], v[234:237], v[194:197], v[88:91]
	v_mfma_f32_16x16x32_bf16 v[76:79], v[226:229], v[202:205], v[76:79]
	v_mfma_f32_16x16x32_bf16 v[72:75], v[234:237], v[202:205], v[72:75]
	v_mfma_f32_16x16x32_bf16 v[68:71], v[226:229], v[210:213], v[68:71]
	v_mfma_f32_16x16x32_bf16 v[64:67], v[234:237], v[210:213], v[64:67]
	v_mfma_f32_16x16x32_bf16 v[108:111], v[230:233], v[190:193], v[108:111]
	v_mfma_f32_16x16x32_bf16 v[104:107], v[238:241], v[190:193], v[104:107]
	v_mfma_f32_16x16x32_bf16 v[92:95], v[230:233], v[198:201], v[92:95]
	v_mfma_f32_16x16x32_bf16 v[88:91], v[238:241], v[198:201], v[88:91]
	v_mfma_f32_16x16x32_bf16 v[76:79], v[230:233], v[206:209], v[76:79]
	v_mfma_f32_16x16x32_bf16 v[72:75], v[238:241], v[206:209], v[72:75]
	v_mfma_f32_16x16x32_bf16 v[68:71], v[230:233], v[214:217], v[68:71]
	v_mfma_f32_16x16x32_bf16 v[64:67], v[238:241], v[214:217], v[64:67]
	s_setprio 0
	s_mov_b32 m0, s28
	v_lshl_add_u64 v[154:155], v[242:243], 0, s[94:95]
	s_barrier
	ds_read_b128 v[186:189], v137 offset:49152
	ds_read_b128 v[190:193], v137 offset:50176
	ds_read_b128 v[194:197], v137 offset:51200
	ds_read_b128 v[198:201], v137 offset:52224
	ds_read_b128 v[202:205], v137 offset:53248
	ds_read_b128 v[206:209], v137 offset:54272
	ds_read_b128 v[210:213], v137 offset:55296
	ds_read_b128 v[214:217], v137 offset:56320
	global_load_lds_dwordx4 v[154:155], off
	v_lshl_add_u64 v[154:155], v[244:245], 0, s[94:95]
	s_mov_b32 m0, s29
	s_nop 0
	global_load_lds_dwordx4 v[154:155], off
	s_setprio 1
	s_barrier
; #define PG8_STAGE(bufoff, gbase) do { _Pragma("unroll") for (int _i = 0; _i < 2; ++_i) \
;         __builtin_amdgcn_global_load_lds((const unsigned*)((const char*)(gbase) + voff[_i]), (LAS unsigned*)(lds + (bufoff) + ldsw + _i * 8192), 16, 0, 0); } while (0)
; #define PG8_MMA(ai, bj, At, Bt) do { __builtin_amdgcn_s_setprio(1); _Pragma("unroll") for (int m = 0; m < 4; ++m) _Pragma("unroll") for (int n = 0; n < 2; ++n) _Pragma("unroll") for (int k = 0; k < 2; ++k) \
;         acc[ai][bj][m][n] = __builtin_amdgcn_mfma_f32_16x16x32_bf16(Bt[n][k], At[m][k], acc[ai][bj][m][n], 0, 0, 0); __builtin_amdgcn_s_setprio(0); } while (0)
; #define PG8_WAIT_V(n) asm volatile("s_waitcnt vmcnt(" #n ")" ::: "memory")
; #define PG8_WAIT_L(n) asm volatile("s_waitcnt lgkmcnt(" #n ")" ::: "memory")
; #define PG8_BAR __builtin_amdgcn_s_barrier()
; #define PG8_SCHED __builtin_amdgcn_sched_barrier(0)
; template <class Epi>
; DI void gemm_phase(LAS unsigned char* lds, const Gemm g, const StaticOrder& S, const Epi& E) {
;     ...
;             PG8_BAR; PG8_WAIT_L(0); PG8_MMA(1, 0, At, B0); PG8_BAR; PG8_SCHED;
;             PG8_STAGE(PG8_SB(1, 1), b3 + hstep);
;             PG8_WAIT_V(6); PG8_BAR; PG8_MMA(1, 1, At, B1); PG8_BAR;
	s_waitcnt lgkmcnt(0)
	v_mfma_f32_16x16x32_bf16 v[60:63], v[138:141], v[186:189], v[60:63]
	v_mfma_f32_16x16x32_bf16 v[56:59], v[146:149], v[186:189], v[56:59]
	v_mfma_f32_16x16x32_bf16 v[52:55], v[138:141], v[194:197], v[52:55]
	v_mfma_f32_16x16x32_bf16 v[48:51], v[146:149], v[194:197], v[48:51]
	v_mfma_f32_16x16x32_bf16 v[36:39], v[138:141], v[202:205], v[36:39]
	v_mfma_f32_16x16x32_bf16 v[32:35], v[146:149], v[202:205], v[32:35]
	v_mfma_f32_16x16x32_bf16 v[20:23], v[138:141], v[210:213], v[20:23]
	v_mfma_f32_16x16x32_bf16 v[16:19], v[146:149], v[210:213], v[16:19]
	v_mfma_f32_16x16x32_bf16 v[60:63], v[142:145], v[190:193], v[60:63]
	v_mfma_f32_16x16x32_bf16 v[56:59], v[150:153], v[190:193], v[56:59]
	v_mfma_f32_16x16x32_bf16 v[52:55], v[142:145], v[198:201], v[52:55]
	v_mfma_f32_16x16x32_bf16 v[48:51], v[150:153], v[198:201], v[48:51]
	v_mfma_f32_16x16x32_bf16 v[36:39], v[142:145], v[206:209], v[36:39]
	v_mfma_f32_16x16x32_bf16 v[32:35], v[150:153], v[206:209], v[32:35]
	v_mfma_f32_16x16x32_bf16 v[20:23], v[142:145], v[214:217], v[20:23]
	v_mfma_f32_16x16x32_bf16 v[16:19], v[150:153], v[214:217], v[16:19]
	s_setprio 0
	s_barrier
	s_add_u32 s18, s18, 0x80080
	s_addc_u32 s19, s19, 0
	s_add_i32 s20, s20, s23
	v_lshl_add_u64 v[138:139], s[18:19], 0, v[158:159]
	s_mov_b32 m0, s20
	s_nop 0
	global_load_lds_dwordx4 v[138:139], off
	v_lshl_add_u64 v[138:139], s[18:19], 0, v[128:129]
	s_add_i32 m0, s20, 0x2000
	s_nop 0
	global_load_lds_dwordx4 v[138:139], off
	s_waitcnt vmcnt(6)
	s_setprio 1
	s_barrier
	v_mfma_f32_16x16x32_bf16 v[44:47], v[226:229], v[186:189], v[44:47]
	v_mfma_f32_16x16x32_bf16 v[40:43], v[234:237], v[186:189], v[40:43]
	v_mfma_f32_16x16x32_bf16 v[28:31], v[226:229], v[194:197], v[28:31]
	v_mfma_f32_16x16x32_bf16 v[24:27], v[234:237], v[194:197], v[24:27]
	v_mfma_f32_16x16x32_bf16 v[12:15], v[226:229], v[202:205], v[12:15]
	v_mfma_f32_16x16x32_bf16 v[8:11], v[234:237], v[202:205], v[8:11]
	v_mfma_f32_16x16x32_bf16 v[4:7], v[226:229], v[210:213], v[4:7]
	v_mfma_f32_16x16x32_bf16 v[0:3], v[234:237], v[210:213], v[0:3]
	v_mfma_f32_16x16x32_bf16 v[44:47], v[230:233], v[190:193], v[44:47]
	v_mfma_f32_16x16x32_bf16 v[40:43], v[238:241], v[190:193], v[40:43]
	v_mfma_f32_16x16x32_bf16 v[28:31], v[230:233], v[198:201], v[28:31]
	v_mfma_f32_16x16x32_bf16 v[24:27], v[238:241], v[198:201], v[24:27]
	v_mfma_f32_16x16x32_bf16 v[12:15], v[230:233], v[206:209], v[12:15]
	v_mfma_f32_16x16x32_bf16 v[8:11], v[238:241], v[206:209], v[8:11]
	v_mfma_f32_16x16x32_bf16 v[4:7], v[230:233], v[214:217], v[4:7]
	v_mfma_f32_16x16x32_bf16 v[0:3], v[238:241], v[214:217], v[0:3]
	s_setprio 0
	s_add_i32 s36, s36, 2
	s_add_u32 s16, s16, 0x100
	s_addc_u32 s17, s17, 0
	s_add_u32 s34, s34, 0x100
	s_addc_u32 s35, s35, 0
	s_cmp_gt_u32 s36, 29
	s_barrier
	s_cbranch_scc0 .LBB0_231
; #define PG8_WAIT_V(n) asm volatile("s_waitcnt vmcnt(" #n ")" ::: "memory")
; #define PG8_BAR __builtin_amdgcn_s_barrier()
; template <class Epi>
; DI void gemm_phase(LAS unsigned char* lds, const Gemm g, const StaticOrder& S, const Epi& E) {
;     ...
;         if (!has_next) break;
; #pragma unroll
;         for (int a = 0; a < 2; ++a)
; #pragma unroll
;             for (int b = 0; b < 2; ++b)
; #pragma unroll
;                 for (int m = 0; m < 4; ++m)
; #pragma unroll
;                     for (int n = 0; n < 2; ++n) acc[a][b][m][n] = (f32x4){0.f, 0.f, 0.f, 0.f};
;         cur = nxt; cA = nA; cB = nB; ++ui;
;     }
;     PG8_WAIT_V(0);
;     if (wr == 0) PG8_BAR;
;     PG8_BAR;
;     DI void operator()(const f32x4 (&acc)[2][2][4][2], const Unit& u, int wr, int wc, int fr, int fq) const {
;         const int row0 = u.pm * BM + wr * 64 + fr, col0 = u.pn * BM + wc * 32 + 8 * fq;
; #pragma unroll
;         for (int ai = 0; ai < 2; ++ai)
; #pragma unroll
;             for (int m = 0; m < 4; ++m) { u16* rowp = O + (size_t)(row0 + ai * HALF + m * 16) * ldc + col0;
; #pragma unroll
;                 for (int bj = 0; bj < 2; ++bj) { const f32x4 v0 = acc[ai][bj][m][0], v1 = acc[ai][bj][m][1];
;                     *(u32x4*)(rowp + bj * HALF) = (u32x4){pk(v0[0], v0[1]), pk(v0[2], v0[3]), pk(v1[0], v1[1]), pk(v1[2], v1[3])}; } }
;     }
	v_lshl_add_u32 v144, s33, 8, v134
	v_lshl_or_b32 v138, s31, 8, v136
	v_ashrrev_i32_e32 v139, 31, v138
	v_mov_b64_e32 v[140:141], s[50:51]
	s_movk_i32 s9, 0x3000
	v_cvt_pk_bf16_f32 v68, v68, v69
	v_cvt_pk_bf16_f32 v69, v70, v71
	v_cvt_pk_bf16_f32 v70, v64, v65
	v_add_u32_e32 v64, 0x80, v144
	v_mad_i64_i32 v[142:143], s[4:5], v144, s9, v[140:141]
	v_lshlrev_b64 v[138:139], 1, v[138:139]
	v_cvt_pk_bf16_f32 v108, v108, v109
	v_cvt_pk_bf16_f32 v109, v110, v111
	v_cvt_pk_bf16_f32 v110, v104, v105
	v_or_b32_e32 v104, 16, v144
	v_mad_i64_i32 v[64:65], s[4:5], v64, s9, v[140:141]
	v_cvt_pk_bf16_f32 v44, v44, v45
	v_cvt_pk_bf16_f32 v45, v46, v47
	v_cvt_pk_bf16_f32 v46, v40, v41
	v_add_u32_e32 v40, 0x90, v144
	v_lshl_add_u64 v[142:143], v[142:143], 0, v[138:139]
	v_cvt_pk_bf16_f32 v111, v106, v107
	v_mad_i64_i32 v[104:105], s[4:5], v104, s9, v[140:141]
	v_cvt_pk_bf16_f32 v92, v92, v93
	v_cvt_pk_bf16_f32 v93, v94, v95
	v_cvt_pk_bf16_f32 v94, v88, v89
	v_or_b32_e32 v88, 32, v144
	v_lshl_add_u64 v[64:65], v[64:65], 0, v[138:139]
	v_cvt_pk_bf16_f32 v47, v42, v43
	v_mad_i64_i32 v[40:41], s[4:5], v40, s9, v[140:141]
	v_cvt_pk_bf16_f32 v28, v28, v29
	v_cvt_pk_bf16_f32 v29, v30, v31
	v_cvt_pk_bf16_f32 v30, v24, v25
	v_add_u32_e32 v24, 0xa0, v144
	global_store_dwordx4 v[142:143], v[108:111], off offset:256
	v_cvt_pk_bf16_f32 v95, v90, v91
	v_mad_i64_i32 v[88:89], s[4:5], v88, s9, v[140:141]
	v_lshl_add_u64 v[108:109], v[104:105], 0, v[138:139]
	v_cvt_pk_bf16_f32 v76, v76, v77
	v_cvt_pk_bf16_f32 v77, v78, v79
	v_cvt_pk_bf16_f32 v78, v72, v73
	v_or_b32_e32 v72, 48, v144
	global_store_dwordx4 v[64:65], v[44:47], off offset:256
	v_cvt_pk_bf16_f32 v31, v26, v27
	v_mad_i64_i32 v[24:25], s[4:5], v24, s9, v[140:141]
	v_lshl_add_u64 v[44:45], v[40:41], 0, v[138:139]
	v_cvt_pk_bf16_f32 v12, v12, v13
	v_cvt_pk_bf16_f32 v13, v14, v15
	v_cvt_pk_bf16_f32 v14, v8, v9
	v_add_u32_e32 v8, 0xb0, v144
	global_store_dwordx4 v[108:109], v[92:95], off offset:256
	v_cvt_pk_bf16_f32 v79, v74, v75
	v_mad_i64_i32 v[72:73], s[4:5], v72, s9, v[140:141]
	v_lshl_add_u64 v[92:93], v[88:89], 0, v[138:139]
	global_store_dwordx4 v[44:45], v[28:31], off offset:256
	v_cvt_pk_bf16_f32 v15, v10, v11
	v_mad_i64_i32 v[8:9], s[4:5], v8, s9, v[140:141]
	v_lshl_add_u64 v[28:29], v[24:25], 0, v[138:139]
	v_cvt_pk_bf16_f32 v124, v124, v125
	v_cvt_pk_bf16_f32 v125, v126, v127
	v_cvt_pk_bf16_f32 v126, v120, v121
	v_cvt_pk_bf16_f32 v127, v122, v123
	v_cvt_pk_bf16_f32 v104, v116, v117
	v_cvt_pk_bf16_f32 v105, v118, v119
	v_cvt_pk_bf16_f32 v106, v112, v113
	v_cvt_pk_bf16_f32 v107, v114, v115
	v_cvt_pk_bf16_f32 v88, v100, v101
	v_cvt_pk_bf16_f32 v89, v102, v103
	v_cvt_pk_bf16_f32 v90, v96, v97
	v_cvt_pk_bf16_f32 v91, v98, v99
	global_store_dwordx4 v[92:93], v[76:79], off offset:256
	v_cvt_pk_bf16_f32 v74, v80, v81
	v_cvt_pk_bf16_f32 v75, v82, v83
	v_lshl_add_u64 v[76:77], v[72:73], 0, v[138:139]
	v_cvt_pk_bf16_f32 v72, v84, v85
	v_cvt_pk_bf16_f32 v73, v86, v87
	v_cvt_pk_bf16_f32 v71, v66, v67
	v_cvt_pk_bf16_f32 v60, v60, v61
	v_cvt_pk_bf16_f32 v61, v62, v63
	v_cvt_pk_bf16_f32 v62, v56, v57
	v_cvt_pk_bf16_f32 v63, v58, v59
	v_cvt_pk_bf16_f32 v40, v52, v53
	v_cvt_pk_bf16_f32 v41, v54, v55
	v_cvt_pk_bf16_f32 v42, v48, v49
	v_cvt_pk_bf16_f32 v43, v50, v51
	v_cvt_pk_bf16_f32 v24, v36, v37
	v_cvt_pk_bf16_f32 v25, v38, v39
	v_cvt_pk_bf16_f32 v26, v32, v33
	v_cvt_pk_bf16_f32 v27, v34, v35
	global_store_dwordx4 v[28:29], v[12:15], off offset:256
	v_cvt_pk_bf16_f32 v10, v16, v17
	v_cvt_pk_bf16_f32 v11, v18, v19
	v_lshl_add_u64 v[12:13], v[8:9], 0, v[138:139]
	v_cvt_pk_bf16_f32 v8, v20, v21
	v_cvt_pk_bf16_f32 v9, v22, v23
	v_cvt_pk_bf16_f32 v4, v4, v5
	v_cvt_pk_bf16_f32 v5, v6, v7
	v_cvt_pk_bf16_f32 v6, v0, v1
	v_cvt_pk_bf16_f32 v7, v2, v3
	s_and_b64 vcc, exec, s[6:7]
	s_mov_b32 s31, s8
	s_mov_b32 s33, s10
	s_mov_b64 s[18:19], s[14:15]
	s_mov_b64 s[16:17], s[12:13]
	global_store_dwordx4 v[142:143], v[124:127], off
	global_store_dwordx4 v[108:109], v[104:107], off
	global_store_dwordx4 v[92:93], v[88:91], off
	global_store_dwordx4 v[76:77], v[72:75], off
	global_store_dwordx4 v[76:77], v[68:71], off offset:256
	global_store_dwordx4 v[64:65], v[60:63], off
	global_store_dwordx4 v[44:45], v[40:43], off
	global_store_dwordx4 v[28:29], v[24:27], off
	global_store_dwordx4 v[12:13], v[8:11], off
	global_store_dwordx4 v[12:13], v[4:7], off offset:256
	s_cbranch_vccz .LBB0_228
	s_waitcnt vmcnt(0)
	s_cmpk_gt_u32 s2, 0xff
	s_cbranch_scc1 .LBB0_235
	s_barrier

; #define PG8_STAGE(bufoff, gbase) do { _Pragma("unroll") for (int _i = 0; _i < 2; ++_i) \
;         __builtin_amdgcn_global_load_lds((const unsigned*)((const char*)(gbase) + voff[_i]), (LAS unsigned*)(lds + (bufoff) + ldsw + _i * 8192), 16, 0, 0); } while (0)
; #define PG8_LDA(dst, b, h) do { _Pragma("unroll") for (int m = 0; m < 4; ++m) _Pragma("unroll") for (int k = 0; k < 2; ++k) dst[m][k] = *(const LAS bf16x8*)(lds + PG8_SA(b, h) + aoff + m * 2048 + k * 1024); } while (0)
; #define PG8_LDB(dst, b, h) do { _Pragma("unroll") for (int n = 0; n < 2; ++n) _Pragma("unroll") for (int k = 0; k < 2; ++k) dst[n][k] = *(const LAS bf16x8*)(lds + PG8_SB(b, h) + boff + n * 2048 + k * 1024); } while (0)
; #define PG8_MMA(ai, bj, At, Bt) do { __builtin_amdgcn_s_setprio(1); _Pragma("unroll") for (int m = 0; m < 4; ++m) _Pragma("unroll") for (int n = 0; n < 2; ++n) _Pragma("unroll") for (int k = 0; k < 2; ++k) \
;         acc[ai][bj][m][n] = __builtin_amdgcn_mfma_f32_16x16x32_bf16(Bt[n][k], At[m][k], acc[ai][bj][m][n], 0, 0, 0); __builtin_amdgcn_s_setprio(0); } while (0)
; #define PG8_WAIT_L(n) asm volatile("s_waitcnt lgkmcnt(" #n ")" ::: "memory")
; #define PG8_BAR __builtin_amdgcn_s_barrier()
; #define PG8_SCHED __builtin_amdgcn_sched_barrier(0)
; template <class Epi>
; DI void gemm_phase(LAS unsigned char* lds, const Gemm g, const StaticOrder& S, const Epi& E) {
;     ...
;         const char* nA = has_next ? (const char*)g.A + (size_t)nxt.pm * tstep : cA; const char* nB = has_next ? (const char*)g.Bt + (size_t)nxt.pn * tstep : cB;
;         for (int t = 0; t < nt; t += 2) {
;             const bool last = (t == nt - 2);
;             const char* a1 = cA + (size_t)(t + 1) * kstep;
;             const char* a2 = last ? nA : cA + (size_t)(t + 2) * kstep; const char* b2 = last ? nB : cB + (size_t)(t + 2) * kstep;
;             const char* a3 = a2 + kstep; const char* b3 = b2 + kstep;
;             PG8_LDB(B0, 0, 0); PG8_SCHED; PG8_LDA(At, 0, 0); PG8_STAGE(PG8_SA(1, 1), a1 + hstep);
;             PG8_WAIT_L(8); PG8_BAR; PG8_WAIT_L(0); PG8_MMA(0, 0, At, B0); PG8_BAR; PG8_SCHED;
;             PG8_LDB(B1, 0, 1); PG8_STAGE(PG8_SB(0, 0), b2);
;             PG8_BAR; PG8_WAIT_L(0); PG8_MMA(0, 1, At, B1); PG8_BAR;
;             PG8_LDA(At, 0, 1); PG8_STAGE(PG8_SA(0, 0), a2);
;             PG8_BAR; PG8_WAIT_L(0); PG8_MMA(1, 0, At, B0); PG8_BAR; PG8_SCHED;
.LBB0_320:
	s_add_u32 s26, s24, 0x100
	s_addc_u32 s27, s25, 0
	s_add_i32 s47, 0, 0x10000
	v_add_u32_e32 v140, s47, v226
	ds_read_b128 v[128:131], v140
	ds_read_b128 v[132:135], v140 offset:1024
	ds_read_b128 v[136:139], v140 offset:2048
	ds_read_b128 v[140:143], v140 offset:3072
	s_cmp_eq_u32 s46, 28
	s_cselect_b32 s31, s4, s27
	s_cselect_b32 s30, s5, s26
	s_cselect_b32 s29, s9, s45
	s_cselect_b32 s28, s11, s33
	v_lshl_add_u64 v[214:215], s[24:25], 0, v[190:191]
	s_add_i32 m0, s38, 0xc000
	ds_read_b128 v[144:147], v228
	ds_read_b128 v[148:151], v228 offset:1024
	ds_read_b128 v[152:155], v228 offset:2048
	ds_read_b128 v[194:197], v228 offset:3072
	ds_read_b128 v[198:201], v228 offset:4096
	ds_read_b128 v[202:205], v228 offset:5120
	ds_read_b128 v[206:209], v228 offset:6144
	ds_read_b128 v[210:213], v228 offset:7168
	global_load_lds_dwordx4 v[214:215], off
	v_lshl_add_u64 v[214:215], s[24:25], 0, v[192:193]
	s_add_i32 m0, s38, 0xe000
	s_nop 0
	global_load_lds_dwordx4 v[214:215], off
	s_waitcnt lgkmcnt(8)
	s_setprio 1
	s_barrier
	s_waitcnt lgkmcnt(0)
	v_mfma_f32_16x16x32_bf16 v[124:127], v[128:131], v[144:147], v[124:127]
	v_mfma_f32_16x16x32_bf16 v[120:123], v[136:139], v[144:147], v[120:123]
	v_mfma_f32_16x16x32_bf16 v[116:119], v[128:131], v[152:155], v[116:119]
	v_mfma_f32_16x16x32_bf16 v[112:115], v[136:139], v[152:155], v[112:115]
	v_mfma_f32_16x16x32_bf16 v[108:111], v[128:131], v[198:201], v[108:111]
	v_mfma_f32_16x16x32_bf16 v[104:107], v[136:139], v[198:201], v[104:107]
	v_mfma_f32_16x16x32_bf16 v[100:103], v[128:131], v[206:209], v[100:103]
	v_mfma_f32_16x16x32_bf16 v[96:99], v[136:139], v[206:209], v[96:99]
	v_mfma_f32_16x16x32_bf16 v[124:127], v[132:135], v[148:151], v[124:127]
	v_mfma_f32_16x16x32_bf16 v[120:123], v[140:143], v[148:151], v[120:123]
	v_mfma_f32_16x16x32_bf16 v[116:119], v[132:135], v[194:197], v[116:119]
	v_mfma_f32_16x16x32_bf16 v[112:115], v[140:143], v[194:197], v[112:115]
	v_mfma_f32_16x16x32_bf16 v[108:111], v[132:135], v[202:205], v[108:111]
	v_mfma_f32_16x16x32_bf16 v[104:107], v[140:143], v[202:205], v[104:107]
	v_mfma_f32_16x16x32_bf16 v[100:103], v[132:135], v[210:213], v[100:103]
	v_mfma_f32_16x16x32_bf16 v[96:99], v[140:143], v[210:213], v[96:99]
	s_setprio 0
	s_barrier
	s_add_i32 s48, 0, 0x14000
	s_add_i32 s24, s47, s37
	v_add_u32_e32 v158, s48, v226
	v_lshl_add_u64 v[218:219], s[28:29], 0, v[188:189]
	s_mov_b32 m0, s24
	ds_read_b128 v[214:217], v158
	ds_read_b128 v[230:233], v158 offset:1024
	ds_read_b128 v[234:237], v158 offset:2048
	ds_read_b128 v[238:241], v158 offset:3072
	global_load_lds_dwordx4 v[218:219], off
	v_lshl_add_u64 v[220:221], s[28:29], 0, v[186:187]
	s_add_i32 m0, s24, 0x2000
	s_nop 0
	global_load_lds_dwordx4 v[220:221], off
	s_setprio 1
	s_barrier
	s_waitcnt lgkmcnt(0)
	v_mfma_f32_16x16x32_bf16 v[60:63], v[214:217], v[144:147], v[60:63]
	v_mfma_f32_16x16x32_bf16 v[56:59], v[234:237], v[144:147], v[56:59]
	v_mfma_f32_16x16x32_bf16 v[52:55], v[214:217], v[152:155], v[52:55]
	v_mfma_f32_16x16x32_bf16 v[48:51], v[234:237], v[152:155], v[48:51]
	v_mfma_f32_16x16x32_bf16 v[44:47], v[214:217], v[198:201], v[44:47]
	v_mfma_f32_16x16x32_bf16 v[40:43], v[234:237], v[198:201], v[40:43]
	v_mfma_f32_16x16x32_bf16 v[36:39], v[214:217], v[206:209], v[36:39]
	v_mfma_f32_16x16x32_bf16 v[32:35], v[234:237], v[206:209], v[32:35]
	v_mfma_f32_16x16x32_bf16 v[60:63], v[230:233], v[148:151], v[60:63]
	v_mfma_f32_16x16x32_bf16 v[56:59], v[238:241], v[148:151], v[56:59]
	v_mfma_f32_16x16x32_bf16 v[52:55], v[230:233], v[194:197], v[52:55]
	v_mfma_f32_16x16x32_bf16 v[48:51], v[238:241], v[194:197], v[48:51]
	v_mfma_f32_16x16x32_bf16 v[44:47], v[230:233], v[202:205], v[44:47]
	v_mfma_f32_16x16x32_bf16 v[40:43], v[238:241], v[202:205], v[40:43]
	v_mfma_f32_16x16x32_bf16 v[36:39], v[230:233], v[210:213], v[36:39]
	v_mfma_f32_16x16x32_bf16 v[32:35], v[238:241], v[210:213], v[32:35]
	s_setprio 0
	s_mov_b32 m0, s38
	v_lshl_add_u64 v[242:243], s[30:31], 0, v[188:189]
	s_barrier
	ds_read_b128 v[144:147], v228 offset:16384
	ds_read_b128 v[148:151], v228 offset:17408
	ds_read_b128 v[152:155], v228 offset:18432
	ds_read_b128 v[194:197], v228 offset:19456
	ds_read_b128 v[198:201], v228 offset:20480
	ds_read_b128 v[202:205], v228 offset:21504
	ds_read_b128 v[206:209], v228 offset:22528
	ds_read_b128 v[210:213], v228 offset:23552
	global_load_lds_dwordx4 v[242:243], off
	v_lshl_add_u64 v[244:245], s[30:31], 0, v[186:187]
	s_mov_b32 m0, s39
	s_nop 0
	global_load_lds_dwordx4 v[244:245], off
	s_setprio 1
	s_barrier
	s_waitcnt lgkmcnt(0)
	v_mfma_f32_16x16x32_bf16 v[92:95], v[128:131], v[144:147], v[92:95]
	v_mfma_f32_16x16x32_bf16 v[88:91], v[136:139], v[144:147], v[88:91]
	v_mfma_f32_16x16x32_bf16 v[84:87], v[128:131], v[152:155], v[84:87]
	v_mfma_f32_16x16x32_bf16 v[80:83], v[136:139], v[152:155], v[80:83]
	v_mfma_f32_16x16x32_bf16 v[76:79], v[128:131], v[198:201], v[76:79]
	v_mfma_f32_16x16x32_bf16 v[72:75], v[136:139], v[198:201], v[72:75]
	v_mfma_f32_16x16x32_bf16 v[68:71], v[128:131], v[206:209], v[68:71]
	v_mfma_f32_16x16x32_bf16 v[64:67], v[136:139], v[206:209], v[64:67]
	v_mfma_f32_16x16x32_bf16 v[92:95], v[132:135], v[148:151], v[92:95]
	v_mfma_f32_16x16x32_bf16 v[88:91], v[140:143], v[148:151], v[88:91]
	v_mfma_f32_16x16x32_bf16 v[84:87], v[132:135], v[194:197], v[84:87]
	v_mfma_f32_16x16x32_bf16 v[80:83], v[140:143], v[194:197], v[80:83]
	v_mfma_f32_16x16x32_bf16 v[76:79], v[132:135], v[202:205], v[76:79]
	v_mfma_f32_16x16x32_bf16 v[72:75], v[140:143], v[202:205], v[72:75]
	v_mfma_f32_16x16x32_bf16 v[68:71], v[132:135], v[210:213], v[68:71]
	v_mfma_f32_16x16x32_bf16 v[64:67], v[140:143], v[210:213], v[64:67]
	s_setprio 0
	s_barrier
; #define PG8_STAGE(bufoff, gbase) do { _Pragma("unroll") for (int _i = 0; _i < 2; ++_i) \
;         __builtin_amdgcn_global_load_lds((const unsigned*)((const char*)(gbase) + voff[_i]), (LAS unsigned*)(lds + (bufoff) + ldsw + _i * 8192), 16, 0, 0); } while (0)
; #define PG8_LDA(dst, b, h) do { _Pragma("unroll") for (int m = 0; m < 4; ++m) _Pragma("unroll") for (int k = 0; k < 2; ++k) dst[m][k] = *(const LAS bf16x8*)(lds + PG8_SA(b, h) + aoff + m * 2048 + k * 1024); } while (0)
; #define PG8_LDB(dst, b, h) do { _Pragma("unroll") for (int n = 0; n < 2; ++n) _Pragma("unroll") for (int k = 0; k < 2; ++k) dst[n][k] = *(const LAS bf16x8*)(lds + PG8_SB(b, h) + boff + n * 2048 + k * 1024); } while (0)
; #define PG8_MMA(ai, bj, At, Bt) do { __builtin_amdgcn_s_setprio(1); _Pragma("unroll") for (int m = 0; m < 4; ++m) _Pragma("unroll") for (int n = 0; n < 2; ++n) _Pragma("unroll") for (int k = 0; k < 2; ++k) \
;         acc[ai][bj][m][n] = __builtin_amdgcn_mfma_f32_16x16x32_bf16(Bt[n][k], At[m][k], acc[ai][bj][m][n], 0, 0, 0); __builtin_amdgcn_s_setprio(0); } while (0)
; #define PG8_WAIT_V(n) asm volatile("s_waitcnt vmcnt(" #n ")" ::: "memory")
; #define PG8_WAIT_L(n) asm volatile("s_waitcnt lgkmcnt(" #n ")" ::: "memory")
; #define PG8_BAR __builtin_amdgcn_s_barrier()
; #define PG8_SCHED __builtin_amdgcn_sched_barrier(0)
; template <class Epi>
; DI void gemm_phase(LAS unsigned char* lds, const Gemm g, const StaticOrder& S, const Epi& E) {
;     ...
;             PG8_STAGE(PG8_SB(0, 1), b2 + hstep);
;             PG8_WAIT_V(6); PG8_BAR; PG8_MMA(1, 1, At, B1); PG8_BAR;
;             PG8_LDB(B0, 1, 0); PG8_SCHED; PG8_LDA(At, 1, 0); PG8_STAGE(PG8_SA(0, 1), a2 + hstep);
;             PG8_WAIT_L(8); PG8_BAR; PG8_WAIT_L(0); PG8_MMA(0, 0, At, B0); PG8_BAR; PG8_SCHED;
;             PG8_LDB(B1, 1, 1); PG8_STAGE(PG8_SB(1, 0), b3);
;             PG8_BAR; PG8_WAIT_L(0); PG8_MMA(0, 1, At, B1); PG8_BAR;
;             PG8_LDA(At, 1, 1); PG8_STAGE(PG8_SA(1, 0), a3);
;             PG8_BAR; PG8_WAIT_L(0); PG8_MMA(1, 0, At, B0); PG8_BAR; PG8_SCHED;
	s_add_u32 s24, s28, 0x80000
	s_addc_u32 s25, s29, 0
	s_add_i32 s47, s48, s37
	v_lshl_add_u64 v[128:129], s[24:25], 0, v[188:189]
	s_mov_b32 m0, s47
	s_nop 0
	global_load_lds_dwordx4 v[128:129], off
	v_lshl_add_u64 v[128:129], s[24:25], 0, v[186:187]
	s_add_i32 m0, s47, 0x2000
	s_nop 0
	global_load_lds_dwordx4 v[128:129], off
	s_waitcnt vmcnt(6)
	s_setprio 1
	s_barrier
	v_mfma_f32_16x16x32_bf16 v[28:31], v[214:217], v[144:147], v[28:31]
	v_mfma_f32_16x16x32_bf16 v[24:27], v[234:237], v[144:147], v[24:27]
	v_mfma_f32_16x16x32_bf16 v[20:23], v[214:217], v[152:155], v[20:23]
	v_mfma_f32_16x16x32_bf16 v[16:19], v[234:237], v[152:155], v[16:19]
	v_mfma_f32_16x16x32_bf16 v[12:15], v[214:217], v[198:201], v[12:15]
	v_mfma_f32_16x16x32_bf16 v[8:11], v[234:237], v[198:201], v[8:11]
	v_mfma_f32_16x16x32_bf16 v[4:7], v[214:217], v[206:209], v[4:7]
	v_mfma_f32_16x16x32_bf16 v[0:3], v[234:237], v[206:209], v[0:3]
	v_mfma_f32_16x16x32_bf16 v[28:31], v[230:233], v[148:151], v[28:31]
	v_mfma_f32_16x16x32_bf16 v[24:27], v[238:241], v[148:151], v[24:27]
	v_mfma_f32_16x16x32_bf16 v[20:23], v[230:233], v[194:197], v[20:23]
	v_mfma_f32_16x16x32_bf16 v[16:19], v[238:241], v[194:197], v[16:19]
	v_mfma_f32_16x16x32_bf16 v[12:15], v[230:233], v[202:205], v[12:15]
	v_mfma_f32_16x16x32_bf16 v[8:11], v[238:241], v[202:205], v[8:11]
	v_mfma_f32_16x16x32_bf16 v[4:7], v[230:233], v[210:213], v[4:7]
	v_mfma_f32_16x16x32_bf16 v[0:3], v[238:241], v[210:213], v[0:3]
	s_setprio 0
	s_add_i32 s47, 0, 0x18000
	v_add_u32_e32 v140, s47, v226
	s_barrier
	ds_read_b128 v[128:131], v140
	ds_read_b128 v[132:135], v140 offset:1024
	ds_read_b128 v[136:139], v140 offset:2048
	ds_read_b128 v[140:143], v140 offset:3072
	s_add_u32 s24, s30, 0x80000
	s_addc_u32 s25, s31, 0
	s_mov_b32 m0, s40
	v_lshl_add_u64 v[214:215], s[24:25], 0, v[188:189]
	ds_read_b128 v[144:147], v228 offset:32768
	ds_read_b128 v[148:151], v228 offset:33792
	ds_read_b128 v[152:155], v228 offset:34816
	ds_read_b128 v[194:197], v228 offset:35840
	ds_read_b128 v[198:201], v228 offset:36864
	ds_read_b128 v[202:205], v228 offset:37888
	ds_read_b128 v[206:209], v228 offset:38912
	ds_read_b128 v[210:213], v228 offset:39936
	global_load_lds_dwordx4 v[214:215], off
	v_lshl_add_u64 v[214:215], s[24:25], 0, v[186:187]
	s_mov_b32 m0, s41
	s_nop 0
	global_load_lds_dwordx4 v[214:215], off
	s_waitcnt lgkmcnt(8)
	s_setprio 1
	s_barrier
	s_waitcnt lgkmcnt(0)
	v_mfma_f32_16x16x32_bf16 v[124:127], v[128:131], v[144:147], v[124:127]
	v_mfma_f32_16x16x32_bf16 v[120:123], v[136:139], v[144:147], v[120:123]
	v_mfma_f32_16x16x32_bf16 v[116:119], v[128:131], v[152:155], v[116:119]
	v_mfma_f32_16x16x32_bf16 v[112:115], v[136:139], v[152:155], v[112:115]
	v_mfma_f32_16x16x32_bf16 v[108:111], v[128:131], v[198:201], v[108:111]
	v_mfma_f32_16x16x32_bf16 v[104:107], v[136:139], v[198:201], v[104:107]
	v_mfma_f32_16x16x32_bf16 v[100:103], v[128:131], v[206:209], v[100:103]
	v_mfma_f32_16x16x32_bf16 v[96:99], v[136:139], v[206:209], v[96:99]
	v_mfma_f32_16x16x32_bf16 v[124:127], v[132:135], v[148:151], v[124:127]
	v_mfma_f32_16x16x32_bf16 v[120:123], v[140:143], v[148:151], v[120:123]
	v_mfma_f32_16x16x32_bf16 v[116:119], v[132:135], v[194:197], v[116:119]
	v_mfma_f32_16x16x32_bf16 v[112:115], v[140:143], v[194:197], v[112:115]
	v_mfma_f32_16x16x32_bf16 v[108:111], v[132:135], v[202:205], v[108:111]
	v_mfma_f32_16x16x32_bf16 v[104:107], v[140:143], v[202:205], v[104:107]
	v_mfma_f32_16x16x32_bf16 v[100:103], v[132:135], v[210:213], v[100:103]
	v_mfma_f32_16x16x32_bf16 v[96:99], v[140:143], v[210:213], v[96:99]
	s_setprio 0
	s_barrier
	s_add_i32 s30, 0, 0x1c000
	s_add_i32 s24, s47, s37
	v_add_u32_e32 v158, s30, v226
	v_lshl_add_u64 v[218:219], v[218:219], 0, s[94:95]
	s_mov_b32 m0, s24
	ds_read_b128 v[214:217], v158
	ds_read_b128 v[230:233], v158 offset:1024
	ds_read_b128 v[234:237], v158 offset:2048
	ds_read_b128 v[238:241], v158 offset:3072
	global_load_lds_dwordx4 v[218:219], off
	v_lshl_add_u64 v[218:219], v[220:221], 0, s[94:95]
	s_add_i32 m0, s24, 0x2000
	s_nop 0
	global_load_lds_dwordx4 v[218:219], off
	s_setprio 1
	s_barrier
	s_waitcnt lgkmcnt(0)
	v_mfma_f32_16x16x32_bf16 v[60:63], v[214:217], v[144:147], v[60:63]
	v_mfma_f32_16x16x32_bf16 v[56:59], v[234:237], v[144:147], v[56:59]
	v_mfma_f32_16x16x32_bf16 v[52:55], v[214:217], v[152:155], v[52:55]
	v_mfma_f32_16x16x32_bf16 v[48:51], v[234:237], v[152:155], v[48:51]
	v_mfma_f32_16x16x32_bf16 v[44:47], v[214:217], v[198:201], v[44:47]
	v_mfma_f32_16x16x32_bf16 v[40:43], v[234:237], v[198:201], v[40:43]
	v_mfma_f32_16x16x32_bf16 v[36:39], v[214:217], v[206:209], v[36:39]
	v_mfma_f32_16x16x32_bf16 v[32:35], v[234:237], v[206:209], v[32:35]
	v_mfma_f32_16x16x32_bf16 v[60:63], v[230:233], v[148:151], v[60:63]
	v_mfma_f32_16x16x32_bf16 v[56:59], v[238:241], v[148:151], v[56:59]
	v_mfma_f32_16x16x32_bf16 v[52:55], v[230:233], v[194:197], v[52:55]
	v_mfma_f32_16x16x32_bf16 v[48:51], v[238:241], v[194:197], v[48:51]
	v_mfma_f32_16x16x32_bf16 v[44:47], v[230:233], v[202:205], v[44:47]
	v_mfma_f32_16x16x32_bf16 v[40:43], v[238:241], v[202:205], v[40:43]
	v_mfma_f32_16x16x32_bf16 v[36:39], v[230:233], v[210:213], v[36:39]
	v_mfma_f32_16x16x32_bf16 v[32:35], v[238:241], v[210:213], v[32:35]
	s_setprio 0
	s_mov_b32 m0, s42
	v_lshl_add_u64 v[218:219], v[242:243], 0, s[94:95]
	s_barrier
	ds_read_b128 v[144:147], v228 offset:49152
	ds_read_b128 v[148:151], v228 offset:50176
	ds_read_b128 v[152:155], v228 offset:51200
	ds_read_b128 v[194:197], v228 offset:52224
	ds_read_b128 v[198:201], v228 offset:53248
	ds_read_b128 v[202:205], v228 offset:54272
	ds_read_b128 v[206:209], v228 offset:55296
	ds_read_b128 v[210:213], v228 offset:56320
	global_load_lds_dwordx4 v[218:219], off
	v_lshl_add_u64 v[218:219], v[244:245], 0, s[94:95]
	s_mov_b32 m0, s43
	s_nop 0
	global_load_lds_dwordx4 v[218:219], off
	s_setprio 1
	s_barrier
; #define PG8_STAGE(bufoff, gbase) do { _Pragma("unroll") for (int _i = 0; _i < 2; ++_i) \
;         __builtin_amdgcn_global_load_lds((const unsigned*)((const char*)(gbase) + voff[_i]), (LAS unsigned*)(lds + (bufoff) + ldsw + _i * 8192), 16, 0, 0); } while (0)
; #define PG8_MMA(ai, bj, At, Bt) do { __builtin_amdgcn_s_setprio(1); _Pragma("unroll") for (int m = 0; m < 4; ++m) _Pragma("unroll") for (int n = 0; n < 2; ++n) _Pragma("unroll") for (int k = 0; k < 2; ++k) \
;         acc[ai][bj][m][n] = __builtin_amdgcn_mfma_f32_16x16x32_bf16(Bt[n][k], At[m][k], acc[ai][bj][m][n], 0, 0, 0); __builtin_amdgcn_s_setprio(0); } while (0)
; #define PG8_WAIT_V(n) asm volatile("s_waitcnt vmcnt(" #n ")" ::: "memory")
; #define PG8_WAIT_L(n) asm volatile("s_waitcnt lgkmcnt(" #n ")" ::: "memory")
; #define PG8_BAR __builtin_amdgcn_s_barrier()
; #define PG8_SCHED __builtin_amdgcn_sched_barrier(0)
; template <class Epi>
; DI void gemm_phase(LAS unsigned char* lds, const Gemm g, const StaticOrder& S, const Epi& E) {
;     ...
;             PG8_BAR; PG8_WAIT_L(0); PG8_MMA(1, 0, At, B0); PG8_BAR; PG8_SCHED;
;             PG8_STAGE(PG8_SB(1, 1), b3 + hstep);
;             PG8_WAIT_V(6); PG8_BAR; PG8_MMA(1, 1, At, B1); PG8_BAR;
;     template <bool LN> DI void run(const f32x4 (&acc)[2][2][4][2], const Unit& u, int wr, int wc, int fr, int fq) const {
;         const unsigned row0 = u.pm * BM + wr * 64 + fr, col0 = u.pn * BM + wc * 32 + 4 * fq;
;         f32x4 gv[2], bv[2];
;         load_gb<LN, 0>(col0, gv, bv);
;         batch<LN, 0, 0, 4>(acc, row0, col0, gv, bv);
	s_waitcnt lgkmcnt(0)
	v_mfma_f32_16x16x32_bf16 v[92:95], v[128:131], v[144:147], v[92:95]
	v_mfma_f32_16x16x32_bf16 v[88:91], v[136:139], v[144:147], v[88:91]
	v_mfma_f32_16x16x32_bf16 v[84:87], v[128:131], v[152:155], v[84:87]
	v_mfma_f32_16x16x32_bf16 v[80:83], v[136:139], v[152:155], v[80:83]
	v_mfma_f32_16x16x32_bf16 v[76:79], v[128:131], v[198:201], v[76:79]
	v_mfma_f32_16x16x32_bf16 v[72:75], v[136:139], v[198:201], v[72:75]
	v_mfma_f32_16x16x32_bf16 v[68:71], v[128:131], v[206:209], v[68:71]
	v_mfma_f32_16x16x32_bf16 v[64:67], v[136:139], v[206:209], v[64:67]
	v_mfma_f32_16x16x32_bf16 v[92:95], v[132:135], v[148:151], v[92:95]
	v_mfma_f32_16x16x32_bf16 v[88:91], v[140:143], v[148:151], v[88:91]
	v_mfma_f32_16x16x32_bf16 v[84:87], v[132:135], v[194:197], v[84:87]
	v_mfma_f32_16x16x32_bf16 v[80:83], v[140:143], v[194:197], v[80:83]
	v_mfma_f32_16x16x32_bf16 v[76:79], v[132:135], v[202:205], v[76:79]
	v_mfma_f32_16x16x32_bf16 v[72:75], v[140:143], v[202:205], v[72:75]
	v_mfma_f32_16x16x32_bf16 v[68:71], v[132:135], v[210:213], v[68:71]
	v_mfma_f32_16x16x32_bf16 v[64:67], v[140:143], v[210:213], v[64:67]
	s_setprio 0
	s_barrier
	s_add_u32 s24, s28, 0x80080
	s_addc_u32 s25, s29, 0
	s_add_i32 s28, s30, s37
	v_lshl_add_u64 v[128:129], s[24:25], 0, v[188:189]
	s_mov_b32 m0, s28
	s_nop 0
	global_load_lds_dwordx4 v[128:129], off
	v_lshl_add_u64 v[128:129], s[24:25], 0, v[186:187]
	s_add_i32 m0, s28, 0x2000
	s_nop 0
	global_load_lds_dwordx4 v[128:129], off
	s_waitcnt vmcnt(6)
	s_setprio 1
	s_barrier
	v_mfma_f32_16x16x32_bf16 v[28:31], v[214:217], v[144:147], v[28:31]
	v_mfma_f32_16x16x32_bf16 v[24:27], v[234:237], v[144:147], v[24:27]
	v_mfma_f32_16x16x32_bf16 v[20:23], v[214:217], v[152:155], v[20:23]
	v_mfma_f32_16x16x32_bf16 v[16:19], v[234:237], v[152:155], v[16:19]
	v_mfma_f32_16x16x32_bf16 v[12:15], v[214:217], v[198:201], v[12:15]
	v_mfma_f32_16x16x32_bf16 v[8:11], v[234:237], v[198:201], v[8:11]
	v_mfma_f32_16x16x32_bf16 v[4:7], v[214:217], v[206:209], v[4:7]
	v_mfma_f32_16x16x32_bf16 v[0:3], v[234:237], v[206:209], v[0:3]
	v_mfma_f32_16x16x32_bf16 v[28:31], v[230:233], v[148:151], v[28:31]
	v_mfma_f32_16x16x32_bf16 v[24:27], v[238:241], v[148:151], v[24:27]
	v_mfma_f32_16x16x32_bf16 v[20:23], v[230:233], v[194:197], v[20:23]
	v_mfma_f32_16x16x32_bf16 v[16:19], v[238:241], v[194:197], v[16:19]
	v_mfma_f32_16x16x32_bf16 v[12:15], v[230:233], v[202:205], v[12:15]
	v_mfma_f32_16x16x32_bf16 v[8:11], v[238:241], v[202:205], v[8:11]
	v_mfma_f32_16x16x32_bf16 v[4:7], v[230:233], v[210:213], v[4:7]
	v_mfma_f32_16x16x32_bf16 v[0:3], v[238:241], v[210:213], v[0:3]
	s_setprio 0
	s_add_i32 s46, s46, 2
	s_add_u32 s33, s33, 0x100
	s_addc_u32 s45, s45, 0
	s_cmp_gt_u32 s46, 29
	s_mov_b64 s[24:25], s[26:27]
	s_barrier
	s_cbranch_scc0 .LBB0_320
	v_lshl_add_u32 v206, s3, 8, v225
	v_lshl_or_b32 v158, s2, 8, v227
	v_lshlrev_b32_e32 v232, 11, v206
	s_andn2_b64 vcc, exec, s[14:15]
	v_or_b32_e32 v231, 16, v158
	v_add_u32_e32 v194, v232, v158
	v_or_b32_e32 v230, 0x80, v158
	v_or_b32_e32 v229, 0x90, v158
	s_cbranch_vccnz .LBB0_323
	v_lshlrev_b64 v[132:133], 2, v[158:159]
	v_lshl_add_u64 v[140:141], s[16:17], 0, v[132:133]
	global_load_dwordx4 v[128:131], v[140:141], off
	v_lshl_add_u64 v[142:143], s[18:19], 0, v[132:133]
	v_readlane_b32 s2, v253, 8
	v_mov_b32_e32 v195, v159
	v_lshlrev_b32_e32 v136, 1, v206
	v_mov_b32_e32 v137, v159
	v_readlane_b32 s3, v253, 9
	v_lshlrev_b64 v[212:213], 2, v[194:195]
	v_add_u32_e32 v146, v232, v231
	v_lshl_add_u64 v[144:145], v[136:137], 2, s[2:3]
	v_lshl_add_u64 v[136:137], s[88:89], 0, v[212:213]
	v_mov_b32_e32 v147, v159
	v_lshl_add_u64 v[146:147], v[146:147], 2, s[88:89]
	v_or_b32_e32 v195, 16, v206
	v_mov_b32_e32 v201, v159
	v_mov_b32_e32 v209, v159
	v_lshl_add_u64 v[212:213], s[90:91], 0, v[212:213]
	s_waitcnt vmcnt(0)
	v_pk_mul_f32 v[152:153], v[130:131], s[78:79] op_sel_hi:[1,0]
	v_pk_mul_f32 v[154:155], v[128:129], s[78:79] op_sel_hi:[1,0]
	global_load_dwordx4 v[132:135], v[142:143], off
	global_load_dwordx4 v[128:131], v[140:141], off offset:64
	global_load_dwordx2 v[204:205], v[144:145], off
	global_load_dwordx4 v[196:199], v[146:147], off
	v_lshlrev_b32_e32 v146, 1, v195
	global_load_dwordx4 v[136:139], v[136:137], off
	v_lshlrev_b32_e32 v195, 11, v195
	v_mov_b32_e32 v147, v159
	v_add_u32_e32 v200, v195, v158
	v_lshl_add_u64 v[146:147], v[146:147], 2, s[2:3]
	v_lshl_add_u64 v[200:201], v[200:201], 2, s[88:89]
	global_load_dwordx2 v[214:215], v[146:147], off
	v_add_u32_e32 v208, v195, v231
	global_load_dwordx4 v[200:203], v[200:201], off
	v_lshl_add_u64 v[208:209], v[208:209], 2, s[88:89]
	global_load_dwordx4 v[208:211], v[208:209], off
	s_waitcnt vmcnt(0)
	v_pk_mul_f32 v[148:149], v[130:131], s[78:79] op_sel_hi:[1,0]
	v_pk_mul_f32 v[150:151], v[128:129], s[78:79] op_sel_hi:[1,0]
	global_load_dwordx4 v[128:131], v[142:143], off offset:64
	v_sub_f32_e32 v137, v137, v204
	v_sub_f32_e32 v136, v136, v204
	v_sub_f32_e32 v139, v139, v204
	v_sub_f32_e32 v138, v138, v204
	v_pk_mul_f32 v[138:139], v[204:205], v[138:139] op_sel:[1,0]
	v_pk_mul_f32 v[136:137], v[204:205], v[136:137] op_sel:[1,0]
	v_pk_fma_f32 v[138:139], v[152:153], v[138:139], v[126:127]
	v_pk_fma_f32 v[136:137], v[154:155], v[136:137], v[124:125]
	v_pk_fma_f32 v[138:139], v[134:135], s[78:79], v[138:139] op_sel_hi:[1,0,1]
	v_pk_fma_f32 v[136:137], v[132:133], s[78:79], v[136:137] op_sel_hi:[1,0,1]
	global_store_dwordx4 v[212:213], v[136:139], off
	s_nop 1
	v_sub_f32_e32 v137, v197, v204
	v_sub_f32_e32 v136, v196, v204
	v_sub_f32_e32 v139, v199, v204
	v_sub_f32_e32 v138, v198, v204
	v_pk_mul_f32 v[138:139], v[204:205], v[138:139] op_sel:[1,0]
	v_pk_mul_f32 v[136:137], v[204:205], v[136:137] op_sel:[1,0]
	v_pk_fma_f32 v[138:139], v[148:149], v[138:139], v[122:123]
	v_pk_fma_f32 v[136:137], v[150:151], v[136:137], v[120:121]
	v_or_b32_e32 v196, 16, v194
	v_mov_b32_e32 v197, v159
	v_lshl_add_u64 v[196:197], v[196:197], 2, s[90:91]
	s_waitcnt vmcnt(0)
;     template <bool LN, int BJ, int LO, int HI> DI void batch(const f32x4 (&acc)[2][2][4][2], unsigned row0, unsigned col0, const f32x4 (&gv)[2], const f32x4 (&bv)[2]) const {
;         f32x4 r[HI - LO]; float mean[(HI - LO) / 2], rstd[(HI - LO) / 2];
; #pragma unroll
;         for (int i = LO; i < HI; ++i) { const int ai = i >> 3, m = (i >> 1) & 3, n = i & 1; const unsigned row = row0 + ai * HALF + m * 16;
;             if (n == 0) { mean[(i - LO) >> 1] = 0.f; rstd[(i - LO) >> 1] = 1.f;
;                 if (LN) { const float2 st = *(const float2*)(stats + row * 2u); mean[(i - LO) >> 1] = st.x; rstd[(i - LO) >> 1] = st.y; } }
;             r[i - LO] = *(const f32x4*)(src + (row * (unsigned)DM + col0 + BJ * HALF + n * 16)); }
; #pragma unroll
;         for (int i = LO; i < HI; ++i) { const int ai = i >> 3, m = (i >> 1) & 3, n = i & 1; const unsigned row = row0 + ai * HALF + m * 16;
;             *(f32x4*)(Y + (row * (unsigned)DM + col0 + BJ * HALF + n * 16)) = acc[ai][BJ][m][n] + ((r[i - LO] - mean[(i - LO) >> 1]) * rstd[(i - LO) >> 1]) * gv[n] + bv[n]; }
;         __builtin_amdgcn_sched_barrier(0);
;     }
;     template <bool LN, int BJ> DI void load_gb(unsigned col0, f32x4 (&gv)[2], f32x4 (&bv)[2]) const {
; #pragma unroll
;         for (int n = 0; n < 2; ++n) {
;             if (LN) { gv[n] = *(const f32x4*)(gam + col0 + BJ * HALF + n * 16) * ALPHA; bv[n] = *(const f32x4*)(bet + col0 + BJ * HALF + n * 16) * ALPHA; }
;             else { gv[n] = (f32x4){ALPHA, ALPHA, ALPHA, ALPHA}; bv[n] = (f32x4){0.f, 0.f, 0.f, 0.f}; }
;         }
;     }
;     template <bool LN> DI void run(const f32x4 (&acc)[2][2][4][2], const Unit& u, int wr, int wc, int fr, int fq) const {
;         const unsigned row0 = u.pm * BM + wr * 64 + fr, col0 = u.pn * BM + wc * 32 + 4 * fq;
;         f32x4 gv[2], bv[2];
;         load_gb<LN, 0>(col0, gv, bv);
;         batch<LN, 0, 0, 4>(acc, row0, col0, gv, bv);
;         batch<LN, 0, 4, 8>(acc, row0, col0, gv, bv);
;         batch<LN, 0, 8, 12>(acc, row0, col0, gv, bv);
;         batch<LN, 0, 12, 16>(acc, row0, col0, gv, bv);
;         load_gb<LN, 1>(col0, gv, bv);
;         batch<LN, 1, 0, 8>(acc, row0, col0, gv, bv);
;         batch<LN, 1, 8, 16>(acc, row0, col0, gv, bv);
	v_pk_fma_f32 v[138:139], v[130:131], s[78:79], v[138:139] op_sel_hi:[1,0,1]
	v_pk_fma_f32 v[136:137], v[128:129], s[78:79], v[136:137] op_sel_hi:[1,0,1]
	global_store_dwordx4 v[196:197], v[136:139], off
	v_add_u32_e32 v196, 0x8000, v194
	v_mov_b32_e32 v197, v159
	v_sub_f32_e32 v137, v201, v214
	v_sub_f32_e32 v136, v200, v214
	v_sub_f32_e32 v139, v203, v214
	v_sub_f32_e32 v138, v202, v214
	v_pk_mul_f32 v[138:139], v[214:215], v[138:139] op_sel:[1,0]
	v_pk_mul_f32 v[136:137], v[214:215], v[136:137] op_sel:[1,0]
	v_pk_fma_f32 v[138:139], v[152:153], v[138:139], v[118:119]
	v_pk_fma_f32 v[136:137], v[154:155], v[136:137], v[116:117]
	v_pk_fma_f32 v[138:139], v[134:135], s[78:79], v[138:139] op_sel_hi:[1,0,1]
	v_pk_fma_f32 v[136:137], v[132:133], s[78:79], v[136:137] op_sel_hi:[1,0,1]
	v_lshl_add_u64 v[196:197], v[196:197], 2, s[90:91]
	global_store_dwordx4 v[196:197], v[136:139], off
	v_add_u32_e32 v196, 0x8010, v194
	v_mov_b32_e32 v197, v159
	v_sub_f32_e32 v137, v209, v214
	v_sub_f32_e32 v136, v208, v214
	v_sub_f32_e32 v139, v211, v214
	v_sub_f32_e32 v138, v210, v214
	v_pk_mul_f32 v[138:139], v[214:215], v[138:139] op_sel:[1,0]
	v_pk_mul_f32 v[136:137], v[214:215], v[136:137] op_sel:[1,0]
	v_pk_fma_f32 v[138:139], v[148:149], v[138:139], v[114:115]
	v_pk_fma_f32 v[136:137], v[150:151], v[136:137], v[112:113]
	v_pk_fma_f32 v[138:139], v[130:131], s[78:79], v[138:139] op_sel_hi:[1,0,1]
	v_pk_fma_f32 v[136:137], v[128:129], s[78:79], v[136:137] op_sel_hi:[1,0,1]
	v_lshl_add_u64 v[196:197], v[196:197], 2, s[90:91]
	global_store_dwordx4 v[196:197], v[136:139], off
	s_nop 1
	v_or_b32_e32 v138, 32, v206
	v_lshlrev_b32_e32 v136, 1, v138
	v_mov_b32_e32 v137, v159
	v_lshlrev_b32_e32 v236, 11, v138
	v_lshl_add_u64 v[200:201], v[136:137], 2, s[2:3]
	v_add_u32_e32 v136, v236, v158
	v_lshl_add_u64 v[136:137], v[136:137], 2, s[88:89]
	global_load_dwordx2 v[204:205], v[200:201], off
	v_add_u32_e32 v196, v236, v231
	global_load_dwordx4 v[136:139], v[136:137], off
	v_mov_b32_e32 v197, v159
	v_lshl_add_u64 v[196:197], v[196:197], 2, s[88:89]
	global_load_dwordx4 v[196:199], v[196:197], off
	v_or_b32_e32 v207, 48, v206
	v_lshlrev_b32_e32 v235, 11, v207
	v_lshlrev_b32_e32 v202, 1, v207
	v_mov_b32_e32 v203, v159
	v_add_u32_e32 v208, v235, v158
	v_mov_b32_e32 v209, v159
	v_lshl_add_u64 v[202:203], v[202:203], 2, s[2:3]
	v_lshl_add_u64 v[208:209], v[208:209], 2, s[88:89]
	global_load_dwordx2 v[216:217], v[202:203], off
	v_add_u32_e32 v212, v235, v231
	global_load_dwordx4 v[208:211], v[208:209], off
	v_mov_b32_e32 v213, v159
	v_lshl_add_u64 v[212:213], v[212:213], 2, s[88:89]
	global_load_dwordx4 v[212:215], v[212:213], off
	v_add_u32_e32 v218, 0x10000, v194
	v_mov_b32_e32 v219, v159
	v_lshl_add_u64 v[218:219], v[218:219], 2, s[90:91]
	s_waitcnt vmcnt(0)
	v_sub_f32_e32 v137, v137, v204
	v_sub_f32_e32 v136, v136, v204
	v_sub_f32_e32 v139, v139, v204
	v_sub_f32_e32 v138, v138, v204
	v_pk_mul_f32 v[138:139], v[204:205], v[138:139] op_sel:[1,0]
	v_pk_mul_f32 v[136:137], v[204:205], v[136:137] op_sel:[1,0]
	v_pk_fma_f32 v[138:139], v[152:153], v[138:139], v[110:111]
	v_pk_fma_f32 v[136:137], v[154:155], v[136:137], v[108:109]
	v_pk_fma_f32 v[138:139], v[134:135], s[78:79], v[138:139] op_sel_hi:[1,0,1]
	v_pk_fma_f32 v[136:137], v[132:133], s[78:79], v[136:137] op_sel_hi:[1,0,1]
	global_store_dwordx4 v[218:219], v[136:139], off
	s_nop 1
	v_sub_f32_e32 v137, v197, v204
	v_sub_f32_e32 v136, v196, v204
	v_sub_f32_e32 v139, v199, v204
	v_sub_f32_e32 v138, v198, v204
	v_pk_mul_f32 v[138:139], v[204:205], v[138:139] op_sel:[1,0]
	v_pk_mul_f32 v[136:137], v[204:205], v[136:137] op_sel:[1,0]
	v_pk_fma_f32 v[138:139], v[148:149], v[138:139], v[106:107]
	v_pk_fma_f32 v[136:137], v[150:151], v[136:137], v[104:105]
	v_add_u32_e32 v196, 0x10010, v194
	v_mov_b32_e32 v197, v159
	v_pk_fma_f32 v[138:139], v[130:131], s[78:79], v[138:139] op_sel_hi:[1,0,1]
	v_pk_fma_f32 v[136:137], v[128:129], s[78:79], v[136:137] op_sel_hi:[1,0,1]
	v_lshl_add_u64 v[196:197], v[196:197], 2, s[90:91]
	global_store_dwordx4 v[196:197], v[136:139], off
	v_add_u32_e32 v196, 0x18000, v194
	v_mov_b32_e32 v197, v159
	v_sub_f32_e32 v137, v209, v216
	v_sub_f32_e32 v136, v208, v216
	v_sub_f32_e32 v139, v211, v216
	v_sub_f32_e32 v138, v210, v216
	v_pk_mul_f32 v[138:139], v[216:217], v[138:139] op_sel:[1,0]
	v_pk_mul_f32 v[136:137], v[216:217], v[136:137] op_sel:[1,0]
	v_pk_fma_f32 v[138:139], v[152:153], v[138:139], v[102:103]
	v_pk_fma_f32 v[136:137], v[154:155], v[136:137], v[100:101]
	v_pk_fma_f32 v[138:139], v[134:135], s[78:79], v[138:139] op_sel_hi:[1,0,1]
	v_pk_fma_f32 v[136:137], v[132:133], s[78:79], v[136:137] op_sel_hi:[1,0,1]
	v_lshl_add_u64 v[196:197], v[196:197], 2, s[90:91]
	global_store_dwordx4 v[196:197], v[136:139], off
	v_add_u32_e32 v196, 0x18010, v194
	v_mov_b32_e32 v197, v159
	v_sub_f32_e32 v137, v213, v216
	v_sub_f32_e32 v136, v212, v216
	v_sub_f32_e32 v139, v215, v216
	v_sub_f32_e32 v138, v214, v216
	v_pk_mul_f32 v[138:139], v[216:217], v[138:139] op_sel:[1,0]
	v_pk_mul_f32 v[136:137], v[216:217], v[136:137] op_sel:[1,0]
	v_pk_fma_f32 v[138:139], v[148:149], v[138:139], v[98:99]
	v_pk_fma_f32 v[136:137], v[150:151], v[136:137], v[96:97]
	v_pk_fma_f32 v[138:139], v[130:131], s[78:79], v[138:139] op_sel_hi:[1,0,1]
	v_pk_fma_f32 v[136:137], v[128:129], s[78:79], v[136:137] op_sel_hi:[1,0,1]
	v_lshl_add_u64 v[196:197], v[196:197], 2, s[90:91]
	global_store_dwordx4 v[196:197], v[136:139], off
	s_nop 1
	v_add_u32_e32 v138, 0x80, v206
	v_lshlrev_b32_e32 v136, 1, v138
	v_mov_b32_e32 v137, v159
	v_lshlrev_b32_e32 v233, 11, v138
	v_lshl_add_u64 v[196:197], v[136:137], 2, s[2:3]
	v_add_u32_e32 v136, v233, v158
	v_lshl_add_u64 v[136:137], v[136:137], 2, s[88:89]
	global_load_dwordx2 v[204:205], v[196:197], off
	v_add_u32_e32 v198, v233, v231
	global_load_dwordx4 v[136:139], v[136:137], off
	v_mov_b32_e32 v199, v159
	v_add_u32_e32 v207, 0x90, v206
	v_lshl_add_u64 v[198:199], v[198:199], 2, s[88:89]
	v_lshlrev_b32_e32 v234, 11, v207
	global_load_dwordx4 v[208:211], v[198:199], off
	v_add_u32_e32 v212, v234, v158
	v_mov_b32_e32 v213, v159
	v_lshl_add_u64 v[212:213], v[212:213], 2, s[88:89]
	global_load_dwordx4 v[212:215], v[212:213], off
	v_lshlrev_b32_e32 v198, 1, v207
	v_mov_b32_e32 v199, v159
	v_lshl_add_u64 v[198:199], v[198:199], 2, s[2:3]
	global_load_dwordx2 v[238:239], v[198:199], off
	v_add_u32_e32 v216, v234, v231
	v_mov_b32_e32 v217, v159
	v_lshl_add_u64 v[216:217], v[216:217], 2, s[88:89]
	global_load_dwordx4 v[216:219], v[216:217], off
	v_add_u32_e32 v240, 0x40000, v194
	v_mov_b32_e32 v241, v159
	v_lshl_add_u64 v[240:241], v[240:241], 2, s[90:91]
	s_waitcnt vmcnt(0)
;     template <bool LN, int BJ, int LO, int HI> DI void batch(const f32x4 (&acc)[2][2][4][2], unsigned row0, unsigned col0, const f32x4 (&gv)[2], const f32x4 (&bv)[2]) const {
;         f32x4 r[HI - LO]; float mean[(HI - LO) / 2], rstd[(HI - LO) / 2];
; #pragma unroll
;         for (int i = LO; i < HI; ++i) { const int ai = i >> 3, m = (i >> 1) & 3, n = i & 1; const unsigned row = row0 + ai * HALF + m * 16;
;             if (n == 0) { mean[(i - LO) >> 1] = 0.f; rstd[(i - LO) >> 1] = 1.f;
;                 if (LN) { const float2 st = *(const float2*)(stats + row * 2u); mean[(i - LO) >> 1] = st.x; rstd[(i - LO) >> 1] = st.y; } }
;             r[i - LO] = *(const f32x4*)(src + (row * (unsigned)DM + col0 + BJ * HALF + n * 16)); }
; #pragma unroll
;         for (int i = LO; i < HI; ++i) { const int ai = i >> 3, m = (i >> 1) & 3, n = i & 1; const unsigned row = row0 + ai * HALF + m * 16;
;             *(f32x4*)(Y + (row * (unsigned)DM + col0 + BJ * HALF + n * 16)) = acc[ai][BJ][m][n] + ((r[i - LO] - mean[(i - LO) >> 1]) * rstd[(i - LO) >> 1]) * gv[n] + bv[n]; }
;         __builtin_amdgcn_sched_barrier(0);
;     }
;     template <bool LN, int BJ> DI void load_gb(unsigned col0, f32x4 (&gv)[2], f32x4 (&bv)[2]) const {
; #pragma unroll
;         for (int n = 0; n < 2; ++n) {
;             if (LN) { gv[n] = *(const f32x4*)(gam + col0 + BJ * HALF + n * 16) * ALPHA; bv[n] = *(const f32x4*)(bet + col0 + BJ * HALF + n * 16) * ALPHA; }
;             else { gv[n] = (f32x4){ALPHA, ALPHA, ALPHA, ALPHA}; bv[n] = (f32x4){0.f, 0.f, 0.f, 0.f}; }
;         }
;     }
;     template <bool LN> DI void run(const f32x4 (&acc)[2][2][4][2], const Unit& u, int wr, int wc, int fr, int fq) const {
;         const unsigned row0 = u.pm * BM + wr * 64 + fr, col0 = u.pn * BM + wc * 32 + 4 * fq;
;         f32x4 gv[2], bv[2];
;         load_gb<LN, 0>(col0, gv, bv);
;         batch<LN, 0, 0, 4>(acc, row0, col0, gv, bv);
;         batch<LN, 0, 4, 8>(acc, row0, col0, gv, bv);
;         batch<LN, 0, 8, 12>(acc, row0, col0, gv, bv);
;         batch<LN, 0, 12, 16>(acc, row0, col0, gv, bv);
;         load_gb<LN, 1>(col0, gv, bv);
;         batch<LN, 1, 0, 8>(acc, row0, col0, gv, bv);
;         batch<LN, 1, 8, 16>(acc, row0, col0, gv, bv);
	v_sub_f32_e32 v137, v137, v204
	v_sub_f32_e32 v136, v136, v204
	v_sub_f32_e32 v139, v139, v204
	v_sub_f32_e32 v138, v138, v204
	v_pk_mul_f32 v[138:139], v[204:205], v[138:139] op_sel:[1,0]
	v_pk_mul_f32 v[136:137], v[204:205], v[136:137] op_sel:[1,0]
	v_pk_fma_f32 v[138:139], v[152:153], v[138:139], v[94:95]
	v_pk_fma_f32 v[136:137], v[154:155], v[136:137], v[92:93]
	v_pk_fma_f32 v[138:139], v[134:135], s[78:79], v[138:139] op_sel_hi:[1,0,1]
	v_pk_fma_f32 v[136:137], v[132:133], s[78:79], v[136:137] op_sel_hi:[1,0,1]
	global_store_dwordx4 v[240:241], v[136:139], off
	s_nop 1
	v_sub_f32_e32 v137, v209, v204
	v_sub_f32_e32 v136, v208, v204
	v_sub_f32_e32 v139, v211, v204
	v_sub_f32_e32 v138, v210, v204
	v_pk_mul_f32 v[138:139], v[204:205], v[138:139] op_sel:[1,0]
	v_pk_mul_f32 v[136:137], v[204:205], v[136:137] op_sel:[1,0]
	v_pk_fma_f32 v[138:139], v[148:149], v[138:139], v[90:91]
	v_pk_fma_f32 v[136:137], v[150:151], v[136:137], v[88:89]
	v_add_u32_e32 v204, 0x40010, v194
	v_mov_b32_e32 v205, v159
	v_pk_fma_f32 v[138:139], v[130:131], s[78:79], v[138:139] op_sel_hi:[1,0,1]
	v_pk_fma_f32 v[136:137], v[128:129], s[78:79], v[136:137] op_sel_hi:[1,0,1]
	v_lshl_add_u64 v[204:205], v[204:205], 2, s[90:91]
	global_store_dwordx4 v[204:205], v[136:139], off
	v_add_u32_e32 v204, 0x48000, v194
	v_mov_b32_e32 v205, v159
	v_sub_f32_e32 v137, v213, v238
	v_sub_f32_e32 v136, v212, v238
	v_sub_f32_e32 v139, v215, v238
	v_sub_f32_e32 v138, v214, v238
	v_pk_mul_f32 v[138:139], v[238:239], v[138:139] op_sel:[1,0]
	v_pk_mul_f32 v[136:137], v[238:239], v[136:137] op_sel:[1,0]
	v_pk_fma_f32 v[138:139], v[152:153], v[138:139], v[86:87]
	v_pk_fma_f32 v[136:137], v[154:155], v[136:137], v[84:85]
	v_pk_fma_f32 v[138:139], v[134:135], s[78:79], v[138:139] op_sel_hi:[1,0,1]
	v_pk_fma_f32 v[136:137], v[132:133], s[78:79], v[136:137] op_sel_hi:[1,0,1]
	v_lshl_add_u64 v[204:205], v[204:205], 2, s[90:91]
	global_store_dwordx4 v[204:205], v[136:139], off
	v_add_u32_e32 v204, 0x48010, v194
	v_mov_b32_e32 v205, v159
	v_sub_f32_e32 v137, v217, v238
	v_sub_f32_e32 v136, v216, v238
	v_sub_f32_e32 v139, v219, v238
	v_sub_f32_e32 v138, v218, v238
	v_pk_mul_f32 v[138:139], v[238:239], v[138:139] op_sel:[1,0]
	v_pk_mul_f32 v[136:137], v[238:239], v[136:137] op_sel:[1,0]
	v_pk_fma_f32 v[138:139], v[148:149], v[138:139], v[82:83]
	v_pk_fma_f32 v[136:137], v[150:151], v[136:137], v[80:81]
	v_pk_fma_f32 v[138:139], v[130:131], s[78:79], v[138:139] op_sel_hi:[1,0,1]
	v_pk_fma_f32 v[136:137], v[128:129], s[78:79], v[136:137] op_sel_hi:[1,0,1]
	v_lshl_add_u64 v[204:205], v[204:205], 2, s[90:91]
	global_store_dwordx4 v[204:205], v[136:139], off
	s_nop 1
	v_add_u32_e32 v138, 0xa0, v206
	v_lshlrev_b32_e32 v136, 1, v138
	v_mov_b32_e32 v137, v159
	v_lshlrev_b32_e32 v237, 11, v138
	v_lshl_add_u64 v[204:205], v[136:137], 2, s[2:3]
	v_add_u32_e32 v136, v237, v158
	v_lshl_add_u64 v[136:137], v[136:137], 2, s[88:89]
	global_load_dwordx2 v[240:241], v[204:205], off
	v_add_u32_e32 v208, v237, v231
	global_load_dwordx4 v[136:139], v[136:137], off
	v_mov_b32_e32 v209, v159
	v_lshl_add_u64 v[208:209], v[208:209], 2, s[88:89]
	global_load_dwordx4 v[212:215], v[208:209], off
	v_add_u32_e32 v208, 0xb0, v206
	v_lshlrev_b32_e32 v206, 1, v208
	v_mov_b32_e32 v207, v159
	v_lshlrev_b32_e32 v238, 11, v208
	v_lshl_add_u64 v[210:211], v[206:207], 2, s[2:3]
	v_add_u32_e32 v206, v238, v158
	v_lshl_add_u64 v[206:207], v[206:207], 2, s[88:89]
	global_load_dwordx2 v[242:243], v[210:211], off
	v_add_u32_e32 v216, v238, v231
	global_load_dwordx4 v[206:209], v[206:207], off
	v_mov_b32_e32 v217, v159
	v_lshl_add_u64 v[216:217], v[216:217], 2, s[88:89]
	global_load_dwordx4 v[216:219], v[216:217], off
	v_add_u32_e32 v244, 0x50000, v194
	v_mov_b32_e32 v245, v159
	v_lshl_add_u64 v[244:245], v[244:245], 2, s[90:91]
	s_waitcnt vmcnt(0)
	v_sub_f32_e32 v137, v137, v240
	v_sub_f32_e32 v136, v136, v240
	v_sub_f32_e32 v139, v139, v240
	v_sub_f32_e32 v138, v138, v240
	v_pk_mul_f32 v[138:139], v[240:241], v[138:139] op_sel:[1,0]
	v_pk_mul_f32 v[136:137], v[240:241], v[136:137] op_sel:[1,0]
	v_pk_fma_f32 v[138:139], v[152:153], v[138:139], v[78:79]
	v_pk_fma_f32 v[136:137], v[154:155], v[136:137], v[76:77]
	v_pk_fma_f32 v[138:139], v[134:135], s[78:79], v[138:139] op_sel_hi:[1,0,1]
	v_pk_fma_f32 v[136:137], v[132:133], s[78:79], v[136:137] op_sel_hi:[1,0,1]
	global_store_dwordx4 v[244:245], v[136:139], off
	s_nop 1
	v_sub_f32_e32 v137, v213, v240
	v_sub_f32_e32 v136, v212, v240
	v_sub_f32_e32 v139, v215, v240
	v_sub_f32_e32 v138, v214, v240
	v_pk_mul_f32 v[138:139], v[240:241], v[138:139] op_sel:[1,0]
	v_pk_mul_f32 v[136:137], v[240:241], v[136:137] op_sel:[1,0]
	v_pk_fma_f32 v[138:139], v[148:149], v[138:139], v[74:75]
	v_pk_fma_f32 v[136:137], v[150:151], v[136:137], v[72:73]
	v_add_u32_e32 v212, 0x50010, v194
	v_mov_b32_e32 v213, v159
	v_pk_fma_f32 v[138:139], v[130:131], s[78:79], v[138:139] op_sel_hi:[1,0,1]
	v_pk_fma_f32 v[136:137], v[128:129], s[78:79], v[136:137] op_sel_hi:[1,0,1]
	v_lshl_add_u64 v[212:213], v[212:213], 2, s[90:91]
	global_store_dwordx4 v[212:213], v[136:139], off
	s_nop 1
	v_sub_f32_e32 v137, v207, v242
	v_sub_f32_e32 v136, v206, v242
	v_sub_f32_e32 v139, v209, v242
	v_sub_f32_e32 v138, v208, v242
	v_pk_mul_f32 v[136:137], v[242:243], v[136:137] op_sel:[1,0]
	v_pk_mul_f32 v[138:139], v[242:243], v[138:139] op_sel:[1,0]
	v_pk_fma_f32 v[136:137], v[154:155], v[136:137], v[68:69]
	v_pk_fma_f32 v[138:139], v[152:153], v[138:139], v[70:71]
	v_pk_fma_f32 v[132:133], v[132:133], s[78:79], v[136:137] op_sel_hi:[1,0,1]
	v_add_u32_e32 v136, 0x58000, v194
	v_mov_b32_e32 v137, v159
	v_pk_fma_f32 v[134:135], v[134:135], s[78:79], v[138:139] op_sel_hi:[1,0,1]
	v_lshl_add_u64 v[136:137], v[136:137], 2, s[90:91]
	global_store_dwordx4 v[136:137], v[132:135], off
	s_nop 1
	v_sub_f32_e32 v133, v217, v242
	v_sub_f32_e32 v132, v216, v242
	v_sub_f32_e32 v135, v219, v242
	v_sub_f32_e32 v134, v218, v242
	v_pk_mul_f32 v[132:133], v[242:243], v[132:133] op_sel:[1,0]
	v_pk_mul_f32 v[134:135], v[242:243], v[134:135] op_sel:[1,0]
	v_pk_fma_f32 v[132:133], v[150:151], v[132:133], v[64:65]
	v_pk_fma_f32 v[134:135], v[148:149], v[134:135], v[66:67]
	v_pk_fma_f32 v[128:129], v[128:129], s[78:79], v[132:133] op_sel_hi:[1,0,1]
	v_add_u32_e32 v132, 0x58010, v194
	v_mov_b32_e32 v133, v159
	v_pk_fma_f32 v[130:131], v[130:131], s[78:79], v[134:135] op_sel_hi:[1,0,1]
	v_lshl_add_u64 v[132:133], v[132:133], 2, s[90:91]
	global_store_dwordx4 v[132:133], v[128:131], off
	global_load_dwordx4 v[128:131], v[140:141], off offset:512
	v_add_u32_e32 v136, v232, v230
	v_mov_b32_e32 v137, v159
	v_lshl_add_u64 v[136:137], v[136:137], 2, s[88:89]
	s_waitcnt vmcnt(0)
;     template <bool LN, int BJ> DI void load_gb(unsigned col0, f32x4 (&gv)[2], f32x4 (&bv)[2]) const {
; #pragma unroll
;         for (int n = 0; n < 2; ++n) {
;             if (LN) { gv[n] = *(const f32x4*)(gam + col0 + BJ * HALF + n * 16) * ALPHA; bv[n] = *(const f32x4*)(bet + col0 + BJ * HALF + n * 16) * ALPHA; }
;             else { gv[n] = (f32x4){ALPHA, ALPHA, ALPHA, ALPHA}; bv[n] = (f32x4){0.f, 0.f, 0.f, 0.f}; }
;         }
;     }
;     template <bool LN> DI void run(const f32x4 (&acc)[2][2][4][2], const Unit& u, int wr, int wc, int fr, int fq) const {
;         const unsigned row0 = u.pm * BM + wr * 64 + fr, col0 = u.pn * BM + wc * 32 + 4 * fq;
;         f32x4 gv[2], bv[2];
;         load_gb<LN, 0>(col0, gv, bv);
;         batch<LN, 0, 0, 4>(acc, row0, col0, gv, bv);
;         batch<LN, 0, 4, 8>(acc, row0, col0, gv, bv);
;         batch<LN, 0, 8, 12>(acc, row0, col0, gv, bv);
;         batch<LN, 0, 12, 16>(acc, row0, col0, gv, bv);
;         load_gb<LN, 1>(col0, gv, bv);
;         batch<LN, 1, 0, 8>(acc, row0, col0, gv, bv);
;         batch<LN, 1, 8, 16>(acc, row0, col0, gv, bv);
	v_pk_mul_f32 v[212:213], v[130:131], s[78:79] op_sel_hi:[1,0]
	v_pk_mul_f32 v[214:215], v[128:129], s[78:79] op_sel_hi:[1,0]
	global_load_dwordx4 v[132:135], v[142:143], off offset:512
	global_load_dwordx4 v[128:131], v[140:141], off offset:576
	s_waitcnt vmcnt(0)
	v_pk_mul_f32 v[206:207], v[130:131], s[78:79] op_sel_hi:[1,0]
	v_pk_mul_f32 v[208:209], v[128:129], s[78:79] op_sel_hi:[1,0]
	global_load_dwordx4 v[128:131], v[142:143], off offset:576
	global_load_dwordx2 v[220:221], v[144:145], off
	global_load_dwordx4 v[240:243], v[136:137], off
	v_add_u32_e32 v136, v232, v229
	v_mov_b32_e32 v137, v159
	v_lshl_add_u64 v[136:137], v[136:137], 2, s[88:89]
	global_load_dwordx4 v[244:247], v[136:137], off
	global_load_dwordx2 v[218:219], v[146:147], off
	v_add_u32_e32 v136, v195, v230
	v_mov_b32_e32 v137, v159
	v_lshl_add_u64 v[136:137], v[136:137], 2, s[88:89]
	global_load_dwordx4 v[248:251], v[136:137], off
	v_add_u32_e32 v136, v195, v229
	v_mov_b32_e32 v137, v159
	v_lshl_add_u64 v[136:137], v[136:137], 2, s[88:89]
	global_load_dwordx4 v[152:155], v[136:137], off
	global_load_dwordx2 v[216:217], v[200:201], off
	v_add_u32_e32 v136, v236, v230
	v_mov_b32_e32 v137, v159
	v_lshl_add_u64 v[136:137], v[136:137], 2, s[88:89]
	global_load_dwordx4 v[148:151], v[136:137], off
	v_add_u32_e32 v136, v236, v229
	v_mov_b32_e32 v137, v159
	v_lshl_add_u64 v[136:137], v[136:137], 2, s[88:89]
	global_load_dwordx4 v[144:147], v[136:137], off
	global_load_dwordx2 v[200:201], v[202:203], off
	v_add_u32_e32 v136, v235, v230
	v_mov_b32_e32 v137, v159
	v_lshl_add_u64 v[136:137], v[136:137], 2, s[88:89]
	global_load_dwordx4 v[140:143], v[136:137], off
	v_add_u32_e32 v136, v235, v229
	v_mov_b32_e32 v137, v159
	v_lshl_add_u64 v[136:137], v[136:137], 2, s[88:89]
	global_load_dwordx4 v[136:139], v[136:137], off
	v_add_u32_e32 v202, 0x80, v194
	v_mov_b32_e32 v203, v159
	v_lshl_add_u64 v[202:203], v[202:203], 2, s[90:91]
	s_waitcnt vmcnt(0)
	v_sub_f32_e32 v241, v241, v220
	v_sub_f32_e32 v240, v240, v220
	v_sub_f32_e32 v243, v243, v220
	v_sub_f32_e32 v242, v242, v220
	v_pk_mul_f32 v[242:243], v[220:221], v[242:243] op_sel:[1,0]
	v_pk_mul_f32 v[240:241], v[220:221], v[240:241] op_sel:[1,0]
	v_pk_fma_f32 v[242:243], v[212:213], v[242:243], v[62:63]
	v_pk_fma_f32 v[240:241], v[214:215], v[240:241], v[60:61]
	v_pk_fma_f32 v[242:243], v[134:135], s[78:79], v[242:243] op_sel_hi:[1,0,1]
	v_pk_fma_f32 v[240:241], v[132:133], s[78:79], v[240:241] op_sel_hi:[1,0,1]
	global_store_dwordx4 v[202:203], v[240:243], off
	v_sub_f32_e32 v203, v245, v220
	v_sub_f32_e32 v202, v244, v220
	v_sub_f32_e32 v241, v247, v220
	v_sub_f32_e32 v240, v246, v220
	v_pk_mul_f32 v[202:203], v[220:221], v[202:203] op_sel:[1,0]
	v_pk_mul_f32 v[240:241], v[220:221], v[240:241] op_sel:[1,0]
	v_pk_fma_f32 v[202:203], v[208:209], v[202:203], v[56:57]
	v_pk_fma_f32 v[220:221], v[206:207], v[240:241], v[58:59]
	v_pk_fma_f32 v[240:241], v[128:129], s[78:79], v[202:203] op_sel_hi:[1,0,1]
	v_add_u32_e32 v202, 0x90, v194
	v_mov_b32_e32 v203, v159
	v_pk_fma_f32 v[242:243], v[130:131], s[78:79], v[220:221] op_sel_hi:[1,0,1]
	v_lshl_add_u64 v[202:203], v[202:203], 2, s[90:91]
	global_store_dwordx4 v[202:203], v[240:243], off
	v_sub_f32_e32 v203, v249, v218
	v_sub_f32_e32 v202, v248, v218
	v_sub_f32_e32 v221, v251, v218
	v_sub_f32_e32 v220, v250, v218
	v_pk_mul_f32 v[202:203], v[218:219], v[202:203] op_sel:[1,0]
	v_pk_mul_f32 v[220:221], v[218:219], v[220:221] op_sel:[1,0]
	v_pk_fma_f32 v[202:203], v[214:215], v[202:203], v[52:53]
	v_pk_fma_f32 v[220:221], v[212:213], v[220:221], v[54:55]
	v_pk_fma_f32 v[240:241], v[132:133], s[78:79], v[202:203] op_sel_hi:[1,0,1]
	v_add_u32_e32 v202, 0x8080, v194
	v_mov_b32_e32 v203, v159
	v_sub_f32_e32 v153, v153, v218
	v_sub_f32_e32 v152, v152, v218
	v_sub_f32_e32 v155, v155, v218
	v_sub_f32_e32 v154, v154, v218
	v_pk_fma_f32 v[242:243], v[134:135], s[78:79], v[220:221] op_sel_hi:[1,0,1]
	v_lshl_add_u64 v[202:203], v[202:203], 2, s[90:91]
	v_pk_mul_f32 v[154:155], v[218:219], v[154:155] op_sel:[1,0]
	v_pk_mul_f32 v[152:153], v[218:219], v[152:153] op_sel:[1,0]
	global_store_dwordx4 v[202:203], v[240:243], off
	v_pk_fma_f32 v[152:153], v[208:209], v[152:153], v[48:49]
	v_pk_fma_f32 v[154:155], v[206:207], v[154:155], v[50:51]
	v_add_u32_e32 v202, 0x8090, v194
	v_mov_b32_e32 v203, v159
	v_sub_f32_e32 v149, v149, v216
	v_sub_f32_e32 v148, v148, v216
	v_sub_f32_e32 v151, v151, v216
	v_sub_f32_e32 v150, v150, v216
	v_pk_fma_f32 v[154:155], v[130:131], s[78:79], v[154:155] op_sel_hi:[1,0,1]
	v_pk_fma_f32 v[152:153], v[128:129], s[78:79], v[152:153] op_sel_hi:[1,0,1]
	v_lshl_add_u64 v[202:203], v[202:203], 2, s[90:91]
	v_pk_mul_f32 v[150:151], v[216:217], v[150:151] op_sel:[1,0]
	v_pk_mul_f32 v[148:149], v[216:217], v[148:149] op_sel:[1,0]
	global_store_dwordx4 v[202:203], v[152:155], off
	v_pk_fma_f32 v[148:149], v[214:215], v[148:149], v[44:45]
	v_pk_fma_f32 v[150:151], v[212:213], v[150:151], v[46:47]
	v_add_u32_e32 v152, 0x10080, v194
	v_mov_b32_e32 v153, v159
	v_sub_f32_e32 v145, v145, v216
	v_sub_f32_e32 v144, v144, v216
	v_sub_f32_e32 v147, v147, v216
	v_sub_f32_e32 v146, v146, v216
	v_pk_fma_f32 v[150:151], v[134:135], s[78:79], v[150:151] op_sel_hi:[1,0,1]
	v_pk_fma_f32 v[148:149], v[132:133], s[78:79], v[148:149] op_sel_hi:[1,0,1]
	v_lshl_add_u64 v[152:153], v[152:153], 2, s[90:91]
	v_pk_mul_f32 v[146:147], v[216:217], v[146:147] op_sel:[1,0]
	v_pk_mul_f32 v[144:145], v[216:217], v[144:145] op_sel:[1,0]
	global_store_dwordx4 v[152:153], v[148:151], off
	v_pk_fma_f32 v[144:145], v[208:209], v[144:145], v[40:41]
	v_pk_fma_f32 v[146:147], v[206:207], v[146:147], v[42:43]
;     template <bool LN, int BJ, int LO, int HI> DI void batch(const f32x4 (&acc)[2][2][4][2], unsigned row0, unsigned col0, const f32x4 (&gv)[2], const f32x4 (&bv)[2]) const {
;         f32x4 r[HI - LO]; float mean[(HI - LO) / 2], rstd[(HI - LO) / 2];
; #pragma unroll
;         for (int i = LO; i < HI; ++i) { const int ai = i >> 3, m = (i >> 1) & 3, n = i & 1; const unsigned row = row0 + ai * HALF + m * 16;
;             if (n == 0) { mean[(i - LO) >> 1] = 0.f; rstd[(i - LO) >> 1] = 1.f;
;                 if (LN) { const float2 st = *(const float2*)(stats + row * 2u); mean[(i - LO) >> 1] = st.x; rstd[(i - LO) >> 1] = st.y; } }
;             r[i - LO] = *(const f32x4*)(src + (row * (unsigned)DM + col0 + BJ * HALF + n * 16)); }
; #pragma unroll
;         for (int i = LO; i < HI; ++i) { const int ai = i >> 3, m = (i >> 1) & 3, n = i & 1; const unsigned row = row0 + ai * HALF + m * 16;
;             *(f32x4*)(Y + (row * (unsigned)DM + col0 + BJ * HALF + n * 16)) = acc[ai][BJ][m][n] + ((r[i - LO] - mean[(i - LO) >> 1]) * rstd[(i - LO) >> 1]) * gv[n] + bv[n]; }
	v_add_u32_e32 v148, 0x10090, v194
	v_mov_b32_e32 v149, v159
	v_sub_f32_e32 v141, v141, v200
	v_sub_f32_e32 v140, v140, v200
	v_sub_f32_e32 v143, v143, v200
	v_sub_f32_e32 v142, v142, v200
	v_pk_fma_f32 v[146:147], v[130:131], s[78:79], v[146:147] op_sel_hi:[1,0,1]
	v_pk_fma_f32 v[144:145], v[128:129], s[78:79], v[144:145] op_sel_hi:[1,0,1]
	v_lshl_add_u64 v[148:149], v[148:149], 2, s[90:91]
	v_pk_mul_f32 v[142:143], v[200:201], v[142:143] op_sel:[1,0]
	v_pk_mul_f32 v[140:141], v[200:201], v[140:141] op_sel:[1,0]
	global_store_dwordx4 v[148:149], v[144:147], off
	v_pk_fma_f32 v[140:141], v[214:215], v[140:141], v[36:37]
	v_pk_fma_f32 v[142:143], v[212:213], v[142:143], v[38:39]
	v_add_u32_e32 v144, 0x18080, v194
	v_mov_b32_e32 v145, v159
	v_sub_f32_e32 v137, v137, v200
	v_sub_f32_e32 v136, v136, v200
	v_sub_f32_e32 v139, v139, v200
	v_sub_f32_e32 v138, v138, v200
	v_pk_fma_f32 v[142:143], v[134:135], s[78:79], v[142:143] op_sel_hi:[1,0,1]
	v_pk_fma_f32 v[140:141], v[132:133], s[78:79], v[140:141] op_sel_hi:[1,0,1]
	v_lshl_add_u64 v[144:145], v[144:145], 2, s[90:91]
	v_pk_mul_f32 v[138:139], v[200:201], v[138:139] op_sel:[1,0]
	v_pk_mul_f32 v[136:137], v[200:201], v[136:137] op_sel:[1,0]
	global_store_dwordx4 v[144:145], v[140:143], off
	v_pk_fma_f32 v[136:137], v[208:209], v[136:137], v[32:33]
	v_pk_fma_f32 v[138:139], v[206:207], v[138:139], v[34:35]
	v_add_u32_e32 v140, 0x18090, v194
	v_mov_b32_e32 v141, v159
	v_pk_fma_f32 v[138:139], v[130:131], s[78:79], v[138:139] op_sel_hi:[1,0,1]
	v_pk_fma_f32 v[136:137], v[128:129], s[78:79], v[136:137] op_sel_hi:[1,0,1]
	v_lshl_add_u64 v[140:141], v[140:141], 2, s[90:91]
	global_store_dwordx4 v[140:141], v[136:139], off
	s_nop 1
	v_add_u32_e32 v136, v233, v230
	v_mov_b32_e32 v137, v159
	v_lshl_add_u64 v[136:137], v[136:137], 2, s[88:89]
	global_load_dwordx2 v[220:221], v[196:197], off
	global_load_dwordx4 v[216:219], v[136:137], off
	v_add_u32_e32 v136, v233, v229
	v_mov_b32_e32 v137, v159
	v_lshl_add_u64 v[136:137], v[136:137], 2, s[88:89]
	global_load_dwordx4 v[240:243], v[136:137], off
	global_load_dwordx2 v[200:201], v[198:199], off
	v_add_u32_e32 v136, v234, v230
	v_mov_b32_e32 v137, v159
	v_lshl_add_u64 v[136:137], v[136:137], 2, s[88:89]
	global_load_dwordx4 v[244:247], v[136:137], off
	v_add_u32_e32 v136, v234, v229
	v_mov_b32_e32 v137, v159
	v_lshl_add_u64 v[136:137], v[136:137], 2, s[88:89]
	global_load_dwordx4 v[152:155], v[136:137], off
	global_load_dwordx2 v[198:199], v[204:205], off
	v_add_u32_e32 v136, v237, v230
	v_mov_b32_e32 v137, v159
	v_lshl_add_u64 v[136:137], v[136:137], 2, s[88:89]
	global_load_dwordx4 v[148:151], v[136:137], off
	v_add_u32_e32 v136, v237, v229
	v_mov_b32_e32 v137, v159
	v_lshl_add_u64 v[136:137], v[136:137], 2, s[88:89]
	global_load_dwordx4 v[144:147], v[136:137], off
	global_load_dwordx2 v[196:197], v[210:211], off
	v_add_u32_e32 v136, v238, v230
	v_mov_b32_e32 v137, v159
	v_lshl_add_u64 v[136:137], v[136:137], 2, s[88:89]
	global_load_dwordx4 v[140:143], v[136:137], off
	v_add_u32_e32 v136, v238, v229
	v_mov_b32_e32 v137, v159
	v_lshl_add_u64 v[136:137], v[136:137], 2, s[88:89]
	global_load_dwordx4 v[136:139], v[136:137], off
	v_add_u32_e32 v210, 0x40080, v194
	v_mov_b32_e32 v211, v159
	v_lshl_add_u64 v[210:211], v[210:211], 2, s[90:91]
	s_waitcnt vmcnt(0)
;     template <bool LN, int BJ, int LO, int HI> DI void batch(const f32x4 (&acc)[2][2][4][2], unsigned row0, unsigned col0, const f32x4 (&gv)[2], const f32x4 (&bv)[2]) const {
;         f32x4 r[HI - LO]; float mean[(HI - LO) / 2], rstd[(HI - LO) / 2];
; #pragma unroll
;         for (int i = LO; i < HI; ++i) { const int ai = i >> 3, m = (i >> 1) & 3, n = i & 1; const unsigned row = row0 + ai * HALF + m * 16;
;             if (n == 0) { mean[(i - LO) >> 1] = 0.f; rstd[(i - LO) >> 1] = 1.f;
;                 if (LN) { const float2 st = *(const float2*)(stats + row * 2u); mean[(i - LO) >> 1] = st.x; rstd[(i - LO) >> 1] = st.y; } }
;             r[i - LO] = *(const f32x4*)(src + (row * (unsigned)DM + col0 + BJ * HALF + n * 16)); }
; #pragma unroll
;         for (int i = LO; i < HI; ++i) { const int ai = i >> 3, m = (i >> 1) & 3, n = i & 1; const unsigned row = row0 + ai * HALF + m * 16;
;             *(f32x4*)(Y + (row * (unsigned)DM + col0 + BJ * HALF + n * 16)) = acc[ai][BJ][m][n] + ((r[i - LO] - mean[(i - LO) >> 1]) * rstd[(i - LO) >> 1]) * gv[n] + bv[n]; }
	v_sub_f32_e32 v203, v217, v220
	v_sub_f32_e32 v202, v216, v220
	v_sub_f32_e32 v205, v219, v220
	v_sub_f32_e32 v204, v218, v220
	v_pk_mul_f32 v[204:205], v[220:221], v[204:205] op_sel:[1,0]
	v_pk_mul_f32 v[202:203], v[220:221], v[202:203] op_sel:[1,0]
	v_pk_fma_f32 v[204:205], v[212:213], v[204:205], v[30:31]
	v_pk_fma_f32 v[202:203], v[214:215], v[202:203], v[28:29]
	v_pk_fma_f32 v[204:205], v[134:135], s[78:79], v[204:205] op_sel_hi:[1,0,1]
	v_pk_fma_f32 v[202:203], v[132:133], s[78:79], v[202:203] op_sel_hi:[1,0,1]
	global_store_dwordx4 v[210:211], v[202:205], off
	v_add_u32_e32 v210, 0x40090, v194
	v_mov_b32_e32 v211, v159
	v_sub_f32_e32 v203, v241, v220
	v_sub_f32_e32 v202, v240, v220
	v_sub_f32_e32 v205, v243, v220
	v_sub_f32_e32 v204, v242, v220
	v_pk_mul_f32 v[204:205], v[220:221], v[204:205] op_sel:[1,0]
	v_pk_mul_f32 v[202:203], v[220:221], v[202:203] op_sel:[1,0]
	v_pk_fma_f32 v[204:205], v[206:207], v[204:205], v[26:27]
	v_pk_fma_f32 v[202:203], v[208:209], v[202:203], v[24:25]
	v_pk_fma_f32 v[204:205], v[130:131], s[78:79], v[204:205] op_sel_hi:[1,0,1]
	v_pk_fma_f32 v[202:203], v[128:129], s[78:79], v[202:203] op_sel_hi:[1,0,1]
	v_lshl_add_u64 v[210:211], v[210:211], 2, s[90:91]
	global_store_dwordx4 v[210:211], v[202:205], off
	v_sub_f32_e32 v149, v149, v198
	v_sub_f32_e32 v148, v148, v198
	v_sub_f32_e32 v203, v245, v200
	v_sub_f32_e32 v202, v244, v200
	v_sub_f32_e32 v141, v141, v196
	v_sub_f32_e32 v140, v140, v196
	v_sub_f32_e32 v205, v247, v200
	v_sub_f32_e32 v204, v246, v200
	v_pk_mul_f32 v[202:203], v[200:201], v[202:203] op_sel:[1,0]
	v_sub_f32_e32 v151, v151, v198
	v_sub_f32_e32 v150, v150, v198
	v_pk_mul_f32 v[148:149], v[198:199], v[148:149] op_sel:[1,0]
	v_sub_f32_e32 v143, v143, v196
	v_sub_f32_e32 v142, v142, v196
	v_pk_mul_f32 v[140:141], v[196:197], v[140:141] op_sel:[1,0]
	v_pk_mul_f32 v[204:205], v[200:201], v[204:205] op_sel:[1,0]
	v_pk_fma_f32 v[202:203], v[214:215], v[202:203], v[20:21]
	v_sub_f32_e32 v153, v153, v200
	v_sub_f32_e32 v152, v152, v200
	v_sub_f32_e32 v155, v155, v200
	v_sub_f32_e32 v154, v154, v200
	v_pk_mul_f32 v[150:151], v[198:199], v[150:151] op_sel:[1,0]
	v_pk_fma_f32 v[148:149], v[214:215], v[148:149], v[12:13]
	v_pk_mul_f32 v[142:143], v[196:197], v[142:143] op_sel:[1,0]
	v_pk_fma_f32 v[140:141], v[214:215], v[140:141], v[4:5]
	v_pk_fma_f32 v[204:205], v[212:213], v[204:205], v[22:23]
	v_pk_fma_f32 v[202:203], v[132:133], s[78:79], v[202:203] op_sel_hi:[1,0,1]
	v_pk_mul_f32 v[154:155], v[200:201], v[154:155] op_sel:[1,0]
	v_pk_mul_f32 v[152:153], v[200:201], v[152:153] op_sel:[1,0]
	v_pk_fma_f32 v[150:151], v[212:213], v[150:151], v[14:15]
	v_pk_fma_f32 v[148:149], v[132:133], s[78:79], v[148:149] op_sel_hi:[1,0,1]
	v_pk_fma_f32 v[142:143], v[212:213], v[142:143], v[6:7]
	v_pk_fma_f32 v[132:133], v[132:133], s[78:79], v[140:141] op_sel_hi:[1,0,1]
	v_add_u32_e32 v140, 0x58080, v194
	v_mov_b32_e32 v141, v159
	v_pk_fma_f32 v[204:205], v[134:135], s[78:79], v[204:205] op_sel_hi:[1,0,1]
	v_pk_fma_f32 v[152:153], v[208:209], v[152:153], v[16:17]
	v_pk_fma_f32 v[154:155], v[206:207], v[154:155], v[18:19]
	v_add_u32_e32 v200, 0x48090, v194
	v_mov_b32_e32 v201, v159
	v_pk_fma_f32 v[150:151], v[134:135], s[78:79], v[150:151] op_sel_hi:[1,0,1]
	v_pk_fma_f32 v[134:135], v[134:135], s[78:79], v[142:143] op_sel_hi:[1,0,1]
	v_lshl_add_u64 v[140:141], v[140:141], 2, s[90:91]
	v_pk_fma_f32 v[154:155], v[130:131], s[78:79], v[154:155] op_sel_hi:[1,0,1]
	v_pk_fma_f32 v[152:153], v[128:129], s[78:79], v[152:153] op_sel_hi:[1,0,1]
	v_lshl_add_u64 v[200:201], v[200:201], 2, s[90:91]
	v_sub_f32_e32 v145, v145, v198
	v_sub_f32_e32 v144, v144, v198
	global_store_dwordx4 v[140:141], v[132:135], off
	global_store_dwordx4 v[200:201], v[152:155], off
	v_sub_f32_e32 v147, v147, v198
	v_sub_f32_e32 v133, v137, v196
	v_sub_f32_e32 v132, v136, v196
	v_add_u32_e32 v152, 0x50080, v194
	v_mov_b32_e32 v153, v159
	v_sub_f32_e32 v146, v146, v198
	v_pk_mul_f32 v[144:145], v[198:199], v[144:145] op_sel:[1,0]
	v_sub_f32_e32 v135, v139, v196
	v_sub_f32_e32 v134, v138, v196
	v_pk_mul_f32 v[132:133], v[196:197], v[132:133] op_sel:[1,0]
	v_lshl_add_u64 v[152:153], v[152:153], 2, s[90:91]
	v_pk_mul_f32 v[146:147], v[198:199], v[146:147] op_sel:[1,0]
	v_pk_fma_f32 v[144:145], v[208:209], v[144:145], v[8:9]
	v_pk_mul_f32 v[134:135], v[196:197], v[134:135] op_sel:[1,0]
	v_pk_fma_f32 v[132:133], v[208:209], v[132:133], v[0:1]
	v_add_u32_e32 v210, 0x48080, v194
	v_mov_b32_e32 v211, v159
	global_store_dwordx4 v[152:153], v[148:151], off
	v_pk_fma_f32 v[146:147], v[206:207], v[146:147], v[10:11]
	v_pk_fma_f32 v[144:145], v[128:129], s[78:79], v[144:145] op_sel_hi:[1,0,1]
	v_add_u32_e32 v148, 0x50090, v194
	v_mov_b32_e32 v149, v159
	v_pk_fma_f32 v[134:135], v[206:207], v[134:135], v[2:3]
	v_pk_fma_f32 v[128:129], v[128:129], s[78:79], v[132:133] op_sel_hi:[1,0,1]
	v_add_u32_e32 v132, 0x58090, v194
	v_mov_b32_e32 v133, v159
	v_lshl_add_u64 v[210:211], v[210:211], 2, s[90:91]
	v_pk_fma_f32 v[146:147], v[130:131], s[78:79], v[146:147] op_sel_hi:[1,0,1]
	v_lshl_add_u64 v[148:149], v[148:149], 2, s[90:91]
	v_pk_fma_f32 v[130:131], v[130:131], s[78:79], v[134:135] op_sel_hi:[1,0,1]
	v_lshl_add_u64 v[132:133], v[132:133], 2, s[90:91]
	global_store_dwordx4 v[210:211], v[202:205], off
	global_store_dwordx4 v[148:149], v[144:147], off
	global_store_dwordx4 v[132:133], v[128:131], off
	s_mov_b64 s[24:25], 0
	s_branch .LBB0_324
